# GEMM k-loops: vmcnt(6) waits in phases 4/8 replaced by vmcnt(10) waits in phases 1,2,4,5,6,8 (five stage copies in flight)
# speedup vs baseline: 1.0071x; 1.0071x over previous
; #define LDA(dst, b, h) _Pragma("unroll") for (int m = 0; m < 4; ++m) _Pragma("unroll") for (int k = 0; k < 2; ++k) \
;     dst[m][k] = *reinterpret_cast<const LAS bf16x8*>(lds + SAo(b, h) + lds_byte(wr * 64 + m * 16 + fr, k * 32 + fq * 8))
; #define LDB(dst, b, h) _Pragma("unroll") for (int n = 0; n < 2; ++n) _Pragma("unroll") for (int k = 0; k < 2; ++k) \
;     dst[n][k] = *reinterpret_cast<const LAS bf16x8*>(lds + SBo(b, h) + lds_byte(wc * 32 + n * 16 + fr, k * 32 + fq * 8))
; #define MMA(ai, bj, At_, Bt_) do { __builtin_amdgcn_s_setprio(1); \
;     _Pragma("unroll") for (int m = 0; m < 4; ++m) _Pragma("unroll") for (int n = 0; n < 2; ++n) _Pragma("unroll") for (int k = 0; k < 2; ++k) \
;       acc[ai][bj][m][n] = __builtin_amdgcn_mfma_f32_16x16x32_bf16(Bt_[n][k], At_[m][k], acc[ai][bj][m][n], 0, 0, 0); \
;     __builtin_amdgcn_s_setprio(0); } while (0)
; #define WAIT_L(n) asm volatile("s_waitcnt lgkmcnt(" #n ")" ::: "memory")
; #define BAR __builtin_amdgcn_s_barrier()
; #define SCHED __builtin_amdgcn_sched_barrier(0)
; template <bool PRE = false>
; __device__ __forceinline__ void gemm_kloop(Acc& acc, const bf16_t* __restrict__ A, int lda, const bf16_t* __restrict__ Bt, int ldb,
;                                            int brow, int bcol, int nt, LAS unsigned char* lds) {
;     ...
;     for (int t = 0; t < nt - 2; t += 2) {
;         LDB(B0, 0, 0); SCHED; LDA(At, 0, 0); STAGE(SAo(1, 1), A, lda, brow + HALF, t + 1, offA);
;         WAIT_L(8); BAR; WAIT_L(0); MMA(0, 0, At, B0); BAR; SCHED;
;         LDB(B1, 0, 1); STAGE(SBo(0, 0), Bt, ldb, bcol, t + 2, offB);
;         BAR; WAIT_L(0); MMA(0, 1, At, B1); BAR;
;         LDA(At, 0, 1); STAGE(SAo(0, 0), A, lda, brow, t + 2, offA);
;         BAR; WAIT_L(0); MMA(1, 0, At, B0); BAR; SCHED;
.LBB0_97:
	ds_read_b128 v[146:149], v141
	ds_read_b128 v[150:153], v141 offset:1024
	ds_read_b128 v[154:157], v141 offset:2048
	ds_read_b128 v[158:161], v141 offset:3072
	s_add_i32 s56, s92, -2
	s_mov_b32 s30, s8
	ds_read_b128 v[162:165], v137
	ds_read_b128 v[166:169], v137 offset:1024
	ds_read_b128 v[170:173], v136
	ds_read_b128 v[174:177], v136 offset:1024
	ds_read_b128 v[184:187], v135
	ds_read_b128 v[188:191], v135 offset:1024
	ds_read_b128 v[204:207], v134
	ds_read_b128 v[208:211], v134 offset:1024
	s_ashr_i32 s57, s56, 31
	s_lshl_b64 s[56:57], s[56:57], 7
	s_lshl_b32 s30, s30, 10
	v_lshl_add_u64 v[192:193], v[130:131], 0, s[56:57]
	s_add_i32 s30, s30, 0
	s_lshl_b64 s[56:57], s[50:51], 1
	s_add_i32 m0, s30, 0xc000
	v_lshl_add_u64 v[200:201], v[192:193], 0, s[56:57]
	s_lshl_b64 s[58:59], s[52:53], 1
	global_load_lds_dwordx4 v[200:201], off
	v_lshl_add_u64 v[192:193], v[192:193], 0, s[58:59]
	s_add_i32 m0, s30, 0xe000
	s_nop 0
	global_load_lds_dwordx4 v[192:193], off
	s_waitcnt lgkmcnt(8)
	s_waitcnt vmcnt(10)
	s_barrier
	s_waitcnt lgkmcnt(0)
	s_setprio 1
	s_waitcnt lgkmcnt(0)
	v_mfma_f32_16x16x32_bf16 v[126:129], v[146:149], v[162:165], v[126:129]
	v_mfma_f32_16x16x32_bf16 v[122:125], v[154:157], v[162:165], v[122:125]
	v_mfma_f32_16x16x32_bf16 v[118:121], v[146:149], v[170:173], v[118:121]
	v_mfma_f32_16x16x32_bf16 v[114:117], v[154:157], v[170:173], v[114:117]
	v_mfma_f32_16x16x32_bf16 v[110:113], v[146:149], v[184:187], v[110:113]
	v_mfma_f32_16x16x32_bf16 v[106:109], v[154:157], v[184:187], v[106:109]
	v_mfma_f32_16x16x32_bf16 v[102:105], v[146:149], v[204:207], v[102:105]
	v_mfma_f32_16x16x32_bf16 v[98:101], v[154:157], v[204:207], v[98:101]
	v_mfma_f32_16x16x32_bf16 v[126:129], v[150:153], v[166:169], v[126:129]
	v_mfma_f32_16x16x32_bf16 v[122:125], v[158:161], v[166:169], v[122:125]
	v_mfma_f32_16x16x32_bf16 v[118:121], v[150:153], v[174:177], v[118:121]
	v_mfma_f32_16x16x32_bf16 v[114:117], v[158:161], v[174:177], v[114:117]
	v_mfma_f32_16x16x32_bf16 v[110:113], v[150:153], v[188:191], v[110:113]
	v_mfma_f32_16x16x32_bf16 v[106:109], v[158:161], v[188:191], v[106:109]
	v_mfma_f32_16x16x32_bf16 v[102:105], v[150:153], v[208:211], v[102:105]
	v_mfma_f32_16x16x32_bf16 v[98:101], v[158:161], v[208:211], v[98:101]
	s_setprio 0
	s_barrier
	s_add_i32 s30, s92, -1
	s_mov_b32 s60, s30
	s_mov_b32 s62, s8
	ds_read_b128 v[212:215], v140
	ds_read_b128 v[216:219], v140 offset:1024
	ds_read_b128 v[220:223], v140 offset:2048
	ds_read_b128 v[224:227], v140 offset:3072
	s_ashr_i32 s61, s60, 31
	s_lshl_b64 s[60:61], s[60:61], 7
	v_lshl_add_u64 v[192:193], v[132:133], 0, s[60:61]
	s_lshl_b32 s60, s62, 10
	s_add_i32 s64, s60, 0
	s_lshl_b64 s[60:61], s[40:41], 1
	s_add_i32 m0, s64, 0x10000
	v_lshl_add_u64 v[200:201], v[192:193], 0, s[60:61]
	s_lshl_b64 s[62:63], s[42:43], 1
	global_load_lds_dwordx4 v[200:201], off
	v_lshl_add_u64 v[192:193], v[192:193], 0, s[62:63]
	s_add_i32 m0, s64, 0x12000
	s_nop 0
	global_load_lds_dwordx4 v[192:193], off
	s_waitcnt vmcnt(10)
	s_barrier
	s_waitcnt lgkmcnt(0)
	s_setprio 1
	s_waitcnt lgkmcnt(0)
	v_mfma_f32_16x16x32_bf16 v[94:97], v[212:215], v[162:165], v[94:97]
	v_mfma_f32_16x16x32_bf16 v[90:93], v[220:223], v[162:165], v[90:93]
	v_mfma_f32_16x16x32_bf16 v[86:89], v[212:215], v[170:173], v[86:89]
	v_mfma_f32_16x16x32_bf16 v[82:85], v[220:223], v[170:173], v[82:85]
	v_mfma_f32_16x16x32_bf16 v[78:81], v[212:215], v[184:187], v[78:81]
	v_mfma_f32_16x16x32_bf16 v[74:77], v[220:223], v[184:187], v[74:77]
	v_mfma_f32_16x16x32_bf16 v[70:73], v[212:215], v[204:207], v[70:73]
	v_mfma_f32_16x16x32_bf16 v[66:69], v[220:223], v[204:207], v[66:69]
	v_mfma_f32_16x16x32_bf16 v[94:97], v[216:219], v[166:169], v[94:97]
	v_mfma_f32_16x16x32_bf16 v[90:93], v[224:227], v[166:169], v[90:93]
	v_mfma_f32_16x16x32_bf16 v[86:89], v[216:219], v[174:177], v[86:89]
	v_mfma_f32_16x16x32_bf16 v[82:85], v[224:227], v[174:177], v[82:85]
	v_mfma_f32_16x16x32_bf16 v[78:81], v[216:219], v[188:191], v[78:81]
	v_mfma_f32_16x16x32_bf16 v[74:77], v[224:227], v[188:191], v[74:77]
	v_mfma_f32_16x16x32_bf16 v[70:73], v[216:219], v[208:211], v[70:73]
	v_mfma_f32_16x16x32_bf16 v[66:69], v[224:227], v[208:211], v[66:69]
	s_setprio 0
	s_mov_b32 s64, s30
	s_mov_b32 s66, s8
	s_barrier
	ds_read_b128 v[162:165], v137 offset:16384
	ds_read_b128 v[166:169], v137 offset:17408
	ds_read_b128 v[170:173], v136 offset:16384
	ds_read_b128 v[174:177], v136 offset:17408
	ds_read_b128 v[184:187], v135 offset:16384
	ds_read_b128 v[188:191], v135 offset:17408
	ds_read_b128 v[204:207], v134 offset:16384
	ds_read_b128 v[208:211], v134 offset:17408
	s_ashr_i32 s65, s64, 31
	s_lshl_b64 s[64:65], s[64:65], 7
	v_lshl_add_u64 v[192:193], v[130:131], 0, s[64:65]
	s_lshl_b32 s64, s66, 10
	s_add_i32 s68, s64, 0
	s_lshl_b64 s[64:65], s[44:45], 1
	v_lshl_add_u64 v[200:201], v[192:193], 0, s[64:65]
	s_mov_b32 m0, s68
	s_lshl_b64 s[66:67], s[46:47], 1
	global_load_lds_dwordx4 v[200:201], off
	v_lshl_add_u64 v[192:193], v[192:193], 0, s[66:67]
	s_add_i32 m0, s68, 0x2000
	s_nop 0
	global_load_lds_dwordx4 v[192:193], off
	s_barrier
; #define LDA(dst, b, h) _Pragma("unroll") for (int m = 0; m < 4; ++m) _Pragma("unroll") for (int k = 0; k < 2; ++k) \
;     dst[m][k] = *reinterpret_cast<const LAS bf16x8*>(lds + SAo(b, h) + lds_byte(wr * 64 + m * 16 + fr, k * 32 + fq * 8))
; #define LDB(dst, b, h) _Pragma("unroll") for (int n = 0; n < 2; ++n) _Pragma("unroll") for (int k = 0; k < 2; ++k) \
;     dst[n][k] = *reinterpret_cast<const LAS bf16x8*>(lds + SBo(b, h) + lds_byte(wc * 32 + n * 16 + fr, k * 32 + fq * 8))
; #define MMA(ai, bj, At_, Bt_) do { __builtin_amdgcn_s_setprio(1); \
;     _Pragma("unroll") for (int m = 0; m < 4; ++m) _Pragma("unroll") for (int n = 0; n < 2; ++n) _Pragma("unroll") for (int k = 0; k < 2; ++k) \
;       acc[ai][bj][m][n] = __builtin_amdgcn_mfma_f32_16x16x32_bf16(Bt_[n][k], At_[m][k], acc[ai][bj][m][n], 0, 0, 0); \
;     __builtin_amdgcn_s_setprio(0); } while (0)
; #define WAIT_V(n) asm volatile("s_waitcnt vmcnt(" #n ")" ::: "memory")
; #define WAIT_L(n) asm volatile("s_waitcnt lgkmcnt(" #n ")" ::: "memory")
; #define BAR __builtin_amdgcn_s_barrier()
; #define SCHED __builtin_amdgcn_sched_barrier(0)
; template <bool PRE = false>
; __device__ __forceinline__ void gemm_kloop(Acc& acc, const bf16_t* __restrict__ A, int lda, const bf16_t* __restrict__ Bt, int ldb,
;                                            int brow, int bcol, int nt, LAS unsigned char* lds) {
;     ...
;         BAR; WAIT_L(0); MMA(1, 0, At, B0); BAR; SCHED;
;         STAGE(SBo(0, 1), Bt, ldb, bcol + HALF, t + 2, offB);
;         WAIT_V(6); BAR; MMA(1, 1, At, B1); BAR;
;         LDB(B0, 1, 0); SCHED; LDA(At, 1, 0); STAGE(SAo(0, 1), A, lda, brow + HALF, t + 2, offA);
;         WAIT_L(8); BAR; WAIT_L(0); MMA(0, 0, At, B0); BAR; SCHED;
;         LDB(B1, 1, 1); STAGE(SBo(1, 0), Bt, ldb, bcol, t + 3, offB);
;         BAR; WAIT_L(0); MMA(0, 1, At, B1); BAR;
	s_waitcnt lgkmcnt(0)
	s_setprio 1
	s_waitcnt lgkmcnt(0)
	v_mfma_f32_16x16x32_bf16 v[62:65], v[146:149], v[162:165], v[62:65]
	v_mfma_f32_16x16x32_bf16 v[58:61], v[154:157], v[162:165], v[58:61]
	v_mfma_f32_16x16x32_bf16 v[54:57], v[146:149], v[170:173], v[54:57]
	v_mfma_f32_16x16x32_bf16 v[50:53], v[154:157], v[170:173], v[50:53]
	v_mfma_f32_16x16x32_bf16 v[46:49], v[146:149], v[184:187], v[46:49]
	v_mfma_f32_16x16x32_bf16 v[42:45], v[154:157], v[184:187], v[42:45]
	v_mfma_f32_16x16x32_bf16 v[38:41], v[146:149], v[204:207], v[38:41]
	v_mfma_f32_16x16x32_bf16 v[34:37], v[154:157], v[204:207], v[34:37]
	v_mfma_f32_16x16x32_bf16 v[62:65], v[150:153], v[166:169], v[62:65]
	v_mfma_f32_16x16x32_bf16 v[58:61], v[158:161], v[166:169], v[58:61]
	v_mfma_f32_16x16x32_bf16 v[54:57], v[150:153], v[174:177], v[54:57]
	v_mfma_f32_16x16x32_bf16 v[50:53], v[158:161], v[174:177], v[50:53]
	v_mfma_f32_16x16x32_bf16 v[46:49], v[150:153], v[188:191], v[46:49]
	v_mfma_f32_16x16x32_bf16 v[42:45], v[158:161], v[188:191], v[42:45]
	v_mfma_f32_16x16x32_bf16 v[38:41], v[150:153], v[208:211], v[38:41]
	v_mfma_f32_16x16x32_bf16 v[34:37], v[158:161], v[208:211], v[34:37]
	s_setprio 0
	s_barrier
	s_mov_b32 s68, s30
	s_mov_b32 s80, s8
	s_ashr_i32 s69, s68, 31
	s_lshl_b64 s[68:69], s[68:69], 7
	v_lshl_add_u64 v[146:147], v[132:133], 0, s[68:69]
	s_lshl_b32 s68, s80, 10
	s_add_i32 s80, s68, 0
	s_lshl_b64 s[68:69], s[48:49], 1
	s_add_i32 m0, s80, 0x14000
	v_lshl_add_u64 v[148:149], v[146:147], 0, s[68:69]
	s_lshl_b64 vcc, s[54:55], 1
	global_load_lds_dwordx4 v[148:149], off
	v_lshl_add_u64 v[146:147], v[146:147], 0, vcc
	s_add_i32 m0, s80, 0x16000
	s_nop 0
	global_load_lds_dwordx4 v[146:147], off
	s_waitcnt vmcnt(10)
	s_barrier
	s_setprio 1
	v_mfma_f32_16x16x32_bf16 v[30:33], v[212:215], v[162:165], v[30:33]
	v_mfma_f32_16x16x32_bf16 v[26:29], v[220:223], v[162:165], v[26:29]
	v_mfma_f32_16x16x32_bf16 v[22:25], v[212:215], v[170:173], v[22:25]
	v_mfma_f32_16x16x32_bf16 v[18:21], v[220:223], v[170:173], v[18:21]
	v_mfma_f32_16x16x32_bf16 v[14:17], v[212:215], v[184:187], v[14:17]
	v_mfma_f32_16x16x32_bf16 v[10:13], v[220:223], v[184:187], v[10:13]
	v_mfma_f32_16x16x32_bf16 v[6:9], v[212:215], v[204:207], v[6:9]
	v_mfma_f32_16x16x32_bf16 v[2:5], v[220:223], v[204:207], v[2:5]
	v_mfma_f32_16x16x32_bf16 v[30:33], v[216:219], v[166:169], v[30:33]
	v_mfma_f32_16x16x32_bf16 v[26:29], v[224:227], v[166:169], v[26:29]
	v_mfma_f32_16x16x32_bf16 v[22:25], v[216:219], v[174:177], v[22:25]
	v_mfma_f32_16x16x32_bf16 v[18:21], v[224:227], v[174:177], v[18:21]
	v_mfma_f32_16x16x32_bf16 v[14:17], v[216:219], v[188:191], v[14:17]
	v_mfma_f32_16x16x32_bf16 v[10:13], v[224:227], v[188:191], v[10:13]
	v_mfma_f32_16x16x32_bf16 v[6:9], v[216:219], v[208:211], v[6:9]
	v_mfma_f32_16x16x32_bf16 v[2:5], v[224:227], v[208:211], v[2:5]
	s_setprio 0
	s_barrier
	ds_read_b128 v[146:149], v139
	ds_read_b128 v[150:153], v139 offset:1024
	ds_read_b128 v[154:157], v139 offset:2048
	ds_read_b128 v[158:161], v139 offset:3072
	s_mov_b32 s80, s30
	s_mov_b32 s93, s8
	ds_read_b128 v[162:165], v137 offset:32768
	ds_read_b128 v[166:169], v137 offset:33792
	ds_read_b128 v[170:173], v136 offset:32768
	ds_read_b128 v[174:177], v136 offset:33792
	ds_read_b128 v[184:187], v135 offset:32768
	ds_read_b128 v[188:191], v135 offset:33792
	ds_read_b128 v[204:207], v134 offset:32768
	ds_read_b128 v[208:211], v134 offset:33792
	s_ashr_i32 s81, s80, 31
	s_lshl_b64 s[80:81], s[80:81], 7
	v_lshl_add_u64 v[192:193], v[130:131], 0, s[80:81]
	s_lshl_b32 s80, s93, 10
	s_add_i32 s80, s80, 0
	s_add_i32 m0, s80, 0x4000
	v_lshl_add_u64 v[200:201], v[192:193], 0, s[56:57]
	global_load_lds_dwordx4 v[200:201], off
	v_lshl_add_u64 v[192:193], v[192:193], 0, s[58:59]
	s_add_i32 m0, s80, 0x6000
	s_nop 0
	global_load_lds_dwordx4 v[192:193], off
	s_waitcnt lgkmcnt(8)
	s_waitcnt vmcnt(10)
	s_barrier
	s_waitcnt lgkmcnt(0)
	s_setprio 1
	s_waitcnt lgkmcnt(0)
	v_mfma_f32_16x16x32_bf16 v[126:129], v[146:149], v[162:165], v[126:129]
	v_mfma_f32_16x16x32_bf16 v[122:125], v[154:157], v[162:165], v[122:125]
	v_mfma_f32_16x16x32_bf16 v[118:121], v[146:149], v[170:173], v[118:121]
	v_mfma_f32_16x16x32_bf16 v[114:117], v[154:157], v[170:173], v[114:117]
	v_mfma_f32_16x16x32_bf16 v[110:113], v[146:149], v[184:187], v[110:113]
	v_mfma_f32_16x16x32_bf16 v[106:109], v[154:157], v[184:187], v[106:109]
	v_mfma_f32_16x16x32_bf16 v[102:105], v[146:149], v[204:207], v[102:105]
	v_mfma_f32_16x16x32_bf16 v[98:101], v[154:157], v[204:207], v[98:101]
	v_mfma_f32_16x16x32_bf16 v[126:129], v[150:153], v[166:169], v[126:129]
	v_mfma_f32_16x16x32_bf16 v[122:125], v[158:161], v[166:169], v[122:125]
	v_mfma_f32_16x16x32_bf16 v[118:121], v[150:153], v[174:177], v[118:121]
	v_mfma_f32_16x16x32_bf16 v[114:117], v[158:161], v[174:177], v[114:117]
	v_mfma_f32_16x16x32_bf16 v[110:113], v[150:153], v[188:191], v[110:113]
	v_mfma_f32_16x16x32_bf16 v[106:109], v[158:161], v[188:191], v[106:109]
	v_mfma_f32_16x16x32_bf16 v[102:105], v[150:153], v[208:211], v[102:105]
	v_mfma_f32_16x16x32_bf16 v[98:101], v[158:161], v[208:211], v[98:101]
	s_setprio 0
	s_barrier
	s_mov_b32 s56, s92
	s_mov_b32 s58, s8
	ds_read_b128 v[212:215], v138
	ds_read_b128 v[216:219], v138 offset:1024
	ds_read_b128 v[220:223], v138 offset:2048
	ds_read_b128 v[224:227], v138 offset:3072
	s_ashr_i32 s57, s56, 31
	s_lshl_b64 s[56:57], s[56:57], 7
	v_lshl_add_u64 v[192:193], v[132:133], 0, s[56:57]
	s_lshl_b32 s56, s58, 10
	s_add_i32 s56, s56, 0
	s_add_i32 m0, s56, 0x18000
	v_lshl_add_u64 v[200:201], v[192:193], 0, s[60:61]
	global_load_lds_dwordx4 v[200:201], off
	v_lshl_add_u64 v[192:193], v[192:193], 0, s[62:63]
	s_add_i32 m0, s56, 0x1a000
	s_nop 0
	global_load_lds_dwordx4 v[192:193], off
	s_waitcnt vmcnt(10)
	s_barrier
; #define LDA(dst, b, h) _Pragma("unroll") for (int m = 0; m < 4; ++m) _Pragma("unroll") for (int k = 0; k < 2; ++k) \
;     dst[m][k] = *reinterpret_cast<const LAS bf16x8*>(lds + SAo(b, h) + lds_byte(wr * 64 + m * 16 + fr, k * 32 + fq * 8))
; #define LDB(dst, b, h) _Pragma("unroll") for (int n = 0; n < 2; ++n) _Pragma("unroll") for (int k = 0; k < 2; ++k) \
;     dst[n][k] = *reinterpret_cast<const LAS bf16x8*>(lds + SBo(b, h) + lds_byte(wc * 32 + n * 16 + fr, k * 32 + fq * 8))
; #define MMA(ai, bj, At_, Bt_) do { __builtin_amdgcn_s_setprio(1); \
;     _Pragma("unroll") for (int m = 0; m < 4; ++m) _Pragma("unroll") for (int n = 0; n < 2; ++n) _Pragma("unroll") for (int k = 0; k < 2; ++k) \
;       acc[ai][bj][m][n] = __builtin_amdgcn_mfma_f32_16x16x32_bf16(Bt_[n][k], At_[m][k], acc[ai][bj][m][n], 0, 0, 0); \
;     __builtin_amdgcn_s_setprio(0); } while (0)
; #define WAIT_V(n) asm volatile("s_waitcnt vmcnt(" #n ")" ::: "memory")
; #define WAIT_L(n) asm volatile("s_waitcnt lgkmcnt(" #n ")" ::: "memory")
; #define BAR __builtin_amdgcn_s_barrier()
; #define SCHED __builtin_amdgcn_sched_barrier(0)
; template <bool PRE = false>
; __device__ __forceinline__ void gemm_kloop(Acc& acc, const bf16_t* __restrict__ A, int lda, const bf16_t* __restrict__ Bt, int ldb,
;                                            int brow, int bcol, int nt, LAS unsigned char* lds) {
;     ...
;         WAIT_L(8); BAR; WAIT_L(0); MMA(0, 0, At, B0); BAR; SCHED;
;         LDB(B1, 1, 1); STAGE(SBo(1, 0), Bt, ldb, bcol, t + 3, offB);
;         BAR; WAIT_L(0); MMA(0, 1, At, B1); BAR;
;         LDA(At, 1, 1); STAGE(SAo(1, 0), A, lda, brow, t + 3, offA);
;         BAR; WAIT_L(0); MMA(1, 0, At, B0); BAR; SCHED;
;         STAGE(SBo(1, 1), Bt, ldb, bcol + HALF, t + 3, offB);
;         WAIT_V(6); BAR; MMA(1, 1, At, B1); BAR;
;     }
;     { LDB(B0, 0, 0); LDA(At, 0, 0); STAGE(SAo(1, 1), A, lda, brow + HALF, nt - 1, offA);
;       BAR; WAIT_L(0); MMA(0, 0, At, B0); BAR;
	s_waitcnt lgkmcnt(0)
	s_setprio 1
	s_waitcnt lgkmcnt(0)
	v_mfma_f32_16x16x32_bf16 v[94:97], v[212:215], v[162:165], v[94:97]
	v_mfma_f32_16x16x32_bf16 v[90:93], v[220:223], v[162:165], v[90:93]
	v_mfma_f32_16x16x32_bf16 v[86:89], v[212:215], v[170:173], v[86:89]
	v_mfma_f32_16x16x32_bf16 v[82:85], v[220:223], v[170:173], v[82:85]
	v_mfma_f32_16x16x32_bf16 v[78:81], v[212:215], v[184:187], v[78:81]
	v_mfma_f32_16x16x32_bf16 v[74:77], v[220:223], v[184:187], v[74:77]
	v_mfma_f32_16x16x32_bf16 v[70:73], v[212:215], v[204:207], v[70:73]
	v_mfma_f32_16x16x32_bf16 v[66:69], v[220:223], v[204:207], v[66:69]
	v_mfma_f32_16x16x32_bf16 v[94:97], v[216:219], v[166:169], v[94:97]
	v_mfma_f32_16x16x32_bf16 v[90:93], v[224:227], v[166:169], v[90:93]
	v_mfma_f32_16x16x32_bf16 v[86:89], v[216:219], v[174:177], v[86:89]
	v_mfma_f32_16x16x32_bf16 v[82:85], v[224:227], v[174:177], v[82:85]
	v_mfma_f32_16x16x32_bf16 v[78:81], v[216:219], v[188:191], v[78:81]
	v_mfma_f32_16x16x32_bf16 v[74:77], v[224:227], v[188:191], v[74:77]
	v_mfma_f32_16x16x32_bf16 v[70:73], v[216:219], v[208:211], v[70:73]
	v_mfma_f32_16x16x32_bf16 v[66:69], v[224:227], v[208:211], v[66:69]
	s_setprio 0
	s_mov_b32 s56, s92
	s_mov_b32 s58, s8
	s_barrier
	ds_read_b128 v[162:165], v137 offset:49152
	ds_read_b128 v[166:169], v137 offset:50176
	ds_read_b128 v[170:173], v136 offset:49152
	ds_read_b128 v[174:177], v136 offset:50176
	ds_read_b128 v[184:187], v135 offset:49152
	ds_read_b128 v[188:191], v135 offset:50176
	ds_read_b128 v[204:207], v134 offset:49152
	ds_read_b128 v[208:211], v134 offset:50176
	s_ashr_i32 s57, s56, 31
	s_lshl_b64 s[56:57], s[56:57], 7
	v_lshl_add_u64 v[192:193], v[130:131], 0, s[56:57]
	s_lshl_b32 s56, s58, 10
	s_add_i32 s56, s56, 0
	s_add_i32 m0, s56, 0x8000
	v_lshl_add_u64 v[200:201], v[192:193], 0, s[64:65]
	global_load_lds_dwordx4 v[200:201], off
	v_lshl_add_u64 v[192:193], v[192:193], 0, s[66:67]
	s_add_i32 m0, s56, 0xa000
	s_nop 0
	global_load_lds_dwordx4 v[192:193], off
	s_barrier
	s_waitcnt lgkmcnt(0)
	s_setprio 1
	s_waitcnt lgkmcnt(0)
	v_mfma_f32_16x16x32_bf16 v[62:65], v[146:149], v[162:165], v[62:65]
	v_mfma_f32_16x16x32_bf16 v[58:61], v[154:157], v[162:165], v[58:61]
	v_mfma_f32_16x16x32_bf16 v[54:57], v[146:149], v[170:173], v[54:57]
	v_mfma_f32_16x16x32_bf16 v[50:53], v[154:157], v[170:173], v[50:53]
	v_mfma_f32_16x16x32_bf16 v[46:49], v[146:149], v[184:187], v[46:49]
	v_mfma_f32_16x16x32_bf16 v[42:45], v[154:157], v[184:187], v[42:45]
	v_mfma_f32_16x16x32_bf16 v[38:41], v[146:149], v[204:207], v[38:41]
	v_mfma_f32_16x16x32_bf16 v[34:37], v[154:157], v[204:207], v[34:37]
	v_mfma_f32_16x16x32_bf16 v[62:65], v[150:153], v[166:169], v[62:65]
	v_mfma_f32_16x16x32_bf16 v[58:61], v[158:161], v[166:169], v[58:61]
	v_mfma_f32_16x16x32_bf16 v[54:57], v[150:153], v[174:177], v[54:57]
	v_mfma_f32_16x16x32_bf16 v[50:53], v[158:161], v[174:177], v[50:53]
	v_mfma_f32_16x16x32_bf16 v[46:49], v[150:153], v[188:191], v[46:49]
	v_mfma_f32_16x16x32_bf16 v[42:45], v[158:161], v[188:191], v[42:45]
	v_mfma_f32_16x16x32_bf16 v[38:41], v[150:153], v[208:211], v[38:41]
	v_mfma_f32_16x16x32_bf16 v[34:37], v[158:161], v[208:211], v[34:37]
	s_setprio 0
	s_barrier
	s_mov_b32 s56, s92
	s_mov_b32 s58, s8
	s_ashr_i32 s57, s56, 31
	s_lshl_b64 s[56:57], s[56:57], 7
	v_lshl_add_u64 v[146:147], v[132:133], 0, s[56:57]
	s_lshl_b32 s56, s58, 10
	s_add_i32 s56, s56, 0
	s_add_i32 m0, s56, 0x1c000
	v_lshl_add_u64 v[148:149], v[146:147], 0, s[68:69]
	global_load_lds_dwordx4 v[148:149], off
	v_lshl_add_u64 v[146:147], v[146:147], 0, vcc
	s_add_i32 m0, s56, 0x1e000
	s_nop 0
	global_load_lds_dwordx4 v[146:147], off
	s_waitcnt vmcnt(10)
	s_barrier
	s_setprio 1
	v_mfma_f32_16x16x32_bf16 v[30:33], v[212:215], v[162:165], v[30:33]
	v_mfma_f32_16x16x32_bf16 v[26:29], v[220:223], v[162:165], v[26:29]
	v_mfma_f32_16x16x32_bf16 v[22:25], v[212:215], v[170:173], v[22:25]
	v_mfma_f32_16x16x32_bf16 v[18:21], v[220:223], v[170:173], v[18:21]
	v_mfma_f32_16x16x32_bf16 v[14:17], v[212:215], v[184:187], v[14:17]
	v_mfma_f32_16x16x32_bf16 v[10:13], v[220:223], v[184:187], v[10:13]
	v_mfma_f32_16x16x32_bf16 v[6:9], v[212:215], v[204:207], v[6:9]
	v_mfma_f32_16x16x32_bf16 v[2:5], v[220:223], v[204:207], v[2:5]
	v_mfma_f32_16x16x32_bf16 v[30:33], v[216:219], v[166:169], v[30:33]
	v_mfma_f32_16x16x32_bf16 v[26:29], v[224:227], v[166:169], v[26:29]
	v_mfma_f32_16x16x32_bf16 v[22:25], v[216:219], v[174:177], v[22:25]
	v_mfma_f32_16x16x32_bf16 v[18:21], v[224:227], v[174:177], v[18:21]
	v_mfma_f32_16x16x32_bf16 v[14:17], v[216:219], v[188:191], v[14:17]
	v_mfma_f32_16x16x32_bf16 v[10:13], v[224:227], v[188:191], v[10:13]
	v_mfma_f32_16x16x32_bf16 v[6:9], v[216:219], v[208:211], v[6:9]
	v_mfma_f32_16x16x32_bf16 v[2:5], v[224:227], v[208:211], v[2:5]
	s_setprio 0
	s_add_i32 s92, s92, 2
	s_cmp_lt_u32 s30, s11
	s_barrier
	s_cbranch_scc1 .LBB0_97
	v_readlane_b32 s30, v254, 9
	s_mov_b32 s40, s30
	ds_read_b128 v[130:133], v141
	ds_read_b128 v[146:149], v141 offset:1024
	ds_read_b128 v[150:153], v141 offset:2048
	ds_read_b128 v[154:157], v141 offset:3072
	ds_read_b128 v[158:161], v137
	ds_read_b128 v[162:165], v137 offset:1024
	ds_read_b128 v[166:169], v136
	ds_read_b128 v[170:173], v136 offset:1024
	ds_read_b128 v[174:177], v135
	ds_read_b128 v[184:187], v135 offset:1024
	ds_read_b128 v[188:191], v134
	ds_read_b128 v[204:207], v134 offset:1024
	s_ashr_i32 s41, s40, 31
	s_lshl_b64 s[40:41], s[40:41], 7
	s_add_u32 s40, s94, s40
	s_addc_u32 s41, s95, s41
	s_lshl_b32 s8, s8, 10
	v_lshl_add_u64 v[192:193], s[40:41], 0, v[144:145]
	s_add_i32 s8, s8, 0
	s_add_i32 m0, s8, 0xc000
	v_lshl_add_u64 v[200:201], s[50:51], 1, v[192:193]
	global_load_lds_dwordx4 v[200:201], off
	v_lshl_add_u64 v[192:193], s[52:53], 1, v[192:193]
	s_add_i32 m0, s8, 0xe000
	s_nop 0
	global_load_lds_dwordx4 v[192:193], off
	s_waitcnt vmcnt(10)
	s_barrier
; #define LDA(dst, b, h) _Pragma("unroll") for (int m = 0; m < 4; ++m) _Pragma("unroll") for (int k = 0; k < 2; ++k) \
;     dst[m][k] = *reinterpret_cast<const LAS bf16x8*>(lds + SAo(b, h) + lds_byte(wr * 64 + m * 16 + fr, k * 32 + fq * 8))
; #define LDB(dst, b, h) _Pragma("unroll") for (int n = 0; n < 2; ++n) _Pragma("unroll") for (int k = 0; k < 2; ++k) \
;     dst[n][k] = *reinterpret_cast<const LAS bf16x8*>(lds + SBo(b, h) + lds_byte(wc * 32 + n * 16 + fr, k * 32 + fq * 8))
; #define MMA(ai, bj, At_, Bt_) do { __builtin_amdgcn_s_setprio(1); \
;     _Pragma("unroll") for (int m = 0; m < 4; ++m) _Pragma("unroll") for (int n = 0; n < 2; ++n) _Pragma("unroll") for (int k = 0; k < 2; ++k) \
;       acc[ai][bj][m][n] = __builtin_amdgcn_mfma_f32_16x16x32_bf16(Bt_[n][k], At_[m][k], acc[ai][bj][m][n], 0, 0, 0); \
;     __builtin_amdgcn_s_setprio(0); } while (0)
; #define WAIT_V(n) asm volatile("s_waitcnt vmcnt(" #n ")" ::: "memory")
; #define WAIT_L(n) asm volatile("s_waitcnt lgkmcnt(" #n ")" ::: "memory")
; #define BAR __builtin_amdgcn_s_barrier()
; template <bool PRE = false>
; __device__ __forceinline__ void gemm_kloop(Acc& acc, const bf16_t* __restrict__ A, int lda, const bf16_t* __restrict__ Bt, int ldb,
;                                            int brow, int bcol, int nt, LAS unsigned char* lds) {
;     ...
;     { LDB(B0, 0, 0); LDA(At, 0, 0); STAGE(SAo(1, 1), A, lda, brow + HALF, nt - 1, offA);
;       BAR; WAIT_L(0); MMA(0, 0, At, B0); BAR;
;       LDB(B1, 0, 1); BAR; WAIT_L(0); MMA(0, 1, At, B1); BAR;
;       LDA(At, 0, 1); WAIT_V(4); BAR; WAIT_L(0); MMA(1, 0, At, B0); MMA(1, 1, At, B1); BAR; }
;     { LDB(B0, 1, 0); LDA(At, 1, 0); WAIT_V(2); BAR; WAIT_L(0); MMA(0, 0, At, B0); BAR;
;       LDB(B1, 1, 1); WAIT_V(0); BAR; WAIT_L(0); MMA(0, 1, At, B1); BAR;
	s_waitcnt lgkmcnt(0)
	s_setprio 1
	s_waitcnt lgkmcnt(0)
	v_mfma_f32_16x16x32_bf16 v[114:117], v[150:153], v[166:169], v[114:117]
	v_mfma_f32_16x16x32_bf16 v[102:105], v[130:133], v[188:191], v[102:105]
	v_mfma_f32_16x16x32_bf16 v[98:101], v[150:153], v[188:191], v[98:101]
	v_mfma_f32_16x16x32_bf16 v[126:129], v[130:133], v[158:161], v[126:129]
	v_mfma_f32_16x16x32_bf16 v[122:125], v[150:153], v[158:161], v[122:125]
	v_mfma_f32_16x16x32_bf16 v[118:121], v[130:133], v[166:169], v[118:121]
	v_mfma_f32_16x16x32_bf16 v[114:117], v[154:157], v[170:173], v[114:117]
	v_mfma_f32_16x16x32_bf16 v[110:113], v[130:133], v[174:177], v[110:113]
	v_mfma_f32_16x16x32_bf16 v[106:109], v[150:153], v[174:177], v[106:109]
	v_mfma_f32_16x16x32_bf16 v[102:105], v[146:149], v[204:207], v[102:105]
	v_mfma_f32_16x16x32_bf16 v[98:101], v[154:157], v[204:207], v[98:101]
	v_mfma_f32_16x16x32_bf16 v[126:129], v[146:149], v[162:165], v[126:129]
	v_mfma_f32_16x16x32_bf16 v[122:125], v[154:157], v[162:165], v[122:125]
	v_mfma_f32_16x16x32_bf16 v[118:121], v[146:149], v[170:173], v[118:121]
	v_mfma_f32_16x16x32_bf16 v[208:211], v[146:149], v[184:187], v[110:113]
	v_mfma_f32_16x16x32_bf16 v[212:215], v[154:157], v[184:187], v[106:109]
	s_setprio 0
	s_barrier
	s_nop 0
	ds_read_b128 v[106:109], v140
	ds_read_b128 v[110:113], v140 offset:1024
	ds_read_b128 v[216:219], v140 offset:2048
	ds_read_b128 v[220:223], v140 offset:3072
	s_waitcnt vmcnt(8)
	s_barrier
	s_waitcnt lgkmcnt(0)
	s_setprio 1
	s_waitcnt lgkmcnt(0)
	v_mfma_f32_16x16x32_bf16 v[86:89], v[106:109], v[166:169], v[86:89]
	v_mfma_f32_16x16x32_bf16 v[82:85], v[216:219], v[166:169], v[82:85]
	v_mfma_f32_16x16x32_bf16 v[70:73], v[106:109], v[188:191], v[70:73]
	v_mfma_f32_16x16x32_bf16 v[66:69], v[216:219], v[188:191], v[66:69]
	v_mfma_f32_16x16x32_bf16 v[94:97], v[106:109], v[158:161], v[94:97]
	v_mfma_f32_16x16x32_bf16 v[90:93], v[216:219], v[158:161], v[90:93]
	v_mfma_f32_16x16x32_bf16 v[86:89], v[110:113], v[170:173], v[86:89]
	v_mfma_f32_16x16x32_bf16 v[82:85], v[220:223], v[170:173], v[82:85]
	v_mfma_f32_16x16x32_bf16 v[78:81], v[106:109], v[174:177], v[78:81]
	v_mfma_f32_16x16x32_bf16 v[74:77], v[216:219], v[174:177], v[74:77]
	v_mfma_f32_16x16x32_bf16 v[70:73], v[110:113], v[204:207], v[70:73]
	v_mfma_f32_16x16x32_bf16 v[66:69], v[220:223], v[204:207], v[66:69]
	v_mfma_f32_16x16x32_bf16 v[224:227], v[110:113], v[162:165], v[94:97]
	v_mfma_f32_16x16x32_bf16 v[158:161], v[220:223], v[162:165], v[90:93]
	v_mfma_f32_16x16x32_bf16 v[162:165], v[110:113], v[184:187], v[78:81]
	v_mfma_f32_16x16x32_bf16 v[166:169], v[220:223], v[184:187], v[74:77]
	s_setprio 0
	s_barrier
	s_nop 0
	ds_read_b128 v[74:77], v137 offset:16384
	ds_read_b128 v[78:81], v137 offset:17408
	ds_read_b128 v[90:93], v136 offset:16384
	ds_read_b128 v[94:97], v136 offset:17408
	ds_read_b128 v[170:173], v135 offset:16384
	ds_read_b128 v[174:177], v135 offset:17408
	ds_read_b128 v[184:187], v134 offset:16384
	ds_read_b128 v[188:191], v134 offset:17408
	s_waitcnt vmcnt(4)
	s_barrier
	s_waitcnt lgkmcnt(0)
	s_setprio 1
	s_waitcnt lgkmcnt(0)
	v_mfma_f32_16x16x32_bf16 v[62:65], v[130:133], v[74:77], v[62:65]
	v_mfma_f32_16x16x32_bf16 v[58:61], v[150:153], v[74:77], v[58:61]
	v_mfma_f32_16x16x32_bf16 v[54:57], v[130:133], v[90:93], v[54:57]
	v_mfma_f32_16x16x32_bf16 v[50:53], v[150:153], v[90:93], v[50:53]
	v_mfma_f32_16x16x32_bf16 v[38:41], v[130:133], v[184:187], v[38:41]
	v_mfma_f32_16x16x32_bf16 v[34:37], v[150:153], v[184:187], v[34:37]
	v_mfma_f32_16x16x32_bf16 v[62:65], v[146:149], v[78:81], v[62:65]
	v_mfma_f32_16x16x32_bf16 v[58:61], v[154:157], v[78:81], v[58:61]
	v_mfma_f32_16x16x32_bf16 v[54:57], v[146:149], v[94:97], v[54:57]
	v_mfma_f32_16x16x32_bf16 v[50:53], v[154:157], v[94:97], v[50:53]
	v_mfma_f32_16x16x32_bf16 v[46:49], v[130:133], v[170:173], v[46:49]
	v_mfma_f32_16x16x32_bf16 v[42:45], v[150:153], v[170:173], v[42:45]
	v_mfma_f32_16x16x32_bf16 v[38:41], v[146:149], v[188:191], v[38:41]
	v_mfma_f32_16x16x32_bf16 v[34:37], v[154:157], v[188:191], v[34:37]
	v_mfma_f32_16x16x32_bf16 v[204:207], v[146:149], v[174:177], v[46:49]
	v_mfma_f32_16x16x32_bf16 v[228:231], v[154:157], v[174:177], v[42:45]
	s_setprio 0
	s_setprio 1
	v_mfma_f32_16x16x32_bf16 v[22:25], v[106:109], v[90:93], v[22:25]
	v_mfma_f32_16x16x32_bf16 v[18:21], v[216:219], v[90:93], v[18:21]
	v_mfma_f32_16x16x32_bf16 v[6:9], v[106:109], v[184:187], v[6:9]
	v_mfma_f32_16x16x32_bf16 v[2:5], v[216:219], v[184:187], v[2:5]
	v_mfma_f32_16x16x32_bf16 v[30:33], v[106:109], v[74:77], v[30:33]
	v_mfma_f32_16x16x32_bf16 v[26:29], v[216:219], v[74:77], v[26:29]
	v_mfma_f32_16x16x32_bf16 v[22:25], v[110:113], v[94:97], v[22:25]
	v_mfma_f32_16x16x32_bf16 v[18:21], v[220:223], v[94:97], v[18:21]
	v_mfma_f32_16x16x32_bf16 v[14:17], v[106:109], v[170:173], v[14:17]
	v_mfma_f32_16x16x32_bf16 v[10:13], v[216:219], v[170:173], v[10:13]
	v_mfma_f32_16x16x32_bf16 v[6:9], v[110:113], v[188:191], v[6:9]
	v_mfma_f32_16x16x32_bf16 v[2:5], v[220:223], v[188:191], v[2:5]
	v_mfma_f32_16x16x32_bf16 v[130:133], v[110:113], v[78:81], v[30:33]
	v_mfma_f32_16x16x32_bf16 v[154:157], v[220:223], v[78:81], v[26:29]
	v_mfma_f32_16x16x32_bf16 v[232:235], v[110:113], v[174:177], v[14:17]
	v_mfma_f32_16x16x32_bf16 v[170:173], v[220:223], v[174:177], v[10:13]
	s_setprio 0
	s_barrier
	s_nop 0
	ds_read_b128 v[10:13], v139
	ds_read_b128 v[14:17], v139 offset:1024
	ds_read_b128 v[174:177], v139 offset:2048
	ds_read_b128 v[184:187], v139 offset:3072
	ds_read_b128 v[26:29], v137 offset:32768
	ds_read_b128 v[30:33], v137 offset:33792
	ds_read_b128 v[42:45], v136 offset:32768
	ds_read_b128 v[46:49], v136 offset:33792
	ds_read_b128 v[188:191], v135 offset:32768
	ds_read_b128 v[216:219], v135 offset:33792
	ds_read_b128 v[220:223], v134 offset:32768
	ds_read_b128 v[236:239], v134 offset:33792
	s_waitcnt vmcnt(2)
	s_barrier
; #define LDA(dst, b, h) _Pragma("unroll") for (int m = 0; m < 4; ++m) _Pragma("unroll") for (int k = 0; k < 2; ++k) \
;     dst[m][k] = *reinterpret_cast<const LAS bf16x8*>(lds + SAo(b, h) + lds_byte(wr * 64 + m * 16 + fr, k * 32 + fq * 8))
; #define LDB(dst, b, h) _Pragma("unroll") for (int n = 0; n < 2; ++n) _Pragma("unroll") for (int k = 0; k < 2; ++k) \
;     dst[n][k] = *reinterpret_cast<const LAS bf16x8*>(lds + SBo(b, h) + lds_byte(wc * 32 + n * 16 + fr, k * 32 + fq * 8))
; #define MMA(ai, bj, At_, Bt_) do { __builtin_amdgcn_s_setprio(1); \
;     _Pragma("unroll") for (int m = 0; m < 4; ++m) _Pragma("unroll") for (int n = 0; n < 2; ++n) _Pragma("unroll") for (int k = 0; k < 2; ++k) \
;       acc[ai][bj][m][n] = __builtin_amdgcn_mfma_f32_16x16x32_bf16(Bt_[n][k], At_[m][k], acc[ai][bj][m][n], 0, 0, 0); \
;     __builtin_amdgcn_s_setprio(0); } while (0)
; #define WAIT_V(n) asm volatile("s_waitcnt vmcnt(" #n ")" ::: "memory")
; #define WAIT_L(n) asm volatile("s_waitcnt lgkmcnt(" #n ")" ::: "memory")
; #define BAR __builtin_amdgcn_s_barrier()
; template <bool PRE = false>
; __device__ __forceinline__ void gemm_kloop(Acc& acc, const bf16_t* __restrict__ A, int lda, const bf16_t* __restrict__ Bt, int ldb,
;                                            int brow, int bcol, int nt, LAS unsigned char* lds) {
;     ...
;       LDA(At, 0, 1); WAIT_V(4); BAR; WAIT_L(0); MMA(1, 0, At, B0); MMA(1, 1, At, B1); BAR; }
;     { LDB(B0, 1, 0); LDA(At, 1, 0); WAIT_V(2); BAR; WAIT_L(0); MMA(0, 0, At, B0); BAR;
;       LDB(B1, 1, 1); WAIT_V(0); BAR; WAIT_L(0); MMA(0, 1, At, B1); BAR;
;       LDA(At, 1, 1); BAR; WAIT_L(0); MMA(1, 0, At, B0); MMA(1, 1, At, B1); BAR; }
;     if (wr == 0) BAR;
	s_waitcnt lgkmcnt(0)
	s_setprio 1
	s_waitcnt lgkmcnt(0)
	v_mfma_f32_16x16x32_bf16 v[74:77], v[10:13], v[26:29], v[126:129]
	v_mfma_f32_16x16x32_bf16 v[150:153], v[14:17], v[30:33], v[74:77]
	v_mfma_f32_16x16x32_bf16 v[74:77], v[174:177], v[26:29], v[122:125]
	v_mfma_f32_16x16x32_bf16 v[146:149], v[184:187], v[30:33], v[74:77]
	v_mfma_f32_16x16x32_bf16 v[74:77], v[10:13], v[42:45], v[118:121]
	v_mfma_f32_16x16x32_bf16 v[110:113], v[14:17], v[46:49], v[74:77]
	v_mfma_f32_16x16x32_bf16 v[74:77], v[174:177], v[42:45], v[114:117]
	v_mfma_f32_16x16x32_bf16 v[106:109], v[184:187], v[46:49], v[74:77]
	v_mfma_f32_16x16x32_bf16 v[74:77], v[10:13], v[188:191], v[208:211]
	v_mfma_f32_16x16x32_bf16 v[94:97], v[14:17], v[216:219], v[74:77]
	v_mfma_f32_16x16x32_bf16 v[74:77], v[174:177], v[188:191], v[212:215]
	v_mfma_f32_16x16x32_bf16 v[90:93], v[184:187], v[216:219], v[74:77]
	v_mfma_f32_16x16x32_bf16 v[74:77], v[10:13], v[220:223], v[102:105]
	v_mfma_f32_16x16x32_bf16 v[78:81], v[14:17], v[236:239], v[74:77]
	v_mfma_f32_16x16x32_bf16 v[74:77], v[174:177], v[220:223], v[98:101]
	v_mfma_f32_16x16x32_bf16 v[74:77], v[184:187], v[236:239], v[74:77]
	s_setprio 0
	s_barrier
	ds_read_b128 v[118:121], v138
	ds_read_b128 v[122:125], v138 offset:1024
	ds_read_b128 v[126:129], v138 offset:2048
	ds_read_b128 v[208:211], v138 offset:3072
	s_waitcnt vmcnt(0)
	s_barrier
	s_waitcnt lgkmcnt(0)
	s_setprio 1
	s_waitcnt lgkmcnt(0)
	v_mfma_f32_16x16x32_bf16 v[98:101], v[118:121], v[26:29], v[224:227]
	v_mfma_f32_16x16x32_bf16 v[26:29], v[126:129], v[26:29], v[158:161]
	v_mfma_f32_16x16x32_bf16 v[114:117], v[208:211], v[30:33], v[26:29]
	v_mfma_f32_16x16x32_bf16 v[26:29], v[118:121], v[42:45], v[86:89]
	v_mfma_f32_16x16x32_bf16 v[102:105], v[122:125], v[46:49], v[26:29]
	v_mfma_f32_16x16x32_bf16 v[26:29], v[126:129], v[42:45], v[82:85]
	v_mfma_f32_16x16x32_bf16 v[138:141], v[122:125], v[30:33], v[98:101]
	v_mfma_f32_16x16x32_bf16 v[98:101], v[208:211], v[46:49], v[26:29]
	v_mfma_f32_16x16x32_bf16 v[26:29], v[118:121], v[188:191], v[162:165]
	v_mfma_f32_16x16x32_bf16 v[86:89], v[122:125], v[216:219], v[26:29]
	v_mfma_f32_16x16x32_bf16 v[26:29], v[126:129], v[188:191], v[166:169]
	v_mfma_f32_16x16x32_bf16 v[82:85], v[208:211], v[216:219], v[26:29]
	v_mfma_f32_16x16x32_bf16 v[26:29], v[118:121], v[220:223], v[70:73]
	v_mfma_f32_16x16x32_bf16 v[70:73], v[122:125], v[236:239], v[26:29]
	v_mfma_f32_16x16x32_bf16 v[26:29], v[126:129], v[220:223], v[66:69]
	v_mfma_f32_16x16x32_bf16 v[66:69], v[208:211], v[236:239], v[26:29]
	s_setprio 0
	s_barrier
	ds_read_b128 v[158:161], v137 offset:49152
	ds_read_b128 v[162:165], v137 offset:50176
	ds_read_b128 v[166:169], v136 offset:49152
	ds_read_b128 v[188:191], v136 offset:50176
	ds_read_b128 v[212:215], v135 offset:49152
	ds_read_b128 v[216:219], v135 offset:50176
	ds_read_b128 v[220:223], v134 offset:49152
	ds_read_b128 v[134:137], v134 offset:50176
	s_barrier
	s_waitcnt lgkmcnt(0)
	s_setprio 1
	s_waitcnt lgkmcnt(0)
	v_mfma_f32_16x16x32_bf16 v[26:29], v[10:13], v[158:161], v[62:65]
	v_mfma_f32_16x16x32_bf16 v[62:65], v[14:17], v[162:165], v[26:29]
	v_mfma_f32_16x16x32_bf16 v[26:29], v[174:177], v[158:161], v[58:61]
	v_mfma_f32_16x16x32_bf16 v[58:61], v[184:187], v[162:165], v[26:29]
	v_mfma_f32_16x16x32_bf16 v[26:29], v[10:13], v[166:169], v[54:57]
	v_mfma_f32_16x16x32_bf16 v[46:49], v[14:17], v[188:191], v[26:29]
	v_mfma_f32_16x16x32_bf16 v[26:29], v[174:177], v[166:169], v[50:53]
	v_mfma_f32_16x16x32_bf16 v[42:45], v[184:187], v[188:191], v[26:29]
	v_mfma_f32_16x16x32_bf16 v[26:29], v[10:13], v[212:215], v[204:207]
	v_mfma_f32_16x16x32_bf16 v[10:13], v[10:13], v[220:223], v[38:41]
	v_mfma_f32_16x16x32_bf16 v[30:33], v[14:17], v[216:219], v[26:29]
	v_mfma_f32_16x16x32_bf16 v[26:29], v[174:177], v[212:215], v[228:231]
	v_mfma_f32_16x16x32_bf16 v[14:17], v[14:17], v[134:137], v[10:13]
	v_mfma_f32_16x16x32_bf16 v[10:13], v[174:177], v[220:223], v[34:37]
	v_mfma_f32_16x16x32_bf16 v[26:29], v[184:187], v[216:219], v[26:29]
	v_mfma_f32_16x16x32_bf16 v[10:13], v[184:187], v[134:137], v[10:13]
	s_setprio 0
	s_setprio 1
	v_mfma_f32_16x16x32_bf16 v[34:37], v[118:121], v[158:161], v[130:133]
	v_mfma_f32_16x16x32_bf16 v[54:57], v[122:125], v[162:165], v[34:37]
	v_mfma_f32_16x16x32_bf16 v[34:37], v[126:129], v[158:161], v[154:157]
	v_mfma_f32_16x16x32_bf16 v[18:21], v[126:129], v[166:169], v[18:21]
	v_mfma_f32_16x16x32_bf16 v[50:53], v[208:211], v[162:165], v[34:37]
	v_mfma_f32_16x16x32_bf16 v[22:25], v[118:121], v[166:169], v[22:25]
	v_mfma_f32_16x16x32_bf16 v[34:37], v[208:211], v[188:191], v[18:21]
	v_mfma_f32_16x16x32_bf16 v[18:21], v[118:121], v[212:215], v[232:235]
	v_mfma_f32_16x16x32_bf16 v[38:41], v[122:125], v[188:191], v[22:25]
	v_mfma_f32_16x16x32_bf16 v[22:25], v[122:125], v[216:219], v[18:21]
	v_mfma_f32_16x16x32_bf16 v[18:21], v[126:129], v[212:215], v[170:173]
	v_mfma_f32_16x16x32_bf16 v[6:9], v[118:121], v[220:223], v[6:9]
	v_mfma_f32_16x16x32_bf16 v[2:5], v[126:129], v[220:223], v[2:5]
	v_mfma_f32_16x16x32_bf16 v[18:21], v[208:211], v[216:219], v[18:21]
	v_mfma_f32_16x16x32_bf16 v[6:9], v[122:125], v[134:137], v[6:9]
	v_mfma_f32_16x16x32_bf16 v[2:5], v[208:211], v[134:137], v[2:5]
	s_setprio 0
	v_cmp_gt_u32_e32 vcc, s85, v1
	s_barrier
	s_and_saveexec_b64 s[40:41], vcc
	s_cbranch_execz .LBB0_100
	s_barrier

; #define LDA(dst, b, h) _Pragma("unroll") for (int m = 0; m < 4; ++m) _Pragma("unroll") for (int k = 0; k < 2; ++k) \
;     dst[m][k] = *reinterpret_cast<const LAS bf16x8*>(lds + SAo(b, h) + lds_byte(wr * 64 + m * 16 + fr, k * 32 + fq * 8))
; #define LDB(dst, b, h) _Pragma("unroll") for (int n = 0; n < 2; ++n) _Pragma("unroll") for (int k = 0; k < 2; ++k) \
;     dst[n][k] = *reinterpret_cast<const LAS bf16x8*>(lds + SBo(b, h) + lds_byte(wc * 32 + n * 16 + fr, k * 32 + fq * 8))
; #define MMA(ai, bj, At_, Bt_) do { __builtin_amdgcn_s_setprio(1); \
;     _Pragma("unroll") for (int m = 0; m < 4; ++m) _Pragma("unroll") for (int n = 0; n < 2; ++n) _Pragma("unroll") for (int k = 0; k < 2; ++k) \
;       acc[ai][bj][m][n] = __builtin_amdgcn_mfma_f32_16x16x32_bf16(Bt_[n][k], At_[m][k], acc[ai][bj][m][n], 0, 0, 0); \
;     __builtin_amdgcn_s_setprio(0); } while (0)
; #define WAIT_L(n) asm volatile("s_waitcnt lgkmcnt(" #n ")" ::: "memory")
; #define BAR __builtin_amdgcn_s_barrier()
; #define SCHED __builtin_amdgcn_sched_barrier(0)
; template <bool PRE = false>
; __device__ __forceinline__ void gemm_kloop(Acc& acc, const bf16_t* __restrict__ A, int lda, const bf16_t* __restrict__ Bt, int ldb,
;                                            int brow, int bcol, int nt, LAS unsigned char* lds) {
;     ...
;     for (int t = 0; t < nt - 2; t += 2) {
;         LDB(B0, 0, 0); SCHED; LDA(At, 0, 0); STAGE(SAo(1, 1), A, lda, brow + HALF, t + 1, offA);
;         WAIT_L(8); BAR; WAIT_L(0); MMA(0, 0, At, B0); BAR; SCHED;
;         LDB(B1, 0, 1); STAGE(SBo(0, 0), Bt, ldb, bcol, t + 2, offB);
;         BAR; WAIT_L(0); MMA(0, 1, At, B1); BAR;
;         LDA(At, 0, 1); STAGE(SAo(0, 0), A, lda, brow, t + 2, offA);
;         BAR; WAIT_L(0); MMA(1, 0, At, B0); BAR; SCHED;
.LBB0_130:
	ds_read_b128 v[146:149], v141
	ds_read_b128 v[150:153], v141 offset:1024
	ds_read_b128 v[154:157], v141 offset:2048
	ds_read_b128 v[158:161], v141 offset:3072
	s_add_i32 s54, s1, 3
	s_mov_b32 s30, s57
	ds_read_b128 v[162:165], v137
	ds_read_b128 v[166:169], v137 offset:1024
	ds_read_b128 v[170:173], v136
	ds_read_b128 v[174:177], v136 offset:1024
	ds_read_b128 v[184:187], v135
	ds_read_b128 v[188:191], v135 offset:1024
	ds_read_b128 v[204:207], v134
	ds_read_b128 v[208:211], v134 offset:1024
	s_ashr_i32 s55, s54, 31
	s_lshl_b64 s[54:55], s[54:55], 7
	s_lshl_b32 s30, s30, 10
	v_lshl_add_u64 v[142:143], v[130:131], 0, s[54:55]
	s_add_i32 s30, s30, 0
	s_add_i32 m0, s30, 0xc000
	v_lshl_add_u64 v[192:193], v[142:143], 0, s[50:51]
	global_load_lds_dwordx4 v[192:193], off
	v_lshl_add_u64 v[142:143], v[142:143], 0, s[52:53]
	s_add_i32 m0, s30, 0xe000
	s_nop 0
	global_load_lds_dwordx4 v[142:143], off
	s_waitcnt lgkmcnt(8)
	s_waitcnt vmcnt(10)
	s_barrier
	s_waitcnt lgkmcnt(0)
	s_setprio 1
	s_waitcnt lgkmcnt(0)
	v_mfma_f32_16x16x32_bf16 v[126:129], v[146:149], v[162:165], v[126:129]
	v_mfma_f32_16x16x32_bf16 v[122:125], v[154:157], v[162:165], v[122:125]
	v_mfma_f32_16x16x32_bf16 v[118:121], v[146:149], v[170:173], v[118:121]
	v_mfma_f32_16x16x32_bf16 v[114:117], v[154:157], v[170:173], v[114:117]
	v_mfma_f32_16x16x32_bf16 v[110:113], v[146:149], v[184:187], v[110:113]
	v_mfma_f32_16x16x32_bf16 v[106:109], v[154:157], v[184:187], v[106:109]
	v_mfma_f32_16x16x32_bf16 v[102:105], v[146:149], v[204:207], v[102:105]
	v_mfma_f32_16x16x32_bf16 v[98:101], v[154:157], v[204:207], v[98:101]
	v_mfma_f32_16x16x32_bf16 v[126:129], v[150:153], v[166:169], v[126:129]
	v_mfma_f32_16x16x32_bf16 v[122:125], v[158:161], v[166:169], v[122:125]
	v_mfma_f32_16x16x32_bf16 v[118:121], v[150:153], v[174:177], v[118:121]
	v_mfma_f32_16x16x32_bf16 v[114:117], v[158:161], v[174:177], v[114:117]
	v_mfma_f32_16x16x32_bf16 v[110:113], v[150:153], v[188:191], v[110:113]
	v_mfma_f32_16x16x32_bf16 v[106:109], v[158:161], v[188:191], v[106:109]
	v_mfma_f32_16x16x32_bf16 v[102:105], v[150:153], v[208:211], v[102:105]
	v_mfma_f32_16x16x32_bf16 v[98:101], v[158:161], v[208:211], v[98:101]
	s_setprio 0
	s_barrier
	s_add_i32 s54, s1, 4
	s_mov_b32 s30, s57
	s_mov_b32 s58, s54
	ds_read_b128 v[212:215], v140
	ds_read_b128 v[216:219], v140 offset:1024
	ds_read_b128 v[220:223], v140 offset:2048
	ds_read_b128 v[224:227], v140 offset:3072
	s_ashr_i32 s59, s58, 31
	s_lshl_b64 s[58:59], s[58:59], 7
	s_lshl_b32 s30, s30, 10
	v_lshl_add_u64 v[142:143], v[132:133], 0, s[58:59]
	s_add_i32 s30, s30, 0
	s_add_i32 m0, s30, 0x10000
	v_lshl_add_u64 v[192:193], v[142:143], 0, s[12:13]
	global_load_lds_dwordx4 v[192:193], off
	v_lshl_add_u64 v[142:143], v[142:143], 0, s[40:41]
	s_add_i32 m0, s30, 0x12000
	s_nop 0
	global_load_lds_dwordx4 v[142:143], off
	s_waitcnt vmcnt(10)
	s_barrier
	s_waitcnt lgkmcnt(0)
	s_setprio 1
	s_waitcnt lgkmcnt(0)
	v_mfma_f32_16x16x32_bf16 v[94:97], v[212:215], v[162:165], v[94:97]
	v_mfma_f32_16x16x32_bf16 v[90:93], v[220:223], v[162:165], v[90:93]
	v_mfma_f32_16x16x32_bf16 v[86:89], v[212:215], v[170:173], v[86:89]
	v_mfma_f32_16x16x32_bf16 v[82:85], v[220:223], v[170:173], v[82:85]
	v_mfma_f32_16x16x32_bf16 v[78:81], v[212:215], v[184:187], v[78:81]
	v_mfma_f32_16x16x32_bf16 v[74:77], v[220:223], v[184:187], v[74:77]
	v_mfma_f32_16x16x32_bf16 v[70:73], v[212:215], v[204:207], v[70:73]
	v_mfma_f32_16x16x32_bf16 v[66:69], v[220:223], v[204:207], v[66:69]
	v_mfma_f32_16x16x32_bf16 v[94:97], v[216:219], v[166:169], v[94:97]
	v_mfma_f32_16x16x32_bf16 v[90:93], v[224:227], v[166:169], v[90:93]
	v_mfma_f32_16x16x32_bf16 v[86:89], v[216:219], v[174:177], v[86:89]
	v_mfma_f32_16x16x32_bf16 v[82:85], v[224:227], v[174:177], v[82:85]
	v_mfma_f32_16x16x32_bf16 v[78:81], v[216:219], v[188:191], v[78:81]
	v_mfma_f32_16x16x32_bf16 v[74:77], v[224:227], v[188:191], v[74:77]
	v_mfma_f32_16x16x32_bf16 v[70:73], v[216:219], v[208:211], v[70:73]
	v_mfma_f32_16x16x32_bf16 v[66:69], v[224:227], v[208:211], v[66:69]
	s_setprio 0
	s_mov_b32 s30, s57
	s_mov_b32 s58, s54
	s_barrier
	ds_read_b128 v[162:165], v137 offset:16384
	ds_read_b128 v[166:169], v137 offset:17408
	ds_read_b128 v[170:173], v136 offset:16384
	ds_read_b128 v[174:177], v136 offset:17408
	ds_read_b128 v[184:187], v135 offset:16384
	ds_read_b128 v[188:191], v135 offset:17408
	ds_read_b128 v[204:207], v134 offset:16384
	ds_read_b128 v[208:211], v134 offset:17408
	s_ashr_i32 s59, s58, 31
	s_lshl_b64 s[58:59], s[58:59], 7
	s_lshl_b32 s30, s30, 10
	v_lshl_add_u64 v[142:143], v[130:131], 0, s[58:59]
	s_add_i32 s30, s30, 0
	v_lshl_add_u64 v[192:193], v[142:143], 0, s[42:43]
	s_mov_b32 m0, s30
	v_lshl_add_u64 v[142:143], v[142:143], 0, s[44:45]
	global_load_lds_dwordx4 v[192:193], off
	s_add_i32 m0, s30, 0x2000
	s_nop 0
	global_load_lds_dwordx4 v[142:143], off
	s_barrier
	s_waitcnt lgkmcnt(0)
	s_setprio 1
	s_waitcnt lgkmcnt(0)
	v_mfma_f32_16x16x32_bf16 v[62:65], v[146:149], v[162:165], v[62:65]
	v_mfma_f32_16x16x32_bf16 v[58:61], v[154:157], v[162:165], v[58:61]
	v_mfma_f32_16x16x32_bf16 v[54:57], v[146:149], v[170:173], v[54:57]
	v_mfma_f32_16x16x32_bf16 v[50:53], v[154:157], v[170:173], v[50:53]
	v_mfma_f32_16x16x32_bf16 v[46:49], v[146:149], v[184:187], v[46:49]
	v_mfma_f32_16x16x32_bf16 v[42:45], v[154:157], v[184:187], v[42:45]
	v_mfma_f32_16x16x32_bf16 v[38:41], v[146:149], v[204:207], v[38:41]
	v_mfma_f32_16x16x32_bf16 v[34:37], v[154:157], v[204:207], v[34:37]
	v_mfma_f32_16x16x32_bf16 v[62:65], v[150:153], v[166:169], v[62:65]
	v_mfma_f32_16x16x32_bf16 v[58:61], v[158:161], v[166:169], v[58:61]
	v_mfma_f32_16x16x32_bf16 v[54:57], v[150:153], v[174:177], v[54:57]
	v_mfma_f32_16x16x32_bf16 v[50:53], v[158:161], v[174:177], v[50:53]
	v_mfma_f32_16x16x32_bf16 v[46:49], v[150:153], v[188:191], v[46:49]
	v_mfma_f32_16x16x32_bf16 v[42:45], v[158:161], v[188:191], v[42:45]
	v_mfma_f32_16x16x32_bf16 v[38:41], v[150:153], v[208:211], v[38:41]
	v_mfma_f32_16x16x32_bf16 v[34:37], v[158:161], v[208:211], v[34:37]
	s_setprio 0
	s_barrier
; #define LDA(dst, b, h) _Pragma("unroll") for (int m = 0; m < 4; ++m) _Pragma("unroll") for (int k = 0; k < 2; ++k) \
;     dst[m][k] = *reinterpret_cast<const LAS bf16x8*>(lds + SAo(b, h) + lds_byte(wr * 64 + m * 16 + fr, k * 32 + fq * 8))
; #define LDB(dst, b, h) _Pragma("unroll") for (int n = 0; n < 2; ++n) _Pragma("unroll") for (int k = 0; k < 2; ++k) \
;     dst[n][k] = *reinterpret_cast<const LAS bf16x8*>(lds + SBo(b, h) + lds_byte(wc * 32 + n * 16 + fr, k * 32 + fq * 8))
; #define MMA(ai, bj, At_, Bt_) do { __builtin_amdgcn_s_setprio(1); \
;     _Pragma("unroll") for (int m = 0; m < 4; ++m) _Pragma("unroll") for (int n = 0; n < 2; ++n) _Pragma("unroll") for (int k = 0; k < 2; ++k) \
;       acc[ai][bj][m][n] = __builtin_amdgcn_mfma_f32_16x16x32_bf16(Bt_[n][k], At_[m][k], acc[ai][bj][m][n], 0, 0, 0); \
;     __builtin_amdgcn_s_setprio(0); } while (0)
; #define WAIT_V(n) asm volatile("s_waitcnt vmcnt(" #n ")" ::: "memory")
; #define WAIT_L(n) asm volatile("s_waitcnt lgkmcnt(" #n ")" ::: "memory")
; #define BAR __builtin_amdgcn_s_barrier()
; #define SCHED __builtin_amdgcn_sched_barrier(0)
; template <bool PRE = false>
; __device__ __forceinline__ void gemm_kloop(Acc& acc, const bf16_t* __restrict__ A, int lda, const bf16_t* __restrict__ Bt, int ldb,
;                                            int brow, int bcol, int nt, LAS unsigned char* lds) {
;     ...
;         STAGE(SBo(0, 1), Bt, ldb, bcol + HALF, t + 2, offB);
;         WAIT_V(6); BAR; MMA(1, 1, At, B1); BAR;
;         LDB(B0, 1, 0); SCHED; LDA(At, 1, 0); STAGE(SAo(0, 1), A, lda, brow + HALF, t + 2, offA);
;         WAIT_L(8); BAR; WAIT_L(0); MMA(0, 0, At, B0); BAR; SCHED;
;         LDB(B1, 1, 1); STAGE(SBo(1, 0), Bt, ldb, bcol, t + 3, offB);
;         BAR; WAIT_L(0); MMA(0, 1, At, B1); BAR;
	s_mov_b32 s30, s57
	s_mov_b32 s58, s54
	s_ashr_i32 s59, s58, 31
	s_lshl_b64 s[58:59], s[58:59], 7
	s_lshl_b32 s30, s30, 10
	v_lshl_add_u64 v[142:143], v[132:133], 0, s[58:59]
	s_add_i32 s30, s30, 0
	s_add_i32 m0, s30, 0x14000
	v_lshl_add_u64 v[146:147], v[142:143], 0, s[46:47]
	global_load_lds_dwordx4 v[146:147], off
	v_lshl_add_u64 v[142:143], v[142:143], 0, s[48:49]
	s_add_i32 m0, s30, 0x16000
	s_nop 0
	global_load_lds_dwordx4 v[142:143], off
	s_waitcnt vmcnt(10)
	s_barrier
	s_setprio 1
	v_mfma_f32_16x16x32_bf16 v[30:33], v[212:215], v[162:165], v[30:33]
	v_mfma_f32_16x16x32_bf16 v[26:29], v[220:223], v[162:165], v[26:29]
	v_mfma_f32_16x16x32_bf16 v[22:25], v[212:215], v[170:173], v[22:25]
	v_mfma_f32_16x16x32_bf16 v[18:21], v[220:223], v[170:173], v[18:21]
	v_mfma_f32_16x16x32_bf16 v[14:17], v[212:215], v[184:187], v[14:17]
	v_mfma_f32_16x16x32_bf16 v[10:13], v[220:223], v[184:187], v[10:13]
	v_mfma_f32_16x16x32_bf16 v[6:9], v[212:215], v[204:207], v[6:9]
	v_mfma_f32_16x16x32_bf16 v[2:5], v[220:223], v[204:207], v[2:5]
	v_mfma_f32_16x16x32_bf16 v[30:33], v[216:219], v[166:169], v[30:33]
	v_mfma_f32_16x16x32_bf16 v[26:29], v[224:227], v[166:169], v[26:29]
	v_mfma_f32_16x16x32_bf16 v[22:25], v[216:219], v[174:177], v[22:25]
	v_mfma_f32_16x16x32_bf16 v[18:21], v[224:227], v[174:177], v[18:21]
	v_mfma_f32_16x16x32_bf16 v[14:17], v[216:219], v[188:191], v[14:17]
	v_mfma_f32_16x16x32_bf16 v[10:13], v[224:227], v[188:191], v[10:13]
	v_mfma_f32_16x16x32_bf16 v[6:9], v[216:219], v[208:211], v[6:9]
	v_mfma_f32_16x16x32_bf16 v[2:5], v[224:227], v[208:211], v[2:5]
	s_setprio 0
	s_barrier
	ds_read_b128 v[146:149], v139
	ds_read_b128 v[150:153], v139 offset:1024
	ds_read_b128 v[154:157], v139 offset:2048
	ds_read_b128 v[158:161], v139 offset:3072
	s_mov_b32 s30, s57
	ds_read_b128 v[162:165], v137 offset:32768
	ds_read_b128 v[166:169], v137 offset:33792
	ds_read_b128 v[170:173], v136 offset:32768
	ds_read_b128 v[174:177], v136 offset:33792
	ds_read_b128 v[184:187], v135 offset:32768
	ds_read_b128 v[188:191], v135 offset:33792
	ds_read_b128 v[204:207], v134 offset:32768
	ds_read_b128 v[208:211], v134 offset:33792
	s_ashr_i32 s55, s54, 31
	s_lshl_b64 s[54:55], s[54:55], 7
	s_lshl_b32 s30, s30, 10
	v_lshl_add_u64 v[142:143], v[130:131], 0, s[54:55]
	s_add_i32 s30, s30, 0
	s_add_i32 m0, s30, 0x4000
	v_lshl_add_u64 v[192:193], v[142:143], 0, s[50:51]
	global_load_lds_dwordx4 v[192:193], off
	v_lshl_add_u64 v[142:143], v[142:143], 0, s[52:53]
	s_add_i32 m0, s30, 0x6000
	s_nop 0
	global_load_lds_dwordx4 v[142:143], off
	s_waitcnt lgkmcnt(8)
	s_waitcnt vmcnt(10)
	s_barrier
	s_waitcnt lgkmcnt(0)
	s_setprio 1
	s_waitcnt lgkmcnt(0)
	v_mfma_f32_16x16x32_bf16 v[126:129], v[146:149], v[162:165], v[126:129]
	v_mfma_f32_16x16x32_bf16 v[122:125], v[154:157], v[162:165], v[122:125]
	v_mfma_f32_16x16x32_bf16 v[118:121], v[146:149], v[170:173], v[118:121]
	v_mfma_f32_16x16x32_bf16 v[114:117], v[154:157], v[170:173], v[114:117]
	v_mfma_f32_16x16x32_bf16 v[110:113], v[146:149], v[184:187], v[110:113]
	v_mfma_f32_16x16x32_bf16 v[106:109], v[154:157], v[184:187], v[106:109]
	v_mfma_f32_16x16x32_bf16 v[102:105], v[146:149], v[204:207], v[102:105]
	v_mfma_f32_16x16x32_bf16 v[98:101], v[154:157], v[204:207], v[98:101]
	v_mfma_f32_16x16x32_bf16 v[126:129], v[150:153], v[166:169], v[126:129]
	v_mfma_f32_16x16x32_bf16 v[122:125], v[158:161], v[166:169], v[122:125]
	v_mfma_f32_16x16x32_bf16 v[118:121], v[150:153], v[174:177], v[118:121]
	v_mfma_f32_16x16x32_bf16 v[114:117], v[158:161], v[174:177], v[114:117]
	v_mfma_f32_16x16x32_bf16 v[110:113], v[150:153], v[188:191], v[110:113]
	v_mfma_f32_16x16x32_bf16 v[106:109], v[158:161], v[188:191], v[106:109]
	v_mfma_f32_16x16x32_bf16 v[102:105], v[150:153], v[208:211], v[102:105]
	v_mfma_f32_16x16x32_bf16 v[98:101], v[158:161], v[208:211], v[98:101]
	s_setprio 0
	s_barrier
	s_add_i32 s54, s1, 5
	s_mov_b32 s30, s57
	s_mov_b32 s58, s54
	ds_read_b128 v[212:215], v138
	ds_read_b128 v[216:219], v138 offset:1024
	ds_read_b128 v[220:223], v138 offset:2048
	ds_read_b128 v[224:227], v138 offset:3072
	s_ashr_i32 s59, s58, 31
	s_lshl_b64 s[58:59], s[58:59], 7
	s_lshl_b32 s30, s30, 10
	v_lshl_add_u64 v[142:143], v[132:133], 0, s[58:59]
	s_add_i32 s30, s30, 0
	s_add_i32 m0, s30, 0x18000
	v_lshl_add_u64 v[192:193], v[142:143], 0, s[12:13]
	global_load_lds_dwordx4 v[192:193], off
	v_lshl_add_u64 v[142:143], v[142:143], 0, s[40:41]
	s_add_i32 m0, s30, 0x1a000
	s_nop 0
	global_load_lds_dwordx4 v[142:143], off
	s_waitcnt vmcnt(10)
	s_barrier
	s_waitcnt lgkmcnt(0)
	s_setprio 1
	s_waitcnt lgkmcnt(0)
	v_mfma_f32_16x16x32_bf16 v[94:97], v[212:215], v[162:165], v[94:97]
	v_mfma_f32_16x16x32_bf16 v[90:93], v[220:223], v[162:165], v[90:93]
	v_mfma_f32_16x16x32_bf16 v[86:89], v[212:215], v[170:173], v[86:89]
	v_mfma_f32_16x16x32_bf16 v[82:85], v[220:223], v[170:173], v[82:85]
	v_mfma_f32_16x16x32_bf16 v[78:81], v[212:215], v[184:187], v[78:81]
	v_mfma_f32_16x16x32_bf16 v[74:77], v[220:223], v[184:187], v[74:77]
	v_mfma_f32_16x16x32_bf16 v[70:73], v[212:215], v[204:207], v[70:73]
	v_mfma_f32_16x16x32_bf16 v[66:69], v[220:223], v[204:207], v[66:69]
	v_mfma_f32_16x16x32_bf16 v[94:97], v[216:219], v[166:169], v[94:97]
	v_mfma_f32_16x16x32_bf16 v[90:93], v[224:227], v[166:169], v[90:93]
	v_mfma_f32_16x16x32_bf16 v[86:89], v[216:219], v[174:177], v[86:89]
	v_mfma_f32_16x16x32_bf16 v[82:85], v[224:227], v[174:177], v[82:85]
	v_mfma_f32_16x16x32_bf16 v[78:81], v[216:219], v[188:191], v[78:81]
	v_mfma_f32_16x16x32_bf16 v[74:77], v[224:227], v[188:191], v[74:77]
	v_mfma_f32_16x16x32_bf16 v[70:73], v[216:219], v[208:211], v[70:73]
	v_mfma_f32_16x16x32_bf16 v[66:69], v[224:227], v[208:211], v[66:69]
	s_setprio 0
	s_mov_b32 s30, s57
	s_mov_b32 s58, s54
	s_barrier
; #define LDA(dst, b, h) _Pragma("unroll") for (int m = 0; m < 4; ++m) _Pragma("unroll") for (int k = 0; k < 2; ++k) \
;     dst[m][k] = *reinterpret_cast<const LAS bf16x8*>(lds + SAo(b, h) + lds_byte(wr * 64 + m * 16 + fr, k * 32 + fq * 8))
; #define LDB(dst, b, h) _Pragma("unroll") for (int n = 0; n < 2; ++n) _Pragma("unroll") for (int k = 0; k < 2; ++k) \
;     dst[n][k] = *reinterpret_cast<const LAS bf16x8*>(lds + SBo(b, h) + lds_byte(wc * 32 + n * 16 + fr, k * 32 + fq * 8))
; #define MMA(ai, bj, At_, Bt_) do { __builtin_amdgcn_s_setprio(1); \
;     _Pragma("unroll") for (int m = 0; m < 4; ++m) _Pragma("unroll") for (int n = 0; n < 2; ++n) _Pragma("unroll") for (int k = 0; k < 2; ++k) \
;       acc[ai][bj][m][n] = __builtin_amdgcn_mfma_f32_16x16x32_bf16(Bt_[n][k], At_[m][k], acc[ai][bj][m][n], 0, 0, 0); \
;     __builtin_amdgcn_s_setprio(0); } while (0)
; #define WAIT_V(n) asm volatile("s_waitcnt vmcnt(" #n ")" ::: "memory")
; #define WAIT_L(n) asm volatile("s_waitcnt lgkmcnt(" #n ")" ::: "memory")
; #define BAR __builtin_amdgcn_s_barrier()
; #define SCHED __builtin_amdgcn_sched_barrier(0)
; template <bool PRE = false>
; __device__ __forceinline__ void gemm_kloop(Acc& acc, const bf16_t* __restrict__ A, int lda, const bf16_t* __restrict__ Bt, int ldb,
;                                            int brow, int bcol, int nt, LAS unsigned char* lds) {
;     ...
;         LDA(At, 1, 1); STAGE(SAo(1, 0), A, lda, brow, t + 3, offA);
;         BAR; WAIT_L(0); MMA(1, 0, At, B0); BAR; SCHED;
;         STAGE(SBo(1, 1), Bt, ldb, bcol + HALF, t + 3, offB);
;         WAIT_V(6); BAR; MMA(1, 1, At, B1); BAR;
;     }
;     { LDB(B0, 0, 0); LDA(At, 0, 0); STAGE(SAo(1, 1), A, lda, brow + HALF, nt - 1, offA);
;       BAR; WAIT_L(0); MMA(0, 0, At, B0); BAR;
	ds_read_b128 v[162:165], v137 offset:49152
	ds_read_b128 v[166:169], v137 offset:50176
	ds_read_b128 v[170:173], v136 offset:49152
	ds_read_b128 v[174:177], v136 offset:50176
	ds_read_b128 v[184:187], v135 offset:49152
	ds_read_b128 v[188:191], v135 offset:50176
	ds_read_b128 v[204:207], v134 offset:49152
	ds_read_b128 v[208:211], v134 offset:50176
	s_ashr_i32 s59, s58, 31
	s_lshl_b64 s[58:59], s[58:59], 7
	s_lshl_b32 s30, s30, 10
	v_lshl_add_u64 v[142:143], v[130:131], 0, s[58:59]
	s_add_i32 s30, s30, 0
	s_add_i32 m0, s30, 0x8000
	v_lshl_add_u64 v[192:193], v[142:143], 0, s[42:43]
	global_load_lds_dwordx4 v[192:193], off
	v_lshl_add_u64 v[142:143], v[142:143], 0, s[44:45]
	s_add_i32 m0, s30, 0xa000
	s_nop 0
	global_load_lds_dwordx4 v[142:143], off
	s_barrier
	s_waitcnt lgkmcnt(0)
	s_setprio 1
	s_waitcnt lgkmcnt(0)
	v_mfma_f32_16x16x32_bf16 v[62:65], v[146:149], v[162:165], v[62:65]
	v_mfma_f32_16x16x32_bf16 v[58:61], v[154:157], v[162:165], v[58:61]
	v_mfma_f32_16x16x32_bf16 v[54:57], v[146:149], v[170:173], v[54:57]
	v_mfma_f32_16x16x32_bf16 v[50:53], v[154:157], v[170:173], v[50:53]
	v_mfma_f32_16x16x32_bf16 v[46:49], v[146:149], v[184:187], v[46:49]
	v_mfma_f32_16x16x32_bf16 v[42:45], v[154:157], v[184:187], v[42:45]
	v_mfma_f32_16x16x32_bf16 v[38:41], v[146:149], v[204:207], v[38:41]
	v_mfma_f32_16x16x32_bf16 v[34:37], v[154:157], v[204:207], v[34:37]
	v_mfma_f32_16x16x32_bf16 v[62:65], v[150:153], v[166:169], v[62:65]
	v_mfma_f32_16x16x32_bf16 v[58:61], v[158:161], v[166:169], v[58:61]
	v_mfma_f32_16x16x32_bf16 v[54:57], v[150:153], v[174:177], v[54:57]
	v_mfma_f32_16x16x32_bf16 v[50:53], v[158:161], v[174:177], v[50:53]
	v_mfma_f32_16x16x32_bf16 v[46:49], v[150:153], v[188:191], v[46:49]
	v_mfma_f32_16x16x32_bf16 v[42:45], v[158:161], v[188:191], v[42:45]
	v_mfma_f32_16x16x32_bf16 v[38:41], v[150:153], v[208:211], v[38:41]
	v_mfma_f32_16x16x32_bf16 v[34:37], v[158:161], v[208:211], v[34:37]
	s_setprio 0
	s_barrier
	s_mov_b32 s30, s57
	s_ashr_i32 s55, s54, 31
	s_lshl_b64 s[54:55], s[54:55], 7
	s_lshl_b32 s30, s30, 10
	v_lshl_add_u64 v[142:143], v[132:133], 0, s[54:55]
	s_add_i32 s30, s30, 0
	s_add_i32 m0, s30, 0x1c000
	v_lshl_add_u64 v[146:147], v[142:143], 0, s[46:47]
	global_load_lds_dwordx4 v[146:147], off
	v_lshl_add_u64 v[142:143], v[142:143], 0, s[48:49]
	s_add_i32 m0, s30, 0x1e000
	s_nop 0
	global_load_lds_dwordx4 v[142:143], off
	s_waitcnt vmcnt(10)
	s_barrier
	s_setprio 1
	v_mfma_f32_16x16x32_bf16 v[30:33], v[212:215], v[162:165], v[30:33]
	v_mfma_f32_16x16x32_bf16 v[26:29], v[220:223], v[162:165], v[26:29]
	v_mfma_f32_16x16x32_bf16 v[22:25], v[212:215], v[170:173], v[22:25]
	v_mfma_f32_16x16x32_bf16 v[18:21], v[220:223], v[170:173], v[18:21]
	v_mfma_f32_16x16x32_bf16 v[14:17], v[212:215], v[184:187], v[14:17]
	v_mfma_f32_16x16x32_bf16 v[10:13], v[220:223], v[184:187], v[10:13]
	v_mfma_f32_16x16x32_bf16 v[6:9], v[212:215], v[204:207], v[6:9]
	v_mfma_f32_16x16x32_bf16 v[2:5], v[220:223], v[204:207], v[2:5]
	v_mfma_f32_16x16x32_bf16 v[30:33], v[216:219], v[166:169], v[30:33]
	v_mfma_f32_16x16x32_bf16 v[26:29], v[224:227], v[166:169], v[26:29]
	v_mfma_f32_16x16x32_bf16 v[22:25], v[216:219], v[174:177], v[22:25]
	v_mfma_f32_16x16x32_bf16 v[18:21], v[224:227], v[174:177], v[18:21]
	v_mfma_f32_16x16x32_bf16 v[14:17], v[216:219], v[188:191], v[14:17]
	v_mfma_f32_16x16x32_bf16 v[10:13], v[224:227], v[188:191], v[10:13]
	v_mfma_f32_16x16x32_bf16 v[6:9], v[216:219], v[208:211], v[6:9]
	v_mfma_f32_16x16x32_bf16 v[2:5], v[224:227], v[208:211], v[2:5]
	s_setprio 0
	s_add_i32 s1, s1, 2
	s_cmp_lt_u32 s1, 12
	s_barrier
	s_cbranch_scc1 .LBB0_130
	s_mov_b32 s12, 15
	ds_read_b128 v[130:133], v141
	ds_read_b128 v[146:149], v141 offset:1024
	ds_read_b128 v[150:153], v141 offset:2048
	ds_read_b128 v[154:157], v141 offset:3072
	ds_read_b128 v[158:161], v137
	ds_read_b128 v[162:165], v137 offset:1024
	ds_read_b128 v[166:169], v136
	ds_read_b128 v[170:173], v136 offset:1024
	ds_read_b128 v[174:177], v135
	ds_read_b128 v[184:187], v135 offset:1024
	ds_read_b128 v[188:191], v134
	ds_read_b128 v[204:207], v134 offset:1024
	s_ashr_i32 s13, s12, 31
	s_lshl_b64 s[12:13], s[12:13], 7
	s_add_u32 s12, s34, s12
	s_addc_u32 s13, s35, s13
	s_lshl_b32 s1, s57, 10
	v_lshl_add_u64 v[142:143], s[12:13], 0, v[144:145]
	s_add_i32 s1, s1, 0
	s_add_i32 m0, s1, 0xc000
	v_lshl_add_u64 v[192:193], v[142:143], 0, s[50:51]
	global_load_lds_dwordx4 v[192:193], off
	v_lshl_add_u64 v[142:143], v[142:143], 0, s[52:53]
	s_add_i32 m0, s1, 0xe000
	s_nop 0
	global_load_lds_dwordx4 v[142:143], off
	s_waitcnt vmcnt(10)
	s_barrier
	s_waitcnt lgkmcnt(0)
	s_setprio 1
	s_waitcnt lgkmcnt(0)
	v_mfma_f32_16x16x32_bf16 v[126:129], v[130:133], v[158:161], v[126:129]
	v_mfma_f32_16x16x32_bf16 v[118:121], v[130:133], v[166:169], v[118:121]
	v_mfma_f32_16x16x32_bf16 v[110:113], v[130:133], v[174:177], v[110:113]
	v_mfma_f32_16x16x32_bf16 v[102:105], v[130:133], v[188:191], v[102:105]
	v_mfma_f32_16x16x32_bf16 v[126:129], v[146:149], v[162:165], v[126:129]
	v_mfma_f32_16x16x32_bf16 v[122:125], v[150:153], v[158:161], v[122:125]
	v_mfma_f32_16x16x32_bf16 v[118:121], v[146:149], v[170:173], v[118:121]
	v_mfma_f32_16x16x32_bf16 v[114:117], v[150:153], v[166:169], v[114:117]
	v_mfma_f32_16x16x32_bf16 v[110:113], v[146:149], v[184:187], v[110:113]
	v_mfma_f32_16x16x32_bf16 v[106:109], v[150:153], v[174:177], v[106:109]
	v_mfma_f32_16x16x32_bf16 v[102:105], v[146:149], v[204:207], v[102:105]
	v_mfma_f32_16x16x32_bf16 v[98:101], v[150:153], v[188:191], v[98:101]
	v_mfma_f32_16x16x32_bf16 v[208:211], v[154:157], v[162:165], v[122:125]
	v_mfma_f32_16x16x32_bf16 v[212:215], v[154:157], v[170:173], v[114:117]
	v_mfma_f32_16x16x32_bf16 v[216:219], v[154:157], v[184:187], v[106:109]
	v_mfma_f32_16x16x32_bf16 v[220:223], v[154:157], v[204:207], v[98:101]
	s_setprio 0
	s_barrier
; #define LDA(dst, b, h) _Pragma("unroll") for (int m = 0; m < 4; ++m) _Pragma("unroll") for (int k = 0; k < 2; ++k) \
;     dst[m][k] = *reinterpret_cast<const LAS bf16x8*>(lds + SAo(b, h) + lds_byte(wr * 64 + m * 16 + fr, k * 32 + fq * 8))
; #define LDB(dst, b, h) _Pragma("unroll") for (int n = 0; n < 2; ++n) _Pragma("unroll") for (int k = 0; k < 2; ++k) \
;     dst[n][k] = *reinterpret_cast<const LAS bf16x8*>(lds + SBo(b, h) + lds_byte(wc * 32 + n * 16 + fr, k * 32 + fq * 8))
; #define MMA(ai, bj, At_, Bt_) do { __builtin_amdgcn_s_setprio(1); \
;     _Pragma("unroll") for (int m = 0; m < 4; ++m) _Pragma("unroll") for (int n = 0; n < 2; ++n) _Pragma("unroll") for (int k = 0; k < 2; ++k) \
;       acc[ai][bj][m][n] = __builtin_amdgcn_mfma_f32_16x16x32_bf16(Bt_[n][k], At_[m][k], acc[ai][bj][m][n], 0, 0, 0); \
;     __builtin_amdgcn_s_setprio(0); } while (0)
; #define WAIT_V(n) asm volatile("s_waitcnt vmcnt(" #n ")" ::: "memory")
; #define WAIT_L(n) asm volatile("s_waitcnt lgkmcnt(" #n ")" ::: "memory")
; #define BAR __builtin_amdgcn_s_barrier()
; template <bool PRE = false>
; __device__ __forceinline__ void gemm_kloop(Acc& acc, const bf16_t* __restrict__ A, int lda, const bf16_t* __restrict__ Bt, int ldb,
;                                            int brow, int bcol, int nt, LAS unsigned char* lds) {
;     ...
;       BAR; WAIT_L(0); MMA(0, 0, At, B0); BAR;
;       LDB(B1, 0, 1); BAR; WAIT_L(0); MMA(0, 1, At, B1); BAR;
;       LDA(At, 0, 1); WAIT_V(4); BAR; WAIT_L(0); MMA(1, 0, At, B0); MMA(1, 1, At, B1); BAR; }
;     { LDB(B0, 1, 0); LDA(At, 1, 0); WAIT_V(2); BAR; WAIT_L(0); MMA(0, 0, At, B0); BAR;
;       LDB(B1, 1, 1); WAIT_V(0); BAR; WAIT_L(0); MMA(0, 1, At, B1); BAR;
	s_nop 1
	ds_read_b128 v[98:101], v140
	ds_read_b128 v[106:109], v140 offset:1024
	ds_read_b128 v[114:117], v140 offset:2048
	ds_read_b128 v[122:125], v140 offset:3072
	s_waitcnt vmcnt(8)
	s_barrier
	s_waitcnt lgkmcnt(0)
	s_setprio 1
	s_waitcnt lgkmcnt(0)
	v_mfma_f32_16x16x32_bf16 v[94:97], v[98:101], v[158:161], v[94:97]
	v_mfma_f32_16x16x32_bf16 v[86:89], v[98:101], v[166:169], v[86:89]
	v_mfma_f32_16x16x32_bf16 v[78:81], v[98:101], v[174:177], v[78:81]
	v_mfma_f32_16x16x32_bf16 v[70:73], v[98:101], v[188:191], v[70:73]
	v_mfma_f32_16x16x32_bf16 v[94:97], v[106:109], v[162:165], v[94:97]
	v_mfma_f32_16x16x32_bf16 v[90:93], v[114:117], v[158:161], v[90:93]
	v_mfma_f32_16x16x32_bf16 v[86:89], v[106:109], v[170:173], v[86:89]
	v_mfma_f32_16x16x32_bf16 v[82:85], v[114:117], v[166:169], v[82:85]
	v_mfma_f32_16x16x32_bf16 v[78:81], v[106:109], v[184:187], v[78:81]
	v_mfma_f32_16x16x32_bf16 v[74:77], v[114:117], v[174:177], v[74:77]
	v_mfma_f32_16x16x32_bf16 v[70:73], v[106:109], v[204:207], v[70:73]
	v_mfma_f32_16x16x32_bf16 v[66:69], v[114:117], v[188:191], v[66:69]
	v_mfma_f32_16x16x32_bf16 v[140:143], v[122:125], v[162:165], v[90:93]
	v_mfma_f32_16x16x32_bf16 v[158:161], v[122:125], v[170:173], v[82:85]
	v_mfma_f32_16x16x32_bf16 v[162:165], v[122:125], v[184:187], v[74:77]
	v_mfma_f32_16x16x32_bf16 v[166:169], v[122:125], v[204:207], v[66:69]
	s_setprio 0
	s_barrier
	s_nop 1
	ds_read_b128 v[66:69], v137 offset:16384
	ds_read_b128 v[74:77], v137 offset:17408
	ds_read_b128 v[82:85], v136 offset:16384
	ds_read_b128 v[90:93], v136 offset:17408
	ds_read_b128 v[170:173], v135 offset:16384
	ds_read_b128 v[174:177], v135 offset:17408
	ds_read_b128 v[184:187], v134 offset:16384
	ds_read_b128 v[188:191], v134 offset:17408
	s_waitcnt vmcnt(4)
	s_barrier
	s_waitcnt lgkmcnt(0)
	s_setprio 1
	s_waitcnt lgkmcnt(0)
	v_mfma_f32_16x16x32_bf16 v[62:65], v[130:133], v[66:69], v[62:65]
	v_mfma_f32_16x16x32_bf16 v[54:57], v[130:133], v[82:85], v[54:57]
	v_mfma_f32_16x16x32_bf16 v[46:49], v[130:133], v[170:173], v[46:49]
	v_mfma_f32_16x16x32_bf16 v[38:41], v[130:133], v[184:187], v[38:41]
	v_mfma_f32_16x16x32_bf16 v[62:65], v[146:149], v[74:77], v[62:65]
	v_mfma_f32_16x16x32_bf16 v[58:61], v[150:153], v[66:69], v[58:61]
	v_mfma_f32_16x16x32_bf16 v[54:57], v[146:149], v[90:93], v[54:57]
	v_mfma_f32_16x16x32_bf16 v[50:53], v[150:153], v[82:85], v[50:53]
	v_mfma_f32_16x16x32_bf16 v[46:49], v[146:149], v[174:177], v[46:49]
	v_mfma_f32_16x16x32_bf16 v[42:45], v[150:153], v[170:173], v[42:45]
	v_mfma_f32_16x16x32_bf16 v[38:41], v[146:149], v[188:191], v[38:41]
	v_mfma_f32_16x16x32_bf16 v[34:37], v[150:153], v[184:187], v[34:37]
	v_mfma_f32_16x16x32_bf16 v[204:207], v[154:157], v[74:77], v[58:61]
	v_mfma_f32_16x16x32_bf16 v[224:227], v[154:157], v[90:93], v[50:53]
	v_mfma_f32_16x16x32_bf16 v[228:231], v[154:157], v[174:177], v[42:45]
	v_mfma_f32_16x16x32_bf16 v[130:133], v[154:157], v[188:191], v[34:37]
	s_setprio 0
	s_setprio 1
	v_mfma_f32_16x16x32_bf16 v[30:33], v[98:101], v[66:69], v[30:33]
	v_mfma_f32_16x16x32_bf16 v[22:25], v[98:101], v[82:85], v[22:25]
	v_mfma_f32_16x16x32_bf16 v[14:17], v[98:101], v[170:173], v[14:17]
	v_mfma_f32_16x16x32_bf16 v[6:9], v[98:101], v[184:187], v[6:9]
	v_mfma_f32_16x16x32_bf16 v[30:33], v[106:109], v[74:77], v[30:33]
	v_mfma_f32_16x16x32_bf16 v[26:29], v[114:117], v[66:69], v[26:29]
	v_mfma_f32_16x16x32_bf16 v[22:25], v[106:109], v[90:93], v[22:25]
	v_mfma_f32_16x16x32_bf16 v[18:21], v[114:117], v[82:85], v[18:21]
	v_mfma_f32_16x16x32_bf16 v[14:17], v[106:109], v[174:177], v[14:17]
	v_mfma_f32_16x16x32_bf16 v[10:13], v[114:117], v[170:173], v[10:13]
	v_mfma_f32_16x16x32_bf16 v[6:9], v[106:109], v[188:191], v[6:9]
	v_mfma_f32_16x16x32_bf16 v[2:5], v[114:117], v[184:187], v[2:5]
	v_mfma_f32_16x16x32_bf16 v[146:149], v[122:125], v[74:77], v[26:29]
	v_mfma_f32_16x16x32_bf16 v[150:153], v[122:125], v[90:93], v[18:21]
	v_mfma_f32_16x16x32_bf16 v[154:157], v[122:125], v[174:177], v[10:13]
	v_mfma_f32_16x16x32_bf16 v[170:173], v[122:125], v[188:191], v[2:5]
	s_setprio 0
	s_barrier
	s_nop 1
	ds_read_b128 v[2:5], v139
	ds_read_b128 v[10:13], v139 offset:1024
	ds_read_b128 v[174:177], v139 offset:2048
	ds_read_b128 v[184:187], v139 offset:3072
	ds_read_b128 v[18:21], v137 offset:32768
	ds_read_b128 v[26:29], v137 offset:33792
	ds_read_b128 v[34:37], v136 offset:32768
	ds_read_b128 v[42:45], v136 offset:33792
	ds_read_b128 v[50:53], v135 offset:32768
	ds_read_b128 v[58:61], v135 offset:33792
	ds_read_b128 v[188:191], v134 offset:32768
	ds_read_b128 v[232:235], v134 offset:33792
	s_waitcnt vmcnt(2)
	s_barrier
; #define LDA(dst, b, h) _Pragma("unroll") for (int m = 0; m < 4; ++m) _Pragma("unroll") for (int k = 0; k < 2; ++k) \
;     dst[m][k] = *reinterpret_cast<const LAS bf16x8*>(lds + SAo(b, h) + lds_byte(wr * 64 + m * 16 + fr, k * 32 + fq * 8))
; #define LDB(dst, b, h) _Pragma("unroll") for (int n = 0; n < 2; ++n) _Pragma("unroll") for (int k = 0; k < 2; ++k) \
;     dst[n][k] = *reinterpret_cast<const LAS bf16x8*>(lds + SBo(b, h) + lds_byte(wc * 32 + n * 16 + fr, k * 32 + fq * 8))
; #define MMA(ai, bj, At_, Bt_) do { __builtin_amdgcn_s_setprio(1); \
;     _Pragma("unroll") for (int m = 0; m < 4; ++m) _Pragma("unroll") for (int n = 0; n < 2; ++n) _Pragma("unroll") for (int k = 0; k < 2; ++k) \
;       acc[ai][bj][m][n] = __builtin_amdgcn_mfma_f32_16x16x32_bf16(Bt_[n][k], At_[m][k], acc[ai][bj][m][n], 0, 0, 0); \
;     __builtin_amdgcn_s_setprio(0); } while (0)
; #define WAIT_V(n) asm volatile("s_waitcnt vmcnt(" #n ")" ::: "memory")
; #define WAIT_L(n) asm volatile("s_waitcnt lgkmcnt(" #n ")" ::: "memory")
; #define BAR __builtin_amdgcn_s_barrier()
; template <bool PRE = false>
; __device__ __forceinline__ void gemm_kloop(Acc& acc, const bf16_t* __restrict__ A, int lda, const bf16_t* __restrict__ Bt, int ldb,
;                                            int brow, int bcol, int nt, LAS unsigned char* lds) {
;     ...
;       LDA(At, 0, 1); WAIT_V(4); BAR; WAIT_L(0); MMA(1, 0, At, B0); MMA(1, 1, At, B1); BAR; }
;     { LDB(B0, 1, 0); LDA(At, 1, 0); WAIT_V(2); BAR; WAIT_L(0); MMA(0, 0, At, B0); BAR;
;       LDB(B1, 1, 1); WAIT_V(0); BAR; WAIT_L(0); MMA(0, 1, At, B1); BAR;
;       LDA(At, 1, 1); BAR; WAIT_L(0); MMA(1, 0, At, B0); MMA(1, 1, At, B1); BAR; }
;     if (wr == 0) BAR;
	s_waitcnt lgkmcnt(0)
	s_setprio 1
	s_waitcnt lgkmcnt(0)
	v_mfma_f32_16x16x32_bf16 v[66:69], v[2:5], v[18:21], v[126:129]
	v_mfma_f32_16x16x32_bf16 v[122:125], v[10:13], v[26:29], v[66:69]
	v_mfma_f32_16x16x32_bf16 v[66:69], v[174:177], v[18:21], v[208:211]
	v_mfma_f32_16x16x32_bf16 v[114:117], v[184:187], v[26:29], v[66:69]
	v_mfma_f32_16x16x32_bf16 v[66:69], v[2:5], v[34:37], v[118:121]
	v_mfma_f32_16x16x32_bf16 v[106:109], v[10:13], v[42:45], v[66:69]
	v_mfma_f32_16x16x32_bf16 v[66:69], v[174:177], v[34:37], v[212:215]
	v_mfma_f32_16x16x32_bf16 v[98:101], v[184:187], v[42:45], v[66:69]
	v_mfma_f32_16x16x32_bf16 v[66:69], v[2:5], v[50:53], v[110:113]
	v_mfma_f32_16x16x32_bf16 v[90:93], v[10:13], v[58:61], v[66:69]
	v_mfma_f32_16x16x32_bf16 v[66:69], v[174:177], v[50:53], v[216:219]
	v_mfma_f32_16x16x32_bf16 v[82:85], v[184:187], v[58:61], v[66:69]
	v_mfma_f32_16x16x32_bf16 v[66:69], v[2:5], v[188:191], v[102:105]
	v_mfma_f32_16x16x32_bf16 v[74:77], v[10:13], v[232:235], v[66:69]
	v_mfma_f32_16x16x32_bf16 v[66:69], v[174:177], v[188:191], v[220:223]
	v_mfma_f32_16x16x32_bf16 v[66:69], v[184:187], v[232:235], v[66:69]
	s_setprio 0
	s_barrier
	ds_read_b128 v[208:211], v138
	ds_read_b128 v[212:215], v138 offset:1024
	ds_read_b128 v[216:219], v138 offset:2048
	ds_read_b128 v[220:223], v138 offset:3072
	s_waitcnt vmcnt(0)
	s_barrier
	s_waitcnt lgkmcnt(0)
	s_setprio 1
	s_waitcnt lgkmcnt(0)
	v_mfma_f32_16x16x32_bf16 v[94:97], v[208:211], v[18:21], v[94:97]
	v_mfma_f32_16x16x32_bf16 v[18:21], v[216:219], v[18:21], v[140:143]
	v_mfma_f32_16x16x32_bf16 v[118:121], v[220:223], v[26:29], v[18:21]
	v_mfma_f32_16x16x32_bf16 v[18:21], v[208:211], v[34:37], v[86:89]
	v_mfma_f32_16x16x32_bf16 v[110:113], v[212:215], v[42:45], v[18:21]
	v_mfma_f32_16x16x32_bf16 v[18:21], v[216:219], v[34:37], v[158:161]
	v_mfma_f32_16x16x32_bf16 v[102:105], v[220:223], v[42:45], v[18:21]
	v_mfma_f32_16x16x32_bf16 v[18:21], v[208:211], v[50:53], v[78:81]
	v_mfma_f32_16x16x32_bf16 v[126:129], v[212:215], v[26:29], v[94:97]
	v_mfma_f32_16x16x32_bf16 v[94:97], v[212:215], v[58:61], v[18:21]
	v_mfma_f32_16x16x32_bf16 v[18:21], v[216:219], v[50:53], v[162:165]
	v_mfma_f32_16x16x32_bf16 v[86:89], v[220:223], v[58:61], v[18:21]
	v_mfma_f32_16x16x32_bf16 v[18:21], v[208:211], v[188:191], v[70:73]
	v_mfma_f32_16x16x32_bf16 v[78:81], v[212:215], v[232:235], v[18:21]
	v_mfma_f32_16x16x32_bf16 v[18:21], v[216:219], v[188:191], v[166:169]
	v_mfma_f32_16x16x32_bf16 v[70:73], v[220:223], v[232:235], v[18:21]
	s_setprio 0
	s_barrier
	ds_read_b128 v[138:141], v137 offset:49152
	ds_read_b128 v[158:161], v137 offset:50176
	ds_read_b128 v[162:165], v136 offset:49152
	ds_read_b128 v[166:169], v136 offset:50176
	ds_read_b128 v[188:191], v135 offset:49152
	ds_read_b128 v[232:235], v135 offset:50176
	ds_read_b128 v[236:239], v134 offset:49152
	ds_read_b128 v[134:137], v134 offset:50176
	s_barrier
	s_waitcnt lgkmcnt(0)
	s_setprio 1
	s_waitcnt lgkmcnt(0)
	v_mfma_f32_16x16x32_bf16 v[18:21], v[2:5], v[138:141], v[62:65]
	v_mfma_f32_16x16x32_bf16 v[58:61], v[10:13], v[158:161], v[18:21]
	v_mfma_f32_16x16x32_bf16 v[18:21], v[174:177], v[138:141], v[204:207]
	v_mfma_f32_16x16x32_bf16 v[50:53], v[184:187], v[158:161], v[18:21]
	v_mfma_f32_16x16x32_bf16 v[18:21], v[2:5], v[162:165], v[54:57]
	v_mfma_f32_16x16x32_bf16 v[42:45], v[10:13], v[166:169], v[18:21]
	v_mfma_f32_16x16x32_bf16 v[18:21], v[174:177], v[162:165], v[224:227]
	v_mfma_f32_16x16x32_bf16 v[34:37], v[184:187], v[166:169], v[18:21]
	v_mfma_f32_16x16x32_bf16 v[18:21], v[2:5], v[188:191], v[46:49]
	v_mfma_f32_16x16x32_bf16 v[2:5], v[2:5], v[236:239], v[38:41]
	v_mfma_f32_16x16x32_bf16 v[26:29], v[10:13], v[232:235], v[18:21]
	v_mfma_f32_16x16x32_bf16 v[18:21], v[174:177], v[188:191], v[228:231]
	v_mfma_f32_16x16x32_bf16 v[10:13], v[10:13], v[134:137], v[2:5]
	v_mfma_f32_16x16x32_bf16 v[2:5], v[174:177], v[236:239], v[130:133]
	v_mfma_f32_16x16x32_bf16 v[18:21], v[184:187], v[232:235], v[18:21]
	v_mfma_f32_16x16x32_bf16 v[2:5], v[184:187], v[134:137], v[2:5]
	s_setprio 0
	s_setprio 1
	v_mfma_f32_16x16x32_bf16 v[30:33], v[208:211], v[138:141], v[30:33]
	v_mfma_f32_16x16x32_bf16 v[62:65], v[212:215], v[158:161], v[30:33]
	v_mfma_f32_16x16x32_bf16 v[30:33], v[216:219], v[138:141], v[146:149]
	v_mfma_f32_16x16x32_bf16 v[22:25], v[208:211], v[162:165], v[22:25]
	v_mfma_f32_16x16x32_bf16 v[14:17], v[208:211], v[188:191], v[14:17]
	v_mfma_f32_16x16x32_bf16 v[54:57], v[220:223], v[158:161], v[30:33]
	v_mfma_f32_16x16x32_bf16 v[46:49], v[212:215], v[166:169], v[22:25]
	v_mfma_f32_16x16x32_bf16 v[22:25], v[216:219], v[162:165], v[150:153]
	v_mfma_f32_16x16x32_bf16 v[30:33], v[212:215], v[232:235], v[14:17]
	v_mfma_f32_16x16x32_bf16 v[14:17], v[216:219], v[188:191], v[154:157]
	v_mfma_f32_16x16x32_bf16 v[6:9], v[208:211], v[236:239], v[6:9]
	v_mfma_f32_16x16x32_bf16 v[38:41], v[220:223], v[166:169], v[22:25]
	v_mfma_f32_16x16x32_bf16 v[22:25], v[220:223], v[232:235], v[14:17]
	v_mfma_f32_16x16x32_bf16 v[14:17], v[212:215], v[134:137], v[6:9]
	v_mfma_f32_16x16x32_bf16 v[6:9], v[216:219], v[236:239], v[170:173]
	v_mfma_f32_16x16x32_bf16 v[6:9], v[220:223], v[134:137], v[6:9]
	s_setprio 0
	v_cmp_gt_u32_e32 vcc, s85, v1
	s_barrier
	s_and_saveexec_b64 s[12:13], vcc
	s_cbranch_execz .LBB0_133
	s_barrier

; #define LDA(dst, b, h) _Pragma("unroll") for (int m = 0; m < 4; ++m) _Pragma("unroll") for (int k = 0; k < 2; ++k) \
;     dst[m][k] = *reinterpret_cast<const LAS bf16x8*>(lds + SAo(b, h) + lds_byte(wr * 64 + m * 16 + fr, k * 32 + fq * 8))
; #define LDB(dst, b, h) _Pragma("unroll") for (int n = 0; n < 2; ++n) _Pragma("unroll") for (int k = 0; k < 2; ++k) \
;     dst[n][k] = *reinterpret_cast<const LAS bf16x8*>(lds + SBo(b, h) + lds_byte(wc * 32 + n * 16 + fr, k * 32 + fq * 8))
; #define MMA(ai, bj, At_, Bt_) do { __builtin_amdgcn_s_setprio(1); \
;     _Pragma("unroll") for (int m = 0; m < 4; ++m) _Pragma("unroll") for (int n = 0; n < 2; ++n) _Pragma("unroll") for (int k = 0; k < 2; ++k) \
;       acc[ai][bj][m][n] = __builtin_amdgcn_mfma_f32_16x16x32_bf16(Bt_[n][k], At_[m][k], acc[ai][bj][m][n], 0, 0, 0); \
;     __builtin_amdgcn_s_setprio(0); } while (0)
; #define WAIT_L(n) asm volatile("s_waitcnt lgkmcnt(" #n ")" ::: "memory")
; #define BAR __builtin_amdgcn_s_barrier()
; #define SCHED __builtin_amdgcn_sched_barrier(0)
; template <bool PRE = false>
; __device__ __forceinline__ void gemm_kloop(Acc& acc, const bf16_t* __restrict__ A, int lda, const bf16_t* __restrict__ Bt, int ldb,
;                                            int brow, int bcol, int nt, LAS unsigned char* lds) {
;     ...
;     for (int t = 0; t < nt - 2; t += 2) {
;         LDB(B0, 0, 0); SCHED; LDA(At, 0, 0); STAGE(SAo(1, 1), A, lda, brow + HALF, t + 1, offA);
;         WAIT_L(8); BAR; WAIT_L(0); MMA(0, 0, At, B0); BAR; SCHED;
;         LDB(B1, 0, 1); STAGE(SBo(0, 0), Bt, ldb, bcol, t + 2, offB);
;         BAR; WAIT_L(0); MMA(0, 1, At, B1); BAR;
;         LDA(At, 0, 1); STAGE(SAo(0, 0), A, lda, brow, t + 2, offA);
;         BAR; WAIT_L(0); MMA(1, 0, At, B0); BAR; SCHED;
.LBB0_543:
	ds_read_b128 v[146:149], v141
	ds_read_b128 v[150:153], v141 offset:1024
	ds_read_b128 v[154:157], v141 offset:2048
	ds_read_b128 v[158:161], v141 offset:3072
	s_add_i32 s52, s1, 3
	s_mov_b32 s8, s26
	ds_read_b128 v[162:165], v137
	ds_read_b128 v[166:169], v137 offset:1024
	ds_read_b128 v[170:173], v136
	ds_read_b128 v[174:177], v136 offset:1024
	ds_read_b128 v[184:187], v135
	ds_read_b128 v[188:191], v135 offset:1024
	ds_read_b128 v[204:207], v134
	ds_read_b128 v[208:211], v134 offset:1024
	s_ashr_i32 s53, s52, 31
	s_lshl_b64 s[52:53], s[52:53], 7
	s_lshl_b32 s8, s8, 10
	v_lshl_add_u64 v[142:143], v[130:131], 0, s[52:53]
	s_add_i32 s8, s8, 0
	s_add_i32 m0, s8, 0xc000
	v_lshl_add_u64 v[192:193], v[142:143], 0, s[48:49]
	global_load_lds_dwordx4 v[192:193], off
	v_lshl_add_u64 v[142:143], v[142:143], 0, s[50:51]
	s_add_i32 m0, s8, 0xe000
	s_nop 0
	global_load_lds_dwordx4 v[142:143], off
	s_waitcnt lgkmcnt(8)
	s_waitcnt vmcnt(10)
	s_barrier
	s_waitcnt lgkmcnt(0)
	s_setprio 1
	s_waitcnt lgkmcnt(0)
	v_mfma_f32_16x16x32_bf16 v[126:129], v[146:149], v[162:165], v[126:129]
	v_mfma_f32_16x16x32_bf16 v[122:125], v[154:157], v[162:165], v[122:125]
	v_mfma_f32_16x16x32_bf16 v[118:121], v[146:149], v[170:173], v[118:121]
	v_mfma_f32_16x16x32_bf16 v[114:117], v[154:157], v[170:173], v[114:117]
	v_mfma_f32_16x16x32_bf16 v[110:113], v[146:149], v[184:187], v[110:113]
	v_mfma_f32_16x16x32_bf16 v[106:109], v[154:157], v[184:187], v[106:109]
	v_mfma_f32_16x16x32_bf16 v[102:105], v[146:149], v[204:207], v[102:105]
	v_mfma_f32_16x16x32_bf16 v[98:101], v[154:157], v[204:207], v[98:101]
	v_mfma_f32_16x16x32_bf16 v[126:129], v[150:153], v[166:169], v[126:129]
	v_mfma_f32_16x16x32_bf16 v[122:125], v[158:161], v[166:169], v[122:125]
	v_mfma_f32_16x16x32_bf16 v[118:121], v[150:153], v[174:177], v[118:121]
	v_mfma_f32_16x16x32_bf16 v[114:117], v[158:161], v[174:177], v[114:117]
	v_mfma_f32_16x16x32_bf16 v[110:113], v[150:153], v[188:191], v[110:113]
	v_mfma_f32_16x16x32_bf16 v[106:109], v[158:161], v[188:191], v[106:109]
	v_mfma_f32_16x16x32_bf16 v[102:105], v[150:153], v[208:211], v[102:105]
	v_mfma_f32_16x16x32_bf16 v[98:101], v[158:161], v[208:211], v[98:101]
	s_setprio 0
	s_barrier
	s_add_i32 s52, s1, 4
	s_mov_b32 s54, s52
	s_mov_b32 s8, s26
	ds_read_b128 v[212:215], v140
	ds_read_b128 v[216:219], v140 offset:1024
	ds_read_b128 v[220:223], v140 offset:2048
	ds_read_b128 v[224:227], v140 offset:3072
	s_ashr_i32 s55, s54, 31
	s_lshl_b64 s[54:55], s[54:55], 7
	s_lshl_b32 s8, s8, 10
	v_lshl_add_u64 v[142:143], v[132:133], 0, s[54:55]
	s_add_i32 s8, s8, 0
	s_add_i32 m0, s8, 0x10000
	v_lshl_add_u64 v[192:193], v[142:143], 0, s[36:37]
	global_load_lds_dwordx4 v[192:193], off
	v_lshl_add_u64 v[142:143], v[142:143], 0, s[38:39]
	s_add_i32 m0, s8, 0x12000
	s_nop 0
	global_load_lds_dwordx4 v[142:143], off
	s_waitcnt vmcnt(10)
	s_barrier
	s_waitcnt lgkmcnt(0)
	s_setprio 1
	s_waitcnt lgkmcnt(0)
	v_mfma_f32_16x16x32_bf16 v[94:97], v[212:215], v[162:165], v[94:97]
	v_mfma_f32_16x16x32_bf16 v[90:93], v[220:223], v[162:165], v[90:93]
	v_mfma_f32_16x16x32_bf16 v[86:89], v[212:215], v[170:173], v[86:89]
	v_mfma_f32_16x16x32_bf16 v[82:85], v[220:223], v[170:173], v[82:85]
	v_mfma_f32_16x16x32_bf16 v[78:81], v[212:215], v[184:187], v[78:81]
	v_mfma_f32_16x16x32_bf16 v[74:77], v[220:223], v[184:187], v[74:77]
	v_mfma_f32_16x16x32_bf16 v[70:73], v[212:215], v[204:207], v[70:73]
	v_mfma_f32_16x16x32_bf16 v[66:69], v[220:223], v[204:207], v[66:69]
	v_mfma_f32_16x16x32_bf16 v[94:97], v[216:219], v[166:169], v[94:97]
	v_mfma_f32_16x16x32_bf16 v[90:93], v[224:227], v[166:169], v[90:93]
	v_mfma_f32_16x16x32_bf16 v[86:89], v[216:219], v[174:177], v[86:89]
	v_mfma_f32_16x16x32_bf16 v[82:85], v[224:227], v[174:177], v[82:85]
	v_mfma_f32_16x16x32_bf16 v[78:81], v[216:219], v[188:191], v[78:81]
	v_mfma_f32_16x16x32_bf16 v[74:77], v[224:227], v[188:191], v[74:77]
	v_mfma_f32_16x16x32_bf16 v[70:73], v[216:219], v[208:211], v[70:73]
	v_mfma_f32_16x16x32_bf16 v[66:69], v[224:227], v[208:211], v[66:69]
	s_setprio 0
	s_mov_b32 s54, s52
	s_mov_b32 s8, s26
	s_barrier
	ds_read_b128 v[162:165], v137 offset:16384
	ds_read_b128 v[166:169], v137 offset:17408
	ds_read_b128 v[170:173], v136 offset:16384
	ds_read_b128 v[174:177], v136 offset:17408
	ds_read_b128 v[184:187], v135 offset:16384
	ds_read_b128 v[188:191], v135 offset:17408
	ds_read_b128 v[204:207], v134 offset:16384
	ds_read_b128 v[208:211], v134 offset:17408
	s_ashr_i32 s55, s54, 31
	s_lshl_b64 s[54:55], s[54:55], 7
	s_lshl_b32 s8, s8, 10
	v_lshl_add_u64 v[142:143], v[130:131], 0, s[54:55]
	s_add_i32 s8, s8, 0
	v_lshl_add_u64 v[192:193], v[142:143], 0, s[40:41]
	s_mov_b32 m0, s8
	v_lshl_add_u64 v[142:143], v[142:143], 0, s[42:43]
	global_load_lds_dwordx4 v[192:193], off
	s_add_i32 m0, s8, 0x2000
	s_nop 0
	global_load_lds_dwordx4 v[142:143], off
	s_barrier
	s_waitcnt lgkmcnt(0)
	s_setprio 1
	s_waitcnt lgkmcnt(0)
	v_mfma_f32_16x16x32_bf16 v[62:65], v[146:149], v[162:165], v[62:65]
	v_mfma_f32_16x16x32_bf16 v[58:61], v[154:157], v[162:165], v[58:61]
	v_mfma_f32_16x16x32_bf16 v[54:57], v[146:149], v[170:173], v[54:57]
	v_mfma_f32_16x16x32_bf16 v[50:53], v[154:157], v[170:173], v[50:53]
	v_mfma_f32_16x16x32_bf16 v[46:49], v[146:149], v[184:187], v[46:49]
	v_mfma_f32_16x16x32_bf16 v[42:45], v[154:157], v[184:187], v[42:45]
	v_mfma_f32_16x16x32_bf16 v[38:41], v[146:149], v[204:207], v[38:41]
	v_mfma_f32_16x16x32_bf16 v[34:37], v[154:157], v[204:207], v[34:37]
	v_mfma_f32_16x16x32_bf16 v[62:65], v[150:153], v[166:169], v[62:65]
	v_mfma_f32_16x16x32_bf16 v[58:61], v[158:161], v[166:169], v[58:61]
	v_mfma_f32_16x16x32_bf16 v[54:57], v[150:153], v[174:177], v[54:57]
	v_mfma_f32_16x16x32_bf16 v[50:53], v[158:161], v[174:177], v[50:53]
	v_mfma_f32_16x16x32_bf16 v[46:49], v[150:153], v[188:191], v[46:49]
	v_mfma_f32_16x16x32_bf16 v[42:45], v[158:161], v[188:191], v[42:45]
	v_mfma_f32_16x16x32_bf16 v[38:41], v[150:153], v[208:211], v[38:41]
	v_mfma_f32_16x16x32_bf16 v[34:37], v[158:161], v[208:211], v[34:37]
	s_setprio 0
	s_barrier
; #define LDA(dst, b, h) _Pragma("unroll") for (int m = 0; m < 4; ++m) _Pragma("unroll") for (int k = 0; k < 2; ++k) \
;     dst[m][k] = *reinterpret_cast<const LAS bf16x8*>(lds + SAo(b, h) + lds_byte(wr * 64 + m * 16 + fr, k * 32 + fq * 8))
; #define LDB(dst, b, h) _Pragma("unroll") for (int n = 0; n < 2; ++n) _Pragma("unroll") for (int k = 0; k < 2; ++k) \
;     dst[n][k] = *reinterpret_cast<const LAS bf16x8*>(lds + SBo(b, h) + lds_byte(wc * 32 + n * 16 + fr, k * 32 + fq * 8))
; #define MMA(ai, bj, At_, Bt_) do { __builtin_amdgcn_s_setprio(1); \
;     _Pragma("unroll") for (int m = 0; m < 4; ++m) _Pragma("unroll") for (int n = 0; n < 2; ++n) _Pragma("unroll") for (int k = 0; k < 2; ++k) \
;       acc[ai][bj][m][n] = __builtin_amdgcn_mfma_f32_16x16x32_bf16(Bt_[n][k], At_[m][k], acc[ai][bj][m][n], 0, 0, 0); \
;     __builtin_amdgcn_s_setprio(0); } while (0)
; #define WAIT_V(n) asm volatile("s_waitcnt vmcnt(" #n ")" ::: "memory")
; #define WAIT_L(n) asm volatile("s_waitcnt lgkmcnt(" #n ")" ::: "memory")
; #define BAR __builtin_amdgcn_s_barrier()
; #define SCHED __builtin_amdgcn_sched_barrier(0)
; template <bool PRE = false>
; __device__ __forceinline__ void gemm_kloop(Acc& acc, const bf16_t* __restrict__ A, int lda, const bf16_t* __restrict__ Bt, int ldb,
;                                            int brow, int bcol, int nt, LAS unsigned char* lds) {
;     ...
;         STAGE(SBo(0, 1), Bt, ldb, bcol + HALF, t + 2, offB);
;         WAIT_V(6); BAR; MMA(1, 1, At, B1); BAR;
;         LDB(B0, 1, 0); SCHED; LDA(At, 1, 0); STAGE(SAo(0, 1), A, lda, brow + HALF, t + 2, offA);
;         WAIT_L(8); BAR; WAIT_L(0); MMA(0, 0, At, B0); BAR; SCHED;
;         LDB(B1, 1, 1); STAGE(SBo(1, 0), Bt, ldb, bcol, t + 3, offB);
;         BAR; WAIT_L(0); MMA(0, 1, At, B1); BAR;
	s_mov_b32 s54, s52
	s_mov_b32 s8, s26
	s_ashr_i32 s55, s54, 31
	s_lshl_b64 s[54:55], s[54:55], 7
	s_lshl_b32 s8, s8, 10
	v_lshl_add_u64 v[142:143], v[132:133], 0, s[54:55]
	s_add_i32 s8, s8, 0
	s_add_i32 m0, s8, 0x14000
	v_lshl_add_u64 v[146:147], v[142:143], 0, s[44:45]
	global_load_lds_dwordx4 v[146:147], off
	v_lshl_add_u64 v[142:143], v[142:143], 0, s[46:47]
	s_add_i32 m0, s8, 0x16000
	s_nop 0
	global_load_lds_dwordx4 v[142:143], off
	s_waitcnt vmcnt(10)
	s_barrier
	s_setprio 1
	v_mfma_f32_16x16x32_bf16 v[30:33], v[212:215], v[162:165], v[30:33]
	v_mfma_f32_16x16x32_bf16 v[26:29], v[220:223], v[162:165], v[26:29]
	v_mfma_f32_16x16x32_bf16 v[22:25], v[212:215], v[170:173], v[22:25]
	v_mfma_f32_16x16x32_bf16 v[18:21], v[220:223], v[170:173], v[18:21]
	v_mfma_f32_16x16x32_bf16 v[14:17], v[212:215], v[184:187], v[14:17]
	v_mfma_f32_16x16x32_bf16 v[10:13], v[220:223], v[184:187], v[10:13]
	v_mfma_f32_16x16x32_bf16 v[6:9], v[212:215], v[204:207], v[6:9]
	v_mfma_f32_16x16x32_bf16 v[2:5], v[220:223], v[204:207], v[2:5]
	v_mfma_f32_16x16x32_bf16 v[30:33], v[216:219], v[166:169], v[30:33]
	v_mfma_f32_16x16x32_bf16 v[26:29], v[224:227], v[166:169], v[26:29]
	v_mfma_f32_16x16x32_bf16 v[22:25], v[216:219], v[174:177], v[22:25]
	v_mfma_f32_16x16x32_bf16 v[18:21], v[224:227], v[174:177], v[18:21]
	v_mfma_f32_16x16x32_bf16 v[14:17], v[216:219], v[188:191], v[14:17]
	v_mfma_f32_16x16x32_bf16 v[10:13], v[224:227], v[188:191], v[10:13]
	v_mfma_f32_16x16x32_bf16 v[6:9], v[216:219], v[208:211], v[6:9]
	v_mfma_f32_16x16x32_bf16 v[2:5], v[224:227], v[208:211], v[2:5]
	s_setprio 0
	s_barrier
	ds_read_b128 v[146:149], v139
	ds_read_b128 v[150:153], v139 offset:1024
	ds_read_b128 v[154:157], v139 offset:2048
	ds_read_b128 v[158:161], v139 offset:3072
	s_mov_b32 s8, s26
	ds_read_b128 v[162:165], v137 offset:32768
	ds_read_b128 v[166:169], v137 offset:33792
	ds_read_b128 v[170:173], v136 offset:32768
	ds_read_b128 v[174:177], v136 offset:33792
	ds_read_b128 v[184:187], v135 offset:32768
	ds_read_b128 v[188:191], v135 offset:33792
	ds_read_b128 v[204:207], v134 offset:32768
	ds_read_b128 v[208:211], v134 offset:33792
	s_ashr_i32 s53, s52, 31
	s_lshl_b64 s[52:53], s[52:53], 7
	s_lshl_b32 s8, s8, 10
	v_lshl_add_u64 v[142:143], v[130:131], 0, s[52:53]
	s_add_i32 s8, s8, 0
	s_add_i32 m0, s8, 0x4000
	v_lshl_add_u64 v[192:193], v[142:143], 0, s[48:49]
	global_load_lds_dwordx4 v[192:193], off
	v_lshl_add_u64 v[142:143], v[142:143], 0, s[50:51]
	s_add_i32 m0, s8, 0x6000
	s_nop 0
	global_load_lds_dwordx4 v[142:143], off
	s_waitcnt lgkmcnt(8)
	s_waitcnt vmcnt(10)
	s_barrier
	s_waitcnt lgkmcnt(0)
	s_setprio 1
	s_waitcnt lgkmcnt(0)
	v_mfma_f32_16x16x32_bf16 v[126:129], v[146:149], v[162:165], v[126:129]
	v_mfma_f32_16x16x32_bf16 v[122:125], v[154:157], v[162:165], v[122:125]
	v_mfma_f32_16x16x32_bf16 v[118:121], v[146:149], v[170:173], v[118:121]
	v_mfma_f32_16x16x32_bf16 v[114:117], v[154:157], v[170:173], v[114:117]
	v_mfma_f32_16x16x32_bf16 v[110:113], v[146:149], v[184:187], v[110:113]
	v_mfma_f32_16x16x32_bf16 v[106:109], v[154:157], v[184:187], v[106:109]
	v_mfma_f32_16x16x32_bf16 v[102:105], v[146:149], v[204:207], v[102:105]
	v_mfma_f32_16x16x32_bf16 v[98:101], v[154:157], v[204:207], v[98:101]
	v_mfma_f32_16x16x32_bf16 v[126:129], v[150:153], v[166:169], v[126:129]
	v_mfma_f32_16x16x32_bf16 v[122:125], v[158:161], v[166:169], v[122:125]
	v_mfma_f32_16x16x32_bf16 v[118:121], v[150:153], v[174:177], v[118:121]
	v_mfma_f32_16x16x32_bf16 v[114:117], v[158:161], v[174:177], v[114:117]
	v_mfma_f32_16x16x32_bf16 v[110:113], v[150:153], v[188:191], v[110:113]
	v_mfma_f32_16x16x32_bf16 v[106:109], v[158:161], v[188:191], v[106:109]
	v_mfma_f32_16x16x32_bf16 v[102:105], v[150:153], v[208:211], v[102:105]
	v_mfma_f32_16x16x32_bf16 v[98:101], v[158:161], v[208:211], v[98:101]
	s_setprio 0
	s_barrier
	s_add_i32 s52, s1, 5
	s_mov_b32 s54, s52
	s_mov_b32 s8, s26
	ds_read_b128 v[212:215], v138
	ds_read_b128 v[216:219], v138 offset:1024
	ds_read_b128 v[220:223], v138 offset:2048
	ds_read_b128 v[224:227], v138 offset:3072
	s_ashr_i32 s55, s54, 31
	s_lshl_b64 s[54:55], s[54:55], 7
	s_lshl_b32 s8, s8, 10
	v_lshl_add_u64 v[142:143], v[132:133], 0, s[54:55]
	s_add_i32 s8, s8, 0
	s_add_i32 m0, s8, 0x18000
	v_lshl_add_u64 v[192:193], v[142:143], 0, s[36:37]
	global_load_lds_dwordx4 v[192:193], off
	v_lshl_add_u64 v[142:143], v[142:143], 0, s[38:39]
	s_add_i32 m0, s8, 0x1a000
	s_nop 0
	global_load_lds_dwordx4 v[142:143], off
	s_waitcnt vmcnt(10)
	s_barrier
	s_waitcnt lgkmcnt(0)
	s_setprio 1
	s_waitcnt lgkmcnt(0)
	v_mfma_f32_16x16x32_bf16 v[94:97], v[212:215], v[162:165], v[94:97]
	v_mfma_f32_16x16x32_bf16 v[90:93], v[220:223], v[162:165], v[90:93]
	v_mfma_f32_16x16x32_bf16 v[86:89], v[212:215], v[170:173], v[86:89]
	v_mfma_f32_16x16x32_bf16 v[82:85], v[220:223], v[170:173], v[82:85]
	v_mfma_f32_16x16x32_bf16 v[78:81], v[212:215], v[184:187], v[78:81]
	v_mfma_f32_16x16x32_bf16 v[74:77], v[220:223], v[184:187], v[74:77]
	v_mfma_f32_16x16x32_bf16 v[70:73], v[212:215], v[204:207], v[70:73]
	v_mfma_f32_16x16x32_bf16 v[66:69], v[220:223], v[204:207], v[66:69]
	v_mfma_f32_16x16x32_bf16 v[94:97], v[216:219], v[166:169], v[94:97]
	v_mfma_f32_16x16x32_bf16 v[90:93], v[224:227], v[166:169], v[90:93]
	v_mfma_f32_16x16x32_bf16 v[86:89], v[216:219], v[174:177], v[86:89]
	v_mfma_f32_16x16x32_bf16 v[82:85], v[224:227], v[174:177], v[82:85]
	v_mfma_f32_16x16x32_bf16 v[78:81], v[216:219], v[188:191], v[78:81]
	v_mfma_f32_16x16x32_bf16 v[74:77], v[224:227], v[188:191], v[74:77]
	v_mfma_f32_16x16x32_bf16 v[70:73], v[216:219], v[208:211], v[70:73]
	v_mfma_f32_16x16x32_bf16 v[66:69], v[224:227], v[208:211], v[66:69]
	s_setprio 0
	s_mov_b32 s54, s52
	s_mov_b32 s8, s26
	s_barrier
; #define LDA(dst, b, h) _Pragma("unroll") for (int m = 0; m < 4; ++m) _Pragma("unroll") for (int k = 0; k < 2; ++k) \
;     dst[m][k] = *reinterpret_cast<const LAS bf16x8*>(lds + SAo(b, h) + lds_byte(wr * 64 + m * 16 + fr, k * 32 + fq * 8))
; #define LDB(dst, b, h) _Pragma("unroll") for (int n = 0; n < 2; ++n) _Pragma("unroll") for (int k = 0; k < 2; ++k) \
;     dst[n][k] = *reinterpret_cast<const LAS bf16x8*>(lds + SBo(b, h) + lds_byte(wc * 32 + n * 16 + fr, k * 32 + fq * 8))
; #define MMA(ai, bj, At_, Bt_) do { __builtin_amdgcn_s_setprio(1); \
;     _Pragma("unroll") for (int m = 0; m < 4; ++m) _Pragma("unroll") for (int n = 0; n < 2; ++n) _Pragma("unroll") for (int k = 0; k < 2; ++k) \
;       acc[ai][bj][m][n] = __builtin_amdgcn_mfma_f32_16x16x32_bf16(Bt_[n][k], At_[m][k], acc[ai][bj][m][n], 0, 0, 0); \
;     __builtin_amdgcn_s_setprio(0); } while (0)
; #define WAIT_V(n) asm volatile("s_waitcnt vmcnt(" #n ")" ::: "memory")
; #define WAIT_L(n) asm volatile("s_waitcnt lgkmcnt(" #n ")" ::: "memory")
; #define BAR __builtin_amdgcn_s_barrier()
; #define SCHED __builtin_amdgcn_sched_barrier(0)
; template <bool PRE = false>
; __device__ __forceinline__ void gemm_kloop(Acc& acc, const bf16_t* __restrict__ A, int lda, const bf16_t* __restrict__ Bt, int ldb,
;                                            int brow, int bcol, int nt, LAS unsigned char* lds) {
;     ...
;         LDA(At, 1, 1); STAGE(SAo(1, 0), A, lda, brow, t + 3, offA);
;         BAR; WAIT_L(0); MMA(1, 0, At, B0); BAR; SCHED;
;         STAGE(SBo(1, 1), Bt, ldb, bcol + HALF, t + 3, offB);
;         WAIT_V(6); BAR; MMA(1, 1, At, B1); BAR;
;     }
;     { LDB(B0, 0, 0); LDA(At, 0, 0); STAGE(SAo(1, 1), A, lda, brow + HALF, nt - 1, offA);
	ds_read_b128 v[162:165], v137 offset:49152
	ds_read_b128 v[166:169], v137 offset:50176
	ds_read_b128 v[170:173], v136 offset:49152
	ds_read_b128 v[174:177], v136 offset:50176
	ds_read_b128 v[184:187], v135 offset:49152
	ds_read_b128 v[188:191], v135 offset:50176
	ds_read_b128 v[204:207], v134 offset:49152
	ds_read_b128 v[208:211], v134 offset:50176
	s_ashr_i32 s55, s54, 31
	s_lshl_b64 s[54:55], s[54:55], 7
	s_lshl_b32 s8, s8, 10
	v_lshl_add_u64 v[142:143], v[130:131], 0, s[54:55]
	s_add_i32 s8, s8, 0
	s_add_i32 m0, s8, 0x8000
	v_lshl_add_u64 v[192:193], v[142:143], 0, s[40:41]
	global_load_lds_dwordx4 v[192:193], off
	v_lshl_add_u64 v[142:143], v[142:143], 0, s[42:43]
	s_add_i32 m0, s8, 0xa000
	s_nop 0
	global_load_lds_dwordx4 v[142:143], off
	s_barrier
	s_waitcnt lgkmcnt(0)
	s_setprio 1
	s_waitcnt lgkmcnt(0)
	v_mfma_f32_16x16x32_bf16 v[62:65], v[146:149], v[162:165], v[62:65]
	v_mfma_f32_16x16x32_bf16 v[58:61], v[154:157], v[162:165], v[58:61]
	v_mfma_f32_16x16x32_bf16 v[54:57], v[146:149], v[170:173], v[54:57]
	v_mfma_f32_16x16x32_bf16 v[50:53], v[154:157], v[170:173], v[50:53]
	v_mfma_f32_16x16x32_bf16 v[46:49], v[146:149], v[184:187], v[46:49]
	v_mfma_f32_16x16x32_bf16 v[42:45], v[154:157], v[184:187], v[42:45]
	v_mfma_f32_16x16x32_bf16 v[38:41], v[146:149], v[204:207], v[38:41]
	v_mfma_f32_16x16x32_bf16 v[34:37], v[154:157], v[204:207], v[34:37]
	v_mfma_f32_16x16x32_bf16 v[62:65], v[150:153], v[166:169], v[62:65]
	v_mfma_f32_16x16x32_bf16 v[58:61], v[158:161], v[166:169], v[58:61]
	v_mfma_f32_16x16x32_bf16 v[54:57], v[150:153], v[174:177], v[54:57]
	v_mfma_f32_16x16x32_bf16 v[50:53], v[158:161], v[174:177], v[50:53]
	v_mfma_f32_16x16x32_bf16 v[46:49], v[150:153], v[188:191], v[46:49]
	v_mfma_f32_16x16x32_bf16 v[42:45], v[158:161], v[188:191], v[42:45]
	v_mfma_f32_16x16x32_bf16 v[38:41], v[150:153], v[208:211], v[38:41]
	v_mfma_f32_16x16x32_bf16 v[34:37], v[158:161], v[208:211], v[34:37]
	s_setprio 0
	s_barrier
	s_mov_b32 s8, s26
	s_ashr_i32 s53, s52, 31
	s_lshl_b64 s[52:53], s[52:53], 7
	s_lshl_b32 s8, s8, 10
	v_lshl_add_u64 v[142:143], v[132:133], 0, s[52:53]
	s_add_i32 s8, s8, 0
	s_add_i32 m0, s8, 0x1c000
	v_lshl_add_u64 v[146:147], v[142:143], 0, s[44:45]
	global_load_lds_dwordx4 v[146:147], off
	v_lshl_add_u64 v[142:143], v[142:143], 0, s[46:47]
	s_add_i32 m0, s8, 0x1e000
	s_nop 0
	global_load_lds_dwordx4 v[142:143], off
	s_waitcnt vmcnt(10)
	s_barrier
	s_setprio 1
	v_mfma_f32_16x16x32_bf16 v[30:33], v[212:215], v[162:165], v[30:33]
	v_mfma_f32_16x16x32_bf16 v[26:29], v[220:223], v[162:165], v[26:29]
	v_mfma_f32_16x16x32_bf16 v[22:25], v[212:215], v[170:173], v[22:25]
	v_mfma_f32_16x16x32_bf16 v[18:21], v[220:223], v[170:173], v[18:21]
	v_mfma_f32_16x16x32_bf16 v[14:17], v[212:215], v[184:187], v[14:17]
	v_mfma_f32_16x16x32_bf16 v[10:13], v[220:223], v[184:187], v[10:13]
	v_mfma_f32_16x16x32_bf16 v[6:9], v[212:215], v[204:207], v[6:9]
	v_mfma_f32_16x16x32_bf16 v[2:5], v[220:223], v[204:207], v[2:5]
	v_mfma_f32_16x16x32_bf16 v[30:33], v[216:219], v[166:169], v[30:33]
	v_mfma_f32_16x16x32_bf16 v[26:29], v[224:227], v[166:169], v[26:29]
	v_mfma_f32_16x16x32_bf16 v[22:25], v[216:219], v[174:177], v[22:25]
	v_mfma_f32_16x16x32_bf16 v[18:21], v[224:227], v[174:177], v[18:21]
	v_mfma_f32_16x16x32_bf16 v[14:17], v[216:219], v[188:191], v[14:17]
	v_mfma_f32_16x16x32_bf16 v[10:13], v[224:227], v[188:191], v[10:13]
	v_mfma_f32_16x16x32_bf16 v[6:9], v[216:219], v[208:211], v[6:9]
	v_mfma_f32_16x16x32_bf16 v[2:5], v[224:227], v[208:211], v[2:5]
	s_setprio 0
	s_add_i32 s1, s1, 2
	s_cmp_lt_u32 s1, 12
	s_barrier
	s_cbranch_scc1 .LBB0_543
	s_mov_b32 s36, 15
	ds_read_b128 v[130:133], v141
	ds_read_b128 v[146:149], v141 offset:1024
	ds_read_b128 v[150:153], v141 offset:2048
	ds_read_b128 v[154:157], v141 offset:3072
	ds_read_b128 v[158:161], v137
	ds_read_b128 v[162:165], v137 offset:1024
	ds_read_b128 v[166:169], v136
	ds_read_b128 v[170:173], v136 offset:1024
	ds_read_b128 v[174:177], v135
	ds_read_b128 v[184:187], v135 offset:1024
	ds_read_b128 v[188:191], v134
	ds_read_b128 v[204:207], v134 offset:1024
	s_ashr_i32 s37, s36, 31
	s_lshl_b64 s[36:37], s[36:37], 7
	v_readlane_b32 s6, v254, 54
	v_readlane_b32 s7, v254, 55
	s_add_u32 s36, s6, s36
	s_addc_u32 s37, s7, s37
	s_lshl_b32 s1, s26, 10
	v_lshl_add_u64 v[142:143], s[36:37], 0, v[144:145]
	s_add_i32 s1, s1, 0
	s_add_i32 m0, s1, 0xc000
	v_lshl_add_u64 v[192:193], v[142:143], 0, s[48:49]
	global_load_lds_dwordx4 v[192:193], off
	v_lshl_add_u64 v[142:143], v[142:143], 0, s[50:51]
	s_add_i32 m0, s1, 0xe000
	s_nop 0
	global_load_lds_dwordx4 v[142:143], off
	s_waitcnt vmcnt(10)
	s_barrier
	s_waitcnt lgkmcnt(0)
	s_setprio 1
	s_waitcnt lgkmcnt(0)
	v_mfma_f32_16x16x32_bf16 v[126:129], v[130:133], v[158:161], v[126:129]
	v_mfma_f32_16x16x32_bf16 v[122:125], v[150:153], v[158:161], v[122:125]
	v_mfma_f32_16x16x32_bf16 v[110:113], v[130:133], v[174:177], v[110:113]
	v_mfma_f32_16x16x32_bf16 v[106:109], v[150:153], v[174:177], v[106:109]
	v_mfma_f32_16x16x32_bf16 v[126:129], v[146:149], v[162:165], v[126:129]
	v_mfma_f32_16x16x32_bf16 v[122:125], v[154:157], v[162:165], v[122:125]
	v_mfma_f32_16x16x32_bf16 v[118:121], v[130:133], v[166:169], v[118:121]
	v_mfma_f32_16x16x32_bf16 v[114:117], v[150:153], v[166:169], v[114:117]
	v_mfma_f32_16x16x32_bf16 v[110:113], v[146:149], v[184:187], v[110:113]
	v_mfma_f32_16x16x32_bf16 v[106:109], v[154:157], v[184:187], v[106:109]
	v_mfma_f32_16x16x32_bf16 v[102:105], v[130:133], v[188:191], v[102:105]
	v_mfma_f32_16x16x32_bf16 v[98:101], v[150:153], v[188:191], v[98:101]
	v_mfma_f32_16x16x32_bf16 v[208:211], v[146:149], v[170:173], v[118:121]
	v_mfma_f32_16x16x32_bf16 v[212:215], v[154:157], v[170:173], v[114:117]
	v_mfma_f32_16x16x32_bf16 v[216:219], v[146:149], v[204:207], v[102:105]
	v_mfma_f32_16x16x32_bf16 v[220:223], v[154:157], v[204:207], v[98:101]
	s_setprio 0
	s_barrier
; #define LDA(dst, b, h) _Pragma("unroll") for (int m = 0; m < 4; ++m) _Pragma("unroll") for (int k = 0; k < 2; ++k) \
;     dst[m][k] = *reinterpret_cast<const LAS bf16x8*>(lds + SAo(b, h) + lds_byte(wr * 64 + m * 16 + fr, k * 32 + fq * 8))
; #define LDB(dst, b, h) _Pragma("unroll") for (int n = 0; n < 2; ++n) _Pragma("unroll") for (int k = 0; k < 2; ++k) \
;     dst[n][k] = *reinterpret_cast<const LAS bf16x8*>(lds + SBo(b, h) + lds_byte(wc * 32 + n * 16 + fr, k * 32 + fq * 8))
; #define MMA(ai, bj, At_, Bt_) do { __builtin_amdgcn_s_setprio(1); \
;     _Pragma("unroll") for (int m = 0; m < 4; ++m) _Pragma("unroll") for (int n = 0; n < 2; ++n) _Pragma("unroll") for (int k = 0; k < 2; ++k) \
;       acc[ai][bj][m][n] = __builtin_amdgcn_mfma_f32_16x16x32_bf16(Bt_[n][k], At_[m][k], acc[ai][bj][m][n], 0, 0, 0); \
;     __builtin_amdgcn_s_setprio(0); } while (0)
; #define WAIT_V(n) asm volatile("s_waitcnt vmcnt(" #n ")" ::: "memory")
; #define WAIT_L(n) asm volatile("s_waitcnt lgkmcnt(" #n ")" ::: "memory")
; #define BAR __builtin_amdgcn_s_barrier()
; template <bool PRE = false>
; __device__ __forceinline__ void gemm_kloop(Acc& acc, const bf16_t* __restrict__ A, int lda, const bf16_t* __restrict__ Bt, int ldb,
;                                            int brow, int bcol, int nt, LAS unsigned char* lds) {
;     ...
;     { LDB(B0, 0, 0); LDA(At, 0, 0); STAGE(SAo(1, 1), A, lda, brow + HALF, nt - 1, offA);
;       BAR; WAIT_L(0); MMA(0, 0, At, B0); BAR;
;       LDB(B1, 0, 1); BAR; WAIT_L(0); MMA(0, 1, At, B1); BAR;
;       LDA(At, 0, 1); WAIT_V(4); BAR; WAIT_L(0); MMA(1, 0, At, B0); MMA(1, 1, At, B1); BAR; }
;     { LDB(B0, 1, 0); LDA(At, 1, 0); WAIT_V(2); BAR; WAIT_L(0); MMA(0, 0, At, B0); BAR;
	s_nop 1
	ds_read_b128 v[98:101], v140
	ds_read_b128 v[102:105], v140 offset:1024
	ds_read_b128 v[114:117], v140 offset:2048
	ds_read_b128 v[118:121], v140 offset:3072
	s_waitcnt vmcnt(8)
	s_barrier
	s_waitcnt lgkmcnt(0)
	s_setprio 1
	s_waitcnt lgkmcnt(0)
	v_mfma_f32_16x16x32_bf16 v[94:97], v[98:101], v[158:161], v[94:97]
	v_mfma_f32_16x16x32_bf16 v[90:93], v[114:117], v[158:161], v[90:93]
	v_mfma_f32_16x16x32_bf16 v[78:81], v[98:101], v[174:177], v[78:81]
	v_mfma_f32_16x16x32_bf16 v[74:77], v[114:117], v[174:177], v[74:77]
	v_mfma_f32_16x16x32_bf16 v[70:73], v[98:101], v[188:191], v[70:73]
	v_mfma_f32_16x16x32_bf16 v[66:69], v[114:117], v[188:191], v[66:69]
	v_mfma_f32_16x16x32_bf16 v[94:97], v[102:105], v[162:165], v[94:97]
	v_mfma_f32_16x16x32_bf16 v[90:93], v[118:121], v[162:165], v[90:93]
	v_mfma_f32_16x16x32_bf16 v[86:89], v[98:101], v[166:169], v[86:89]
	v_mfma_f32_16x16x32_bf16 v[82:85], v[114:117], v[166:169], v[82:85]
	v_mfma_f32_16x16x32_bf16 v[78:81], v[102:105], v[184:187], v[78:81]
	v_mfma_f32_16x16x32_bf16 v[74:77], v[118:121], v[184:187], v[74:77]
	v_mfma_f32_16x16x32_bf16 v[70:73], v[102:105], v[204:207], v[70:73]
	v_mfma_f32_16x16x32_bf16 v[66:69], v[118:121], v[204:207], v[66:69]
	v_mfma_f32_16x16x32_bf16 v[140:143], v[102:105], v[170:173], v[86:89]
	v_mfma_f32_16x16x32_bf16 v[158:161], v[118:121], v[170:173], v[82:85]
	s_setprio 0
	s_barrier
	s_nop 0
	ds_read_b128 v[82:85], v137 offset:16384
	ds_read_b128 v[86:89], v137 offset:17408
	ds_read_b128 v[162:165], v136 offset:16384
	ds_read_b128 v[166:169], v136 offset:17408
	ds_read_b128 v[170:173], v135 offset:16384
	ds_read_b128 v[174:177], v135 offset:17408
	ds_read_b128 v[184:187], v134 offset:16384
	ds_read_b128 v[188:191], v134 offset:17408
	s_waitcnt vmcnt(4)
	s_barrier
	s_waitcnt lgkmcnt(0)
	s_setprio 1
	s_waitcnt lgkmcnt(0)
	v_mfma_f32_16x16x32_bf16 v[58:61], v[150:153], v[82:85], v[58:61]
	v_mfma_f32_16x16x32_bf16 v[46:49], v[130:133], v[170:173], v[46:49]
	v_mfma_f32_16x16x32_bf16 v[38:41], v[130:133], v[184:187], v[38:41]
	v_mfma_f32_16x16x32_bf16 v[62:65], v[130:133], v[82:85], v[62:65]
	v_mfma_f32_16x16x32_bf16 v[58:61], v[154:157], v[86:89], v[58:61]
	v_mfma_f32_16x16x32_bf16 v[54:57], v[130:133], v[162:165], v[54:57]
	v_mfma_f32_16x16x32_bf16 v[50:53], v[150:153], v[162:165], v[50:53]
	v_mfma_f32_16x16x32_bf16 v[46:49], v[146:149], v[174:177], v[46:49]
	v_mfma_f32_16x16x32_bf16 v[42:45], v[150:153], v[170:173], v[42:45]
	v_mfma_f32_16x16x32_bf16 v[38:41], v[146:149], v[188:191], v[38:41]
	v_mfma_f32_16x16x32_bf16 v[34:37], v[150:153], v[184:187], v[34:37]
	v_mfma_f32_16x16x32_bf16 v[204:207], v[146:149], v[86:89], v[62:65]
	v_mfma_f32_16x16x32_bf16 v[224:227], v[146:149], v[166:169], v[54:57]
	v_mfma_f32_16x16x32_bf16 v[228:231], v[154:157], v[166:169], v[50:53]
	v_mfma_f32_16x16x32_bf16 v[232:235], v[154:157], v[174:177], v[42:45]
	v_mfma_f32_16x16x32_bf16 v[130:133], v[154:157], v[188:191], v[34:37]
	s_setprio 0
	s_setprio 1
	v_mfma_f32_16x16x32_bf16 v[30:33], v[98:101], v[82:85], v[30:33]
	v_mfma_f32_16x16x32_bf16 v[22:25], v[98:101], v[162:165], v[22:25]
	v_mfma_f32_16x16x32_bf16 v[14:17], v[98:101], v[170:173], v[14:17]
	v_mfma_f32_16x16x32_bf16 v[6:9], v[98:101], v[184:187], v[6:9]
	v_mfma_f32_16x16x32_bf16 v[30:33], v[102:105], v[86:89], v[30:33]
	v_mfma_f32_16x16x32_bf16 v[26:29], v[114:117], v[82:85], v[26:29]
	v_mfma_f32_16x16x32_bf16 v[22:25], v[102:105], v[166:169], v[22:25]
	v_mfma_f32_16x16x32_bf16 v[18:21], v[114:117], v[162:165], v[18:21]
	v_mfma_f32_16x16x32_bf16 v[14:17], v[102:105], v[174:177], v[14:17]
	v_mfma_f32_16x16x32_bf16 v[10:13], v[114:117], v[170:173], v[10:13]
	v_mfma_f32_16x16x32_bf16 v[6:9], v[102:105], v[188:191], v[6:9]
	v_mfma_f32_16x16x32_bf16 v[2:5], v[114:117], v[184:187], v[2:5]
	v_mfma_f32_16x16x32_bf16 v[146:149], v[118:121], v[86:89], v[26:29]
	v_mfma_f32_16x16x32_bf16 v[150:153], v[118:121], v[166:169], v[18:21]
	v_mfma_f32_16x16x32_bf16 v[154:157], v[118:121], v[174:177], v[10:13]
	v_mfma_f32_16x16x32_bf16 v[162:165], v[118:121], v[188:191], v[2:5]
	s_setprio 0
	s_barrier
	s_nop 1
	ds_read_b128 v[2:5], v139
	ds_read_b128 v[10:13], v139 offset:1024
	ds_read_b128 v[166:169], v139 offset:2048
	ds_read_b128 v[170:173], v139 offset:3072
	ds_read_b128 v[18:21], v137 offset:32768
	ds_read_b128 v[26:29], v137 offset:33792
	ds_read_b128 v[34:37], v136 offset:32768
	ds_read_b128 v[42:45], v136 offset:33792
	ds_read_b128 v[54:57], v135 offset:32768
	ds_read_b128 v[174:177], v135 offset:33792
	ds_read_b128 v[184:187], v134 offset:32768
	ds_read_b128 v[188:191], v134 offset:33792
	s_waitcnt vmcnt(2)
	s_barrier
; #define LDA(dst, b, h) _Pragma("unroll") for (int m = 0; m < 4; ++m) _Pragma("unroll") for (int k = 0; k < 2; ++k) \
;     dst[m][k] = *reinterpret_cast<const LAS bf16x8*>(lds + SAo(b, h) + lds_byte(wr * 64 + m * 16 + fr, k * 32 + fq * 8))
; #define LDB(dst, b, h) _Pragma("unroll") for (int n = 0; n < 2; ++n) _Pragma("unroll") for (int k = 0; k < 2; ++k) \
;     dst[n][k] = *reinterpret_cast<const LAS bf16x8*>(lds + SBo(b, h) + lds_byte(wc * 32 + n * 16 + fr, k * 32 + fq * 8))
; #define MMA(ai, bj, At_, Bt_) do { __builtin_amdgcn_s_setprio(1); \
;     _Pragma("unroll") for (int m = 0; m < 4; ++m) _Pragma("unroll") for (int n = 0; n < 2; ++n) _Pragma("unroll") for (int k = 0; k < 2; ++k) \
;       acc[ai][bj][m][n] = __builtin_amdgcn_mfma_f32_16x16x32_bf16(Bt_[n][k], At_[m][k], acc[ai][bj][m][n], 0, 0, 0); \
;     __builtin_amdgcn_s_setprio(0); } while (0)
; #define WAIT_V(n) asm volatile("s_waitcnt vmcnt(" #n ")" ::: "memory")
; #define WAIT_L(n) asm volatile("s_waitcnt lgkmcnt(" #n ")" ::: "memory")
; #define BAR __builtin_amdgcn_s_barrier()
; template <bool PRE = false>
; __device__ __forceinline__ void gemm_kloop(Acc& acc, const bf16_t* __restrict__ A, int lda, const bf16_t* __restrict__ Bt, int ldb,
;                                            int brow, int bcol, int nt, LAS unsigned char* lds) {
;     ...
;     { LDB(B0, 1, 0); LDA(At, 1, 0); WAIT_V(2); BAR; WAIT_L(0); MMA(0, 0, At, B0); BAR;
;       LDB(B1, 1, 1); WAIT_V(0); BAR; WAIT_L(0); MMA(0, 1, At, B1); BAR;
;       LDA(At, 1, 1); BAR; WAIT_L(0); MMA(1, 0, At, B0); MMA(1, 1, At, B1); BAR; }
;     if (wr == 0) BAR;
	s_waitcnt lgkmcnt(0)
	s_setprio 1
	s_waitcnt lgkmcnt(0)
	v_mfma_f32_16x16x32_bf16 v[50:53], v[2:5], v[18:21], v[126:129]
	v_mfma_f32_16x16x32_bf16 v[118:121], v[10:13], v[26:29], v[50:53]
	v_mfma_f32_16x16x32_bf16 v[50:53], v[166:169], v[18:21], v[122:125]
	v_mfma_f32_16x16x32_bf16 v[114:117], v[170:173], v[26:29], v[50:53]
	v_mfma_f32_16x16x32_bf16 v[50:53], v[2:5], v[34:37], v[208:211]
	v_mfma_f32_16x16x32_bf16 v[102:105], v[10:13], v[42:45], v[50:53]
	v_mfma_f32_16x16x32_bf16 v[50:53], v[166:169], v[34:37], v[212:215]
	v_mfma_f32_16x16x32_bf16 v[98:101], v[170:173], v[42:45], v[50:53]
	v_mfma_f32_16x16x32_bf16 v[50:53], v[2:5], v[54:57], v[110:113]
	v_mfma_f32_16x16x32_bf16 v[86:89], v[10:13], v[174:177], v[50:53]
	v_mfma_f32_16x16x32_bf16 v[50:53], v[166:169], v[54:57], v[106:109]
	v_mfma_f32_16x16x32_bf16 v[82:85], v[170:173], v[174:177], v[50:53]
	v_mfma_f32_16x16x32_bf16 v[50:53], v[2:5], v[184:187], v[216:219]
	v_mfma_f32_16x16x32_bf16 v[62:65], v[10:13], v[188:191], v[50:53]
	v_mfma_f32_16x16x32_bf16 v[50:53], v[166:169], v[184:187], v[220:223]
	v_mfma_f32_16x16x32_bf16 v[50:53], v[170:173], v[188:191], v[50:53]
	s_setprio 0
	s_barrier
	ds_read_b128 v[208:211], v138
	ds_read_b128 v[212:215], v138 offset:1024
	ds_read_b128 v[216:219], v138 offset:2048
	ds_read_b128 v[220:223], v138 offset:3072
	s_waitcnt vmcnt(0)
	s_barrier
	s_waitcnt lgkmcnt(0)
	s_setprio 1
	s_waitcnt lgkmcnt(0)
	v_mfma_f32_16x16x32_bf16 v[94:97], v[208:211], v[18:21], v[94:97]
	v_mfma_f32_16x16x32_bf16 v[18:21], v[216:219], v[18:21], v[90:93]
	v_mfma_f32_16x16x32_bf16 v[122:125], v[220:223], v[26:29], v[18:21]
	v_mfma_f32_16x16x32_bf16 v[18:21], v[208:211], v[34:37], v[140:143]
	v_mfma_f32_16x16x32_bf16 v[110:113], v[212:215], v[42:45], v[18:21]
	v_mfma_f32_16x16x32_bf16 v[18:21], v[216:219], v[34:37], v[158:161]
	v_mfma_f32_16x16x32_bf16 v[106:109], v[220:223], v[42:45], v[18:21]
	v_mfma_f32_16x16x32_bf16 v[18:21], v[208:211], v[54:57], v[78:81]
	v_mfma_f32_16x16x32_bf16 v[126:129], v[212:215], v[26:29], v[94:97]
	v_mfma_f32_16x16x32_bf16 v[94:97], v[212:215], v[174:177], v[18:21]
	v_mfma_f32_16x16x32_bf16 v[18:21], v[216:219], v[54:57], v[74:77]
	v_mfma_f32_16x16x32_bf16 v[90:93], v[220:223], v[174:177], v[18:21]
	v_mfma_f32_16x16x32_bf16 v[18:21], v[208:211], v[184:187], v[70:73]
	v_mfma_f32_16x16x32_bf16 v[78:81], v[212:215], v[188:191], v[18:21]
	v_mfma_f32_16x16x32_bf16 v[18:21], v[216:219], v[184:187], v[66:69]
	v_mfma_f32_16x16x32_bf16 v[66:69], v[220:223], v[188:191], v[18:21]
	s_setprio 0
	s_barrier
	ds_read_b128 v[138:141], v137 offset:49152
	ds_read_b128 v[158:161], v137 offset:50176
	ds_read_b128 v[174:177], v136 offset:49152
	ds_read_b128 v[184:187], v136 offset:50176
	ds_read_b128 v[188:191], v135 offset:49152
	ds_read_b128 v[236:239], v135 offset:50176
	ds_read_b128 v[240:243], v134 offset:49152
	ds_read_b128 v[134:137], v134 offset:50176
	s_barrier
	s_waitcnt lgkmcnt(0)
	s_setprio 1
	s_waitcnt lgkmcnt(0)
	v_mfma_f32_16x16x32_bf16 v[18:21], v[2:5], v[138:141], v[204:207]
	v_mfma_f32_16x16x32_bf16 v[70:73], v[10:13], v[158:161], v[18:21]
	v_mfma_f32_16x16x32_bf16 v[18:21], v[166:169], v[138:141], v[58:61]
	v_mfma_f32_16x16x32_bf16 v[54:57], v[170:173], v[158:161], v[18:21]
	v_mfma_f32_16x16x32_bf16 v[18:21], v[2:5], v[174:177], v[224:227]
	v_mfma_f32_16x16x32_bf16 v[42:45], v[10:13], v[184:187], v[18:21]
	v_mfma_f32_16x16x32_bf16 v[18:21], v[166:169], v[174:177], v[228:231]
	v_mfma_f32_16x16x32_bf16 v[34:37], v[170:173], v[184:187], v[18:21]
	v_mfma_f32_16x16x32_bf16 v[18:21], v[2:5], v[188:191], v[46:49]
	v_mfma_f32_16x16x32_bf16 v[2:5], v[2:5], v[240:243], v[38:41]
	v_mfma_f32_16x16x32_bf16 v[26:29], v[10:13], v[236:239], v[18:21]
	v_mfma_f32_16x16x32_bf16 v[18:21], v[166:169], v[188:191], v[232:235]
	v_mfma_f32_16x16x32_bf16 v[10:13], v[10:13], v[134:137], v[2:5]
	v_mfma_f32_16x16x32_bf16 v[2:5], v[166:169], v[240:243], v[130:133]
	v_mfma_f32_16x16x32_bf16 v[18:21], v[170:173], v[236:239], v[18:21]
	v_mfma_f32_16x16x32_bf16 v[2:5], v[170:173], v[134:137], v[2:5]
	s_setprio 0
	s_setprio 1
	v_mfma_f32_16x16x32_bf16 v[30:33], v[208:211], v[138:141], v[30:33]
	v_mfma_f32_16x16x32_bf16 v[74:77], v[212:215], v[158:161], v[30:33]
	v_mfma_f32_16x16x32_bf16 v[30:33], v[216:219], v[138:141], v[146:149]
	v_mfma_f32_16x16x32_bf16 v[22:25], v[208:211], v[174:177], v[22:25]
	v_mfma_f32_16x16x32_bf16 v[14:17], v[208:211], v[188:191], v[14:17]
	v_mfma_f32_16x16x32_bf16 v[58:61], v[220:223], v[158:161], v[30:33]
	v_mfma_f32_16x16x32_bf16 v[46:49], v[212:215], v[184:187], v[22:25]
	v_mfma_f32_16x16x32_bf16 v[22:25], v[216:219], v[174:177], v[150:153]
	v_mfma_f32_16x16x32_bf16 v[30:33], v[212:215], v[236:239], v[14:17]
	v_mfma_f32_16x16x32_bf16 v[14:17], v[216:219], v[188:191], v[154:157]
	v_mfma_f32_16x16x32_bf16 v[6:9], v[208:211], v[240:243], v[6:9]
	v_mfma_f32_16x16x32_bf16 v[38:41], v[220:223], v[184:187], v[22:25]
	v_mfma_f32_16x16x32_bf16 v[22:25], v[220:223], v[236:239], v[14:17]
	v_mfma_f32_16x16x32_bf16 v[14:17], v[212:215], v[134:137], v[6:9]
	v_mfma_f32_16x16x32_bf16 v[6:9], v[216:219], v[240:243], v[162:165]
	v_mfma_f32_16x16x32_bf16 v[6:9], v[220:223], v[134:137], v[6:9]
	s_setprio 0
	v_cmp_gt_u32_e32 vcc, s85, v1
	s_barrier
	s_and_saveexec_b64 s[36:37], vcc
	s_cbranch_execz .LBB0_546
	s_barrier

; #define LDA(dst, b, h) _Pragma("unroll") for (int m = 0; m < 4; ++m) _Pragma("unroll") for (int k = 0; k < 2; ++k) \
;     dst[m][k] = *reinterpret_cast<const LAS bf16x8*>(lds + SAo(b, h) + lds_byte(wr * 64 + m * 16 + fr, k * 32 + fq * 8))
; #define LDB(dst, b, h) _Pragma("unroll") for (int n = 0; n < 2; ++n) _Pragma("unroll") for (int k = 0; k < 2; ++k) \
;     dst[n][k] = *reinterpret_cast<const LAS bf16x8*>(lds + SBo(b, h) + lds_byte(wc * 32 + n * 16 + fr, k * 32 + fq * 8))
; #define MMA(ai, bj, At_, Bt_) do { __builtin_amdgcn_s_setprio(1); \
;     _Pragma("unroll") for (int m = 0; m < 4; ++m) _Pragma("unroll") for (int n = 0; n < 2; ++n) _Pragma("unroll") for (int k = 0; k < 2; ++k) \
;       acc[ai][bj][m][n] = __builtin_amdgcn_mfma_f32_16x16x32_bf16(Bt_[n][k], At_[m][k], acc[ai][bj][m][n], 0, 0, 0); \
;     __builtin_amdgcn_s_setprio(0); } while (0)
; #define WAIT_L(n) asm volatile("s_waitcnt lgkmcnt(" #n ")" ::: "memory")
; #define BAR __builtin_amdgcn_s_barrier()
; #define SCHED __builtin_amdgcn_sched_barrier(0)
; template <bool PRE = false>
; __device__ __forceinline__ void gemm_kloop(Acc& acc, const bf16_t* __restrict__ A, int lda, const bf16_t* __restrict__ Bt, int ldb,
;                                            int brow, int bcol, int nt, LAS unsigned char* lds) {
;     ...
;     for (int t = 0; t < nt - 2; t += 2) {
;         LDB(B0, 0, 0); SCHED; LDA(At, 0, 0); STAGE(SAo(1, 1), A, lda, brow + HALF, t + 1, offA);
;         WAIT_L(8); BAR; WAIT_L(0); MMA(0, 0, At, B0); BAR; SCHED;
;         LDB(B1, 0, 1); STAGE(SBo(0, 0), Bt, ldb, bcol, t + 2, offB);
;         BAR; WAIT_L(0); MMA(0, 1, At, B1); BAR;
;         LDA(At, 0, 1); STAGE(SAo(0, 0), A, lda, brow, t + 2, offA);
;         BAR; WAIT_L(0); MMA(1, 0, At, B0); BAR; SCHED;
.LBB0_555:
	ds_read_b128 v[146:149], v141
	ds_read_b128 v[150:153], v141 offset:1024
	ds_read_b128 v[154:157], v141 offset:2048
	ds_read_b128 v[158:161], v141 offset:3072
	s_add_i32 s36, s93, 3
	s_mov_b32 s8, s92
	ds_read_b128 v[162:165], v137
	ds_read_b128 v[166:169], v137 offset:1024
	ds_read_b128 v[170:173], v136
	ds_read_b128 v[174:177], v136 offset:1024
	ds_read_b128 v[184:187], v135
	ds_read_b128 v[188:191], v135 offset:1024
	ds_read_b128 v[200:203], v134
	ds_read_b128 v[204:207], v134 offset:1024
	s_ashr_i32 s37, s36, 31
	s_lshl_b64 s[36:37], s[36:37], 7
	s_lshl_b32 s8, s8, 10
	v_lshl_add_u64 v[142:143], v[6:7], 0, s[36:37]
	s_add_i32 s8, s8, 0
	s_lshl_b64 s[36:37], s[48:49], 1
	s_add_i32 m0, s8, 0xc000
	v_lshl_add_u64 v[192:193], v[142:143], 0, s[36:37]
	s_lshl_b64 s[52:53], s[50:51], 1
	global_load_lds_dwordx4 v[192:193], off
	v_lshl_add_u64 v[142:143], v[142:143], 0, s[52:53]
	s_add_i32 m0, s8, 0xe000
	s_nop 0
	global_load_lds_dwordx4 v[142:143], off
	s_waitcnt lgkmcnt(8)
	s_waitcnt vmcnt(10)
	s_barrier
	s_waitcnt lgkmcnt(0)
	s_setprio 1
	s_waitcnt lgkmcnt(0)
	v_mfma_f32_16x16x32_bf16 v[2:5], v[146:149], v[162:165], v[2:5]
	v_mfma_f32_16x16x32_bf16 v[10:13], v[154:157], v[162:165], v[10:13]
	v_mfma_f32_16x16x32_bf16 v[34:37], v[146:149], v[170:173], v[34:37]
	v_mfma_f32_16x16x32_bf16 v[42:45], v[154:157], v[170:173], v[42:45]
	v_mfma_f32_16x16x32_bf16 v[66:69], v[146:149], v[184:187], v[66:69]
	v_mfma_f32_16x16x32_bf16 v[74:77], v[154:157], v[184:187], v[74:77]
	v_mfma_f32_16x16x32_bf16 v[98:101], v[146:149], v[200:203], v[98:101]
	v_mfma_f32_16x16x32_bf16 v[106:109], v[154:157], v[200:203], v[106:109]
	v_mfma_f32_16x16x32_bf16 v[2:5], v[150:153], v[166:169], v[2:5]
	v_mfma_f32_16x16x32_bf16 v[10:13], v[158:161], v[166:169], v[10:13]
	v_mfma_f32_16x16x32_bf16 v[34:37], v[150:153], v[174:177], v[34:37]
	v_mfma_f32_16x16x32_bf16 v[42:45], v[158:161], v[174:177], v[42:45]
	v_mfma_f32_16x16x32_bf16 v[66:69], v[150:153], v[188:191], v[66:69]
	v_mfma_f32_16x16x32_bf16 v[74:77], v[158:161], v[188:191], v[74:77]
	v_mfma_f32_16x16x32_bf16 v[98:101], v[150:153], v[204:207], v[98:101]
	v_mfma_f32_16x16x32_bf16 v[106:109], v[158:161], v[204:207], v[106:109]
	s_setprio 0
	s_barrier
	s_add_i32 s66, s93, 4
	s_mov_b32 s54, s66
	s_mov_b32 s8, s92
	ds_read_b128 v[208:211], v140
	ds_read_b128 v[212:215], v140 offset:1024
	ds_read_b128 v[216:219], v140 offset:2048
	ds_read_b128 v[220:223], v140 offset:3072
	s_ashr_i32 s55, s54, 31
	s_lshl_b64 s[54:55], s[54:55], 7
	s_lshl_b32 s8, s8, 10
	v_lshl_add_u64 v[142:143], v[8:9], 0, s[54:55]
	s_add_i32 s8, s8, 0
	s_lshl_b64 s[54:55], s[0:1], 1
	s_add_i32 m0, s8, 0x10000
	v_lshl_add_u64 v[192:193], v[142:143], 0, s[54:55]
	s_lshl_b64 s[56:57], s[38:39], 1
	global_load_lds_dwordx4 v[192:193], off
	v_lshl_add_u64 v[142:143], v[142:143], 0, s[56:57]
	s_add_i32 m0, s8, 0x12000
	s_nop 0
	global_load_lds_dwordx4 v[142:143], off
	s_waitcnt vmcnt(10)
	s_barrier
	s_waitcnt lgkmcnt(0)
	s_setprio 1
	s_waitcnt lgkmcnt(0)
	v_mfma_f32_16x16x32_bf16 v[18:21], v[208:211], v[162:165], v[18:21]
	v_mfma_f32_16x16x32_bf16 v[26:29], v[216:219], v[162:165], v[26:29]
	v_mfma_f32_16x16x32_bf16 v[50:53], v[208:211], v[170:173], v[50:53]
	v_mfma_f32_16x16x32_bf16 v[58:61], v[216:219], v[170:173], v[58:61]
	v_mfma_f32_16x16x32_bf16 v[82:85], v[208:211], v[184:187], v[82:85]
	v_mfma_f32_16x16x32_bf16 v[90:93], v[216:219], v[184:187], v[90:93]
	v_mfma_f32_16x16x32_bf16 v[114:117], v[208:211], v[200:203], v[114:117]
	v_mfma_f32_16x16x32_bf16 v[122:125], v[216:219], v[200:203], v[122:125]
	v_mfma_f32_16x16x32_bf16 v[18:21], v[212:215], v[166:169], v[18:21]
	v_mfma_f32_16x16x32_bf16 v[26:29], v[220:223], v[166:169], v[26:29]
	v_mfma_f32_16x16x32_bf16 v[50:53], v[212:215], v[174:177], v[50:53]
	v_mfma_f32_16x16x32_bf16 v[58:61], v[220:223], v[174:177], v[58:61]
	v_mfma_f32_16x16x32_bf16 v[82:85], v[212:215], v[188:191], v[82:85]
	v_mfma_f32_16x16x32_bf16 v[90:93], v[220:223], v[188:191], v[90:93]
	v_mfma_f32_16x16x32_bf16 v[114:117], v[212:215], v[204:207], v[114:117]
	v_mfma_f32_16x16x32_bf16 v[122:125], v[220:223], v[204:207], v[122:125]
	s_setprio 0
	s_mov_b32 s58, s66
	s_mov_b32 s8, s92
	s_barrier
	ds_read_b128 v[162:165], v137 offset:16384
	ds_read_b128 v[166:169], v137 offset:17408
	ds_read_b128 v[170:173], v136 offset:16384
	ds_read_b128 v[174:177], v136 offset:17408
	ds_read_b128 v[184:187], v135 offset:16384
	ds_read_b128 v[188:191], v135 offset:17408
	ds_read_b128 v[200:203], v134 offset:16384
	ds_read_b128 v[204:207], v134 offset:17408
	s_ashr_i32 s59, s58, 31
	s_lshl_b64 s[58:59], s[58:59], 7
	s_lshl_b32 s8, s8, 10
	v_lshl_add_u64 v[142:143], v[6:7], 0, s[58:59]
	s_add_i32 s8, s8, 0
	s_lshl_b64 s[58:59], s[40:41], 1
	v_lshl_add_u64 v[192:193], v[142:143], 0, s[58:59]
	s_mov_b32 m0, s8
	s_lshl_b64 s[60:61], s[42:43], 1
	global_load_lds_dwordx4 v[192:193], off
	v_lshl_add_u64 v[142:143], v[142:143], 0, s[60:61]
	s_add_i32 m0, s8, 0x2000
	s_nop 0
	global_load_lds_dwordx4 v[142:143], off
	s_barrier
	s_waitcnt lgkmcnt(0)
	s_setprio 1
	s_waitcnt lgkmcnt(0)
	v_mfma_f32_16x16x32_bf16 v[130:133], v[146:149], v[162:165], v[130:133]
	v_mfma_f32_16x16x32_bf16 v[126:129], v[154:157], v[162:165], v[126:129]
	v_mfma_f32_16x16x32_bf16 v[102:105], v[146:149], v[170:173], v[102:105]
	v_mfma_f32_16x16x32_bf16 v[94:97], v[154:157], v[170:173], v[94:97]
	v_mfma_f32_16x16x32_bf16 v[70:73], v[146:149], v[184:187], v[70:73]
	v_mfma_f32_16x16x32_bf16 v[62:65], v[154:157], v[184:187], v[62:65]
	v_mfma_f32_16x16x32_bf16 v[38:41], v[146:149], v[200:203], v[38:41]
	v_mfma_f32_16x16x32_bf16 v[30:33], v[154:157], v[200:203], v[30:33]
	v_mfma_f32_16x16x32_bf16 v[130:133], v[150:153], v[166:169], v[130:133]
	v_mfma_f32_16x16x32_bf16 v[126:129], v[158:161], v[166:169], v[126:129]
	v_mfma_f32_16x16x32_bf16 v[102:105], v[150:153], v[174:177], v[102:105]
	v_mfma_f32_16x16x32_bf16 v[94:97], v[158:161], v[174:177], v[94:97]
	v_mfma_f32_16x16x32_bf16 v[70:73], v[150:153], v[188:191], v[70:73]
	v_mfma_f32_16x16x32_bf16 v[62:65], v[158:161], v[188:191], v[62:65]
	v_mfma_f32_16x16x32_bf16 v[38:41], v[150:153], v[204:207], v[38:41]
	v_mfma_f32_16x16x32_bf16 v[30:33], v[158:161], v[204:207], v[30:33]
	s_setprio 0
	s_barrier
; #define LDA(dst, b, h) _Pragma("unroll") for (int m = 0; m < 4; ++m) _Pragma("unroll") for (int k = 0; k < 2; ++k) \
;     dst[m][k] = *reinterpret_cast<const LAS bf16x8*>(lds + SAo(b, h) + lds_byte(wr * 64 + m * 16 + fr, k * 32 + fq * 8))
; #define LDB(dst, b, h) _Pragma("unroll") for (int n = 0; n < 2; ++n) _Pragma("unroll") for (int k = 0; k < 2; ++k) \
;     dst[n][k] = *reinterpret_cast<const LAS bf16x8*>(lds + SBo(b, h) + lds_byte(wc * 32 + n * 16 + fr, k * 32 + fq * 8))
; #define MMA(ai, bj, At_, Bt_) do { __builtin_amdgcn_s_setprio(1); \
;     _Pragma("unroll") for (int m = 0; m < 4; ++m) _Pragma("unroll") for (int n = 0; n < 2; ++n) _Pragma("unroll") for (int k = 0; k < 2; ++k) \
;       acc[ai][bj][m][n] = __builtin_amdgcn_mfma_f32_16x16x32_bf16(Bt_[n][k], At_[m][k], acc[ai][bj][m][n], 0, 0, 0); \
;     __builtin_amdgcn_s_setprio(0); } while (0)
; #define WAIT_V(n) asm volatile("s_waitcnt vmcnt(" #n ")" ::: "memory")
; #define WAIT_L(n) asm volatile("s_waitcnt lgkmcnt(" #n ")" ::: "memory")
; #define BAR __builtin_amdgcn_s_barrier()
; #define SCHED __builtin_amdgcn_sched_barrier(0)
; template <bool PRE = false>
; __device__ __forceinline__ void gemm_kloop(Acc& acc, const bf16_t* __restrict__ A, int lda, const bf16_t* __restrict__ Bt, int ldb,
;                                            int brow, int bcol, int nt, LAS unsigned char* lds) {
;     ...
;         STAGE(SBo(0, 1), Bt, ldb, bcol + HALF, t + 2, offB);
;         WAIT_V(6); BAR; MMA(1, 1, At, B1); BAR;
;         LDB(B0, 1, 0); SCHED; LDA(At, 1, 0); STAGE(SAo(0, 1), A, lda, brow + HALF, t + 2, offA);
;         WAIT_L(8); BAR; WAIT_L(0); MMA(0, 0, At, B0); BAR; SCHED;
;         LDB(B1, 1, 1); STAGE(SBo(1, 0), Bt, ldb, bcol, t + 3, offB);
;         BAR; WAIT_L(0); MMA(0, 1, At, B1); BAR;
	s_mov_b32 s62, s66
	s_mov_b32 s8, s92
	s_ashr_i32 s63, s62, 31
	s_lshl_b64 s[62:63], s[62:63], 7
	s_lshl_b32 s8, s8, 10
	v_lshl_add_u64 v[142:143], v[8:9], 0, s[62:63]
	s_add_i32 s8, s8, 0
	s_lshl_b64 s[62:63], s[44:45], 1
	s_add_i32 m0, s8, 0x14000
	v_lshl_add_u64 v[146:147], v[142:143], 0, s[62:63]
	s_lshl_b64 s[64:65], s[46:47], 1
	global_load_lds_dwordx4 v[146:147], off
	v_lshl_add_u64 v[142:143], v[142:143], 0, s[64:65]
	s_add_i32 m0, s8, 0x16000
	s_nop 0
	global_load_lds_dwordx4 v[142:143], off
	s_waitcnt vmcnt(10)
	s_barrier
	s_setprio 1
	v_mfma_f32_16x16x32_bf16 v[118:121], v[208:211], v[162:165], v[118:121]
	v_mfma_f32_16x16x32_bf16 v[110:113], v[216:219], v[162:165], v[110:113]
	v_mfma_f32_16x16x32_bf16 v[86:89], v[208:211], v[170:173], v[86:89]
	v_mfma_f32_16x16x32_bf16 v[78:81], v[216:219], v[170:173], v[78:81]
	v_mfma_f32_16x16x32_bf16 v[54:57], v[208:211], v[184:187], v[54:57]
	v_mfma_f32_16x16x32_bf16 v[46:49], v[216:219], v[184:187], v[46:49]
	v_mfma_f32_16x16x32_bf16 v[22:25], v[208:211], v[200:203], v[22:25]
	v_mfma_f32_16x16x32_bf16 v[14:17], v[216:219], v[200:203], v[14:17]
	v_mfma_f32_16x16x32_bf16 v[118:121], v[212:215], v[166:169], v[118:121]
	v_mfma_f32_16x16x32_bf16 v[110:113], v[220:223], v[166:169], v[110:113]
	v_mfma_f32_16x16x32_bf16 v[86:89], v[212:215], v[174:177], v[86:89]
	v_mfma_f32_16x16x32_bf16 v[78:81], v[220:223], v[174:177], v[78:81]
	v_mfma_f32_16x16x32_bf16 v[54:57], v[212:215], v[188:191], v[54:57]
	v_mfma_f32_16x16x32_bf16 v[46:49], v[220:223], v[188:191], v[46:49]
	v_mfma_f32_16x16x32_bf16 v[22:25], v[212:215], v[204:207], v[22:25]
	v_mfma_f32_16x16x32_bf16 v[14:17], v[220:223], v[204:207], v[14:17]
	s_setprio 0
	s_barrier
	ds_read_b128 v[146:149], v139
	ds_read_b128 v[150:153], v139 offset:1024
	ds_read_b128 v[154:157], v139 offset:2048
	ds_read_b128 v[158:161], v139 offset:3072
	s_mov_b32 s8, s92
	ds_read_b128 v[162:165], v137 offset:32768
	ds_read_b128 v[166:169], v137 offset:33792
	ds_read_b128 v[170:173], v136 offset:32768
	ds_read_b128 v[174:177], v136 offset:33792
	ds_read_b128 v[184:187], v135 offset:32768
	ds_read_b128 v[188:191], v135 offset:33792
	ds_read_b128 v[200:203], v134 offset:32768
	ds_read_b128 v[204:207], v134 offset:33792
	s_ashr_i32 s67, s66, 31
	s_lshl_b64 s[66:67], s[66:67], 7
	s_lshl_b32 s8, s8, 10
	v_lshl_add_u64 v[142:143], v[6:7], 0, s[66:67]
	s_add_i32 s8, s8, 0
	s_add_i32 m0, s8, 0x4000
	v_lshl_add_u64 v[192:193], v[142:143], 0, s[36:37]
	global_load_lds_dwordx4 v[192:193], off
	v_lshl_add_u64 v[142:143], v[142:143], 0, s[52:53]
	s_add_i32 m0, s8, 0x6000
	s_nop 0
	global_load_lds_dwordx4 v[142:143], off
	s_waitcnt lgkmcnt(8)
	s_waitcnt vmcnt(10)
	s_barrier
	s_waitcnt lgkmcnt(0)
	s_setprio 1
	s_waitcnt lgkmcnt(0)
	v_mfma_f32_16x16x32_bf16 v[2:5], v[146:149], v[162:165], v[2:5]
	v_mfma_f32_16x16x32_bf16 v[10:13], v[154:157], v[162:165], v[10:13]
	v_mfma_f32_16x16x32_bf16 v[34:37], v[146:149], v[170:173], v[34:37]
	v_mfma_f32_16x16x32_bf16 v[42:45], v[154:157], v[170:173], v[42:45]
	v_mfma_f32_16x16x32_bf16 v[66:69], v[146:149], v[184:187], v[66:69]
	v_mfma_f32_16x16x32_bf16 v[74:77], v[154:157], v[184:187], v[74:77]
	v_mfma_f32_16x16x32_bf16 v[98:101], v[146:149], v[200:203], v[98:101]
	v_mfma_f32_16x16x32_bf16 v[106:109], v[154:157], v[200:203], v[106:109]
	v_mfma_f32_16x16x32_bf16 v[2:5], v[150:153], v[166:169], v[2:5]
	v_mfma_f32_16x16x32_bf16 v[10:13], v[158:161], v[166:169], v[10:13]
	v_mfma_f32_16x16x32_bf16 v[34:37], v[150:153], v[174:177], v[34:37]
	v_mfma_f32_16x16x32_bf16 v[42:45], v[158:161], v[174:177], v[42:45]
	v_mfma_f32_16x16x32_bf16 v[66:69], v[150:153], v[188:191], v[66:69]
	v_mfma_f32_16x16x32_bf16 v[74:77], v[158:161], v[188:191], v[74:77]
	v_mfma_f32_16x16x32_bf16 v[98:101], v[150:153], v[204:207], v[98:101]
	v_mfma_f32_16x16x32_bf16 v[106:109], v[158:161], v[204:207], v[106:109]
	s_setprio 0
	s_barrier
	s_add_i32 s36, s93, 5
	s_mov_b32 s52, s36
	s_mov_b32 s8, s92
	ds_read_b128 v[208:211], v138
	ds_read_b128 v[212:215], v138 offset:1024
	ds_read_b128 v[216:219], v138 offset:2048
	ds_read_b128 v[220:223], v138 offset:3072
	s_ashr_i32 s53, s52, 31
	s_lshl_b64 s[52:53], s[52:53], 7
	s_lshl_b32 s8, s8, 10
	v_lshl_add_u64 v[142:143], v[8:9], 0, s[52:53]
	s_add_i32 s8, s8, 0
	s_add_i32 m0, s8, 0x18000
	v_lshl_add_u64 v[192:193], v[142:143], 0, s[54:55]
	global_load_lds_dwordx4 v[192:193], off
	v_lshl_add_u64 v[142:143], v[142:143], 0, s[56:57]
	s_add_i32 m0, s8, 0x1a000
	s_nop 0
	global_load_lds_dwordx4 v[142:143], off
	s_waitcnt vmcnt(10)
	s_barrier
	s_waitcnt lgkmcnt(0)
	s_setprio 1
	s_waitcnt lgkmcnt(0)
	v_mfma_f32_16x16x32_bf16 v[18:21], v[208:211], v[162:165], v[18:21]
	v_mfma_f32_16x16x32_bf16 v[26:29], v[216:219], v[162:165], v[26:29]
	v_mfma_f32_16x16x32_bf16 v[50:53], v[208:211], v[170:173], v[50:53]
	v_mfma_f32_16x16x32_bf16 v[58:61], v[216:219], v[170:173], v[58:61]
	v_mfma_f32_16x16x32_bf16 v[82:85], v[208:211], v[184:187], v[82:85]
	v_mfma_f32_16x16x32_bf16 v[90:93], v[216:219], v[184:187], v[90:93]
	v_mfma_f32_16x16x32_bf16 v[114:117], v[208:211], v[200:203], v[114:117]
	v_mfma_f32_16x16x32_bf16 v[122:125], v[216:219], v[200:203], v[122:125]
	v_mfma_f32_16x16x32_bf16 v[18:21], v[212:215], v[166:169], v[18:21]
	v_mfma_f32_16x16x32_bf16 v[26:29], v[220:223], v[166:169], v[26:29]
	v_mfma_f32_16x16x32_bf16 v[50:53], v[212:215], v[174:177], v[50:53]
	v_mfma_f32_16x16x32_bf16 v[58:61], v[220:223], v[174:177], v[58:61]
	v_mfma_f32_16x16x32_bf16 v[82:85], v[212:215], v[188:191], v[82:85]
	v_mfma_f32_16x16x32_bf16 v[90:93], v[220:223], v[188:191], v[90:93]
	v_mfma_f32_16x16x32_bf16 v[114:117], v[212:215], v[204:207], v[114:117]
	v_mfma_f32_16x16x32_bf16 v[122:125], v[220:223], v[204:207], v[122:125]
	s_setprio 0
	s_mov_b32 s52, s36
	s_mov_b32 s8, s92
	s_barrier
; #define LDA(dst, b, h) _Pragma("unroll") for (int m = 0; m < 4; ++m) _Pragma("unroll") for (int k = 0; k < 2; ++k) \
;     dst[m][k] = *reinterpret_cast<const LAS bf16x8*>(lds + SAo(b, h) + lds_byte(wr * 64 + m * 16 + fr, k * 32 + fq * 8))
; #define LDB(dst, b, h) _Pragma("unroll") for (int n = 0; n < 2; ++n) _Pragma("unroll") for (int k = 0; k < 2; ++k) \
;     dst[n][k] = *reinterpret_cast<const LAS bf16x8*>(lds + SBo(b, h) + lds_byte(wc * 32 + n * 16 + fr, k * 32 + fq * 8))
; #define MMA(ai, bj, At_, Bt_) do { __builtin_amdgcn_s_setprio(1); \
;     _Pragma("unroll") for (int m = 0; m < 4; ++m) _Pragma("unroll") for (int n = 0; n < 2; ++n) _Pragma("unroll") for (int k = 0; k < 2; ++k) \
;       acc[ai][bj][m][n] = __builtin_amdgcn_mfma_f32_16x16x32_bf16(Bt_[n][k], At_[m][k], acc[ai][bj][m][n], 0, 0, 0); \
;     __builtin_amdgcn_s_setprio(0); } while (0)
; #define WAIT_V(n) asm volatile("s_waitcnt vmcnt(" #n ")" ::: "memory")
; #define WAIT_L(n) asm volatile("s_waitcnt lgkmcnt(" #n ")" ::: "memory")
; #define BAR __builtin_amdgcn_s_barrier()
; #define SCHED __builtin_amdgcn_sched_barrier(0)
; template <bool PRE = false>
; __device__ __forceinline__ void gemm_kloop(Acc& acc, const bf16_t* __restrict__ A, int lda, const bf16_t* __restrict__ Bt, int ldb,
;                                            int brow, int bcol, int nt, LAS unsigned char* lds) {
;     ...
;         LDA(At, 1, 1); STAGE(SAo(1, 0), A, lda, brow, t + 3, offA);
;         BAR; WAIT_L(0); MMA(1, 0, At, B0); BAR; SCHED;
;         STAGE(SBo(1, 1), Bt, ldb, bcol + HALF, t + 3, offB);
;         WAIT_V(6); BAR; MMA(1, 1, At, B1); BAR;
;     }
;     { LDB(B0, 0, 0); LDA(At, 0, 0); STAGE(SAo(1, 1), A, lda, brow + HALF, nt - 1, offA);
	ds_read_b128 v[162:165], v137 offset:49152
	ds_read_b128 v[166:169], v137 offset:50176
	ds_read_b128 v[170:173], v136 offset:49152
	ds_read_b128 v[174:177], v136 offset:50176
	ds_read_b128 v[184:187], v135 offset:49152
	ds_read_b128 v[188:191], v135 offset:50176
	ds_read_b128 v[200:203], v134 offset:49152
	ds_read_b128 v[204:207], v134 offset:50176
	s_ashr_i32 s53, s52, 31
	s_lshl_b64 s[52:53], s[52:53], 7
	s_lshl_b32 s8, s8, 10
	v_lshl_add_u64 v[142:143], v[6:7], 0, s[52:53]
	s_add_i32 s8, s8, 0
	s_add_i32 m0, s8, 0x8000
	v_lshl_add_u64 v[192:193], v[142:143], 0, s[58:59]
	global_load_lds_dwordx4 v[192:193], off
	v_lshl_add_u64 v[142:143], v[142:143], 0, s[60:61]
	s_add_i32 m0, s8, 0xa000
	s_nop 0
	global_load_lds_dwordx4 v[142:143], off
	s_barrier
	s_waitcnt lgkmcnt(0)
	s_setprio 1
	s_waitcnt lgkmcnt(0)
	v_mfma_f32_16x16x32_bf16 v[130:133], v[146:149], v[162:165], v[130:133]
	v_mfma_f32_16x16x32_bf16 v[126:129], v[154:157], v[162:165], v[126:129]
	v_mfma_f32_16x16x32_bf16 v[102:105], v[146:149], v[170:173], v[102:105]
	v_mfma_f32_16x16x32_bf16 v[94:97], v[154:157], v[170:173], v[94:97]
	v_mfma_f32_16x16x32_bf16 v[70:73], v[146:149], v[184:187], v[70:73]
	v_mfma_f32_16x16x32_bf16 v[62:65], v[154:157], v[184:187], v[62:65]
	v_mfma_f32_16x16x32_bf16 v[38:41], v[146:149], v[200:203], v[38:41]
	v_mfma_f32_16x16x32_bf16 v[30:33], v[154:157], v[200:203], v[30:33]
	v_mfma_f32_16x16x32_bf16 v[130:133], v[150:153], v[166:169], v[130:133]
	v_mfma_f32_16x16x32_bf16 v[126:129], v[158:161], v[166:169], v[126:129]
	v_mfma_f32_16x16x32_bf16 v[102:105], v[150:153], v[174:177], v[102:105]
	v_mfma_f32_16x16x32_bf16 v[94:97], v[158:161], v[174:177], v[94:97]
	v_mfma_f32_16x16x32_bf16 v[70:73], v[150:153], v[188:191], v[70:73]
	v_mfma_f32_16x16x32_bf16 v[62:65], v[158:161], v[188:191], v[62:65]
	v_mfma_f32_16x16x32_bf16 v[38:41], v[150:153], v[204:207], v[38:41]
	v_mfma_f32_16x16x32_bf16 v[30:33], v[158:161], v[204:207], v[30:33]
	s_setprio 0
	s_barrier
	s_mov_b32 s8, s92
	s_ashr_i32 s37, s36, 31
	s_lshl_b64 s[36:37], s[36:37], 7
	s_lshl_b32 s8, s8, 10
	v_lshl_add_u64 v[142:143], v[8:9], 0, s[36:37]
	s_add_i32 s8, s8, 0
	s_add_i32 m0, s8, 0x1c000
	v_lshl_add_u64 v[146:147], v[142:143], 0, s[62:63]
	global_load_lds_dwordx4 v[146:147], off
	v_lshl_add_u64 v[142:143], v[142:143], 0, s[64:65]
	s_add_i32 m0, s8, 0x1e000
	s_nop 0
	global_load_lds_dwordx4 v[142:143], off
	s_waitcnt vmcnt(10)
	s_barrier
	s_setprio 1
	v_mfma_f32_16x16x32_bf16 v[118:121], v[208:211], v[162:165], v[118:121]
	v_mfma_f32_16x16x32_bf16 v[110:113], v[216:219], v[162:165], v[110:113]
	v_mfma_f32_16x16x32_bf16 v[86:89], v[208:211], v[170:173], v[86:89]
	v_mfma_f32_16x16x32_bf16 v[78:81], v[216:219], v[170:173], v[78:81]
	v_mfma_f32_16x16x32_bf16 v[54:57], v[208:211], v[184:187], v[54:57]
	v_mfma_f32_16x16x32_bf16 v[46:49], v[216:219], v[184:187], v[46:49]
	v_mfma_f32_16x16x32_bf16 v[22:25], v[208:211], v[200:203], v[22:25]
	v_mfma_f32_16x16x32_bf16 v[14:17], v[216:219], v[200:203], v[14:17]
	v_mfma_f32_16x16x32_bf16 v[118:121], v[212:215], v[166:169], v[118:121]
	v_mfma_f32_16x16x32_bf16 v[110:113], v[220:223], v[166:169], v[110:113]
	v_mfma_f32_16x16x32_bf16 v[86:89], v[212:215], v[174:177], v[86:89]
	v_mfma_f32_16x16x32_bf16 v[78:81], v[220:223], v[174:177], v[78:81]
	v_mfma_f32_16x16x32_bf16 v[54:57], v[212:215], v[188:191], v[54:57]
	v_mfma_f32_16x16x32_bf16 v[46:49], v[220:223], v[188:191], v[46:49]
	v_mfma_f32_16x16x32_bf16 v[22:25], v[212:215], v[204:207], v[22:25]
	v_mfma_f32_16x16x32_bf16 v[14:17], v[220:223], v[204:207], v[14:17]
	s_setprio 0
	s_add_i32 s93, s93, 2
	s_cmp_lt_u32 s93, 4
	s_barrier
	s_cbranch_scc1 .LBB0_555
	s_mov_b32 s36, 7
	ds_read_b128 v[6:9], v141
	ds_read_b128 v[146:149], v141 offset:1024
	ds_read_b128 v[150:153], v141 offset:2048
	ds_read_b128 v[154:157], v141 offset:3072
	ds_read_b128 v[158:161], v137
	ds_read_b128 v[162:165], v137 offset:1024
	ds_read_b128 v[166:169], v136
	ds_read_b128 v[170:173], v136 offset:1024
	ds_read_b128 v[174:177], v135
	ds_read_b128 v[184:187], v135 offset:1024
	ds_read_b128 v[188:191], v134
	ds_read_b128 v[200:203], v134 offset:1024
	s_ashr_i32 s37, s36, 31
	s_lshl_b64 s[36:37], s[36:37], 7
	s_add_u32 s12, s12, s36
	s_addc_u32 s13, s13, s37
	s_lshl_b32 s8, s92, 10
	v_lshl_add_u64 v[142:143], s[12:13], 0, v[144:145]
	s_add_i32 s8, s8, 0
	s_add_i32 m0, s8, 0xc000
	v_lshl_add_u64 v[192:193], s[48:49], 1, v[142:143]
	global_load_lds_dwordx4 v[192:193], off
	v_lshl_add_u64 v[142:143], s[50:51], 1, v[142:143]
	s_add_i32 m0, s8, 0xe000
	s_nop 0
	global_load_lds_dwordx4 v[142:143], off
	s_waitcnt vmcnt(10)
	s_barrier
	s_waitcnt lgkmcnt(0)
	s_setprio 1
	s_waitcnt lgkmcnt(0)
	v_mfma_f32_16x16x32_bf16 v[10:13], v[150:153], v[158:161], v[10:13]
	v_mfma_f32_16x16x32_bf16 v[204:207], v[154:157], v[162:165], v[10:13]
	v_mfma_f32_16x16x32_bf16 v[10:13], v[6:9], v[166:169], v[34:37]
	v_mfma_f32_16x16x32_bf16 v[34:37], v[146:149], v[170:173], v[10:13]
	v_mfma_f32_16x16x32_bf16 v[10:13], v[150:153], v[166:169], v[42:45]
	v_mfma_f32_16x16x32_bf16 v[208:211], v[154:157], v[170:173], v[10:13]
	v_mfma_f32_16x16x32_bf16 v[10:13], v[6:9], v[174:177], v[66:69]
	v_mfma_f32_16x16x32_bf16 v[66:69], v[146:149], v[184:187], v[10:13]
	v_mfma_f32_16x16x32_bf16 v[10:13], v[150:153], v[174:177], v[74:77]
	v_mfma_f32_16x16x32_bf16 v[212:215], v[154:157], v[184:187], v[10:13]
	v_mfma_f32_16x16x32_bf16 v[10:13], v[6:9], v[188:191], v[98:101]
	v_mfma_f32_16x16x32_bf16 v[2:5], v[6:9], v[158:161], v[2:5]
	v_mfma_f32_16x16x32_bf16 v[98:101], v[146:149], v[200:203], v[10:13]
	v_mfma_f32_16x16x32_bf16 v[10:13], v[150:153], v[188:191], v[106:109]
	v_mfma_f32_16x16x32_bf16 v[2:5], v[146:149], v[162:165], v[2:5]
	v_mfma_f32_16x16x32_bf16 v[216:219], v[154:157], v[200:203], v[10:13]
	s_setprio 0
	s_barrier
; #define LDA(dst, b, h) _Pragma("unroll") for (int m = 0; m < 4; ++m) _Pragma("unroll") for (int k = 0; k < 2; ++k) \
;     dst[m][k] = *reinterpret_cast<const LAS bf16x8*>(lds + SAo(b, h) + lds_byte(wr * 64 + m * 16 + fr, k * 32 + fq * 8))
; #define LDB(dst, b, h) _Pragma("unroll") for (int n = 0; n < 2; ++n) _Pragma("unroll") for (int k = 0; k < 2; ++k) \
;     dst[n][k] = *reinterpret_cast<const LAS bf16x8*>(lds + SBo(b, h) + lds_byte(wc * 32 + n * 16 + fr, k * 32 + fq * 8))
; #define MMA(ai, bj, At_, Bt_) do { __builtin_amdgcn_s_setprio(1); \
;     _Pragma("unroll") for (int m = 0; m < 4; ++m) _Pragma("unroll") for (int n = 0; n < 2; ++n) _Pragma("unroll") for (int k = 0; k < 2; ++k) \
;       acc[ai][bj][m][n] = __builtin_amdgcn_mfma_f32_16x16x32_bf16(Bt_[n][k], At_[m][k], acc[ai][bj][m][n], 0, 0, 0); \
;     __builtin_amdgcn_s_setprio(0); } while (0)
; #define WAIT_V(n) asm volatile("s_waitcnt vmcnt(" #n ")" ::: "memory")
; #define WAIT_L(n) asm volatile("s_waitcnt lgkmcnt(" #n ")" ::: "memory")
; #define BAR __builtin_amdgcn_s_barrier()
; template <bool PRE = false>
; __device__ __forceinline__ void gemm_kloop(Acc& acc, const bf16_t* __restrict__ A, int lda, const bf16_t* __restrict__ Bt, int ldb,
;                                            int brow, int bcol, int nt, LAS unsigned char* lds) {
;     ...
;     { LDB(B0, 0, 0); LDA(At, 0, 0); STAGE(SAo(1, 1), A, lda, brow + HALF, nt - 1, offA);
;       BAR; WAIT_L(0); MMA(0, 0, At, B0); BAR;
;       LDB(B1, 0, 1); BAR; WAIT_L(0); MMA(0, 1, At, B1); BAR;
;       LDA(At, 0, 1); WAIT_V(4); BAR; WAIT_L(0); MMA(1, 0, At, B0); MMA(1, 1, At, B1); BAR; }
;     { LDB(B0, 1, 0); LDA(At, 1, 0); WAIT_V(2); BAR; WAIT_L(0); MMA(0, 0, At, B0); BAR;
	s_nop 3
	ds_read_b128 v[10:13], v140
	ds_read_b128 v[42:45], v140 offset:1024
	ds_read_b128 v[74:77], v140 offset:2048
	ds_read_b128 v[106:109], v140 offset:3072
	s_waitcnt vmcnt(8)
	s_barrier
	s_waitcnt lgkmcnt(0)
	s_setprio 1
	s_waitcnt lgkmcnt(0)
	v_mfma_f32_16x16x32_bf16 v[18:21], v[10:13], v[158:161], v[18:21]
	v_mfma_f32_16x16x32_bf16 v[140:143], v[42:45], v[162:165], v[18:21]
	v_mfma_f32_16x16x32_bf16 v[18:21], v[74:77], v[158:161], v[26:29]
	v_mfma_f32_16x16x32_bf16 v[158:161], v[106:109], v[162:165], v[18:21]
	v_mfma_f32_16x16x32_bf16 v[18:21], v[10:13], v[166:169], v[50:53]
	v_mfma_f32_16x16x32_bf16 v[162:165], v[42:45], v[170:173], v[18:21]
	v_mfma_f32_16x16x32_bf16 v[18:21], v[74:77], v[166:169], v[58:61]
	v_mfma_f32_16x16x32_bf16 v[166:169], v[106:109], v[170:173], v[18:21]
	v_mfma_f32_16x16x32_bf16 v[18:21], v[10:13], v[174:177], v[82:85]
	v_mfma_f32_16x16x32_bf16 v[170:173], v[42:45], v[184:187], v[18:21]
	v_mfma_f32_16x16x32_bf16 v[18:21], v[74:77], v[174:177], v[90:93]
	v_mfma_f32_16x16x32_bf16 v[174:177], v[106:109], v[184:187], v[18:21]
	v_mfma_f32_16x16x32_bf16 v[18:21], v[10:13], v[188:191], v[114:117]
	v_mfma_f32_16x16x32_bf16 v[184:187], v[42:45], v[200:203], v[18:21]
	v_mfma_f32_16x16x32_bf16 v[18:21], v[74:77], v[188:191], v[122:125]
	v_mfma_f32_16x16x32_bf16 v[188:191], v[106:109], v[200:203], v[18:21]
	s_setprio 0
	s_barrier
	s_nop 4
	ds_read_b128 v[18:21], v137 offset:16384
	ds_read_b128 v[26:29], v137 offset:17408
	ds_read_b128 v[50:53], v136 offset:16384
	ds_read_b128 v[58:61], v136 offset:17408
	ds_read_b128 v[82:85], v135 offset:16384
	ds_read_b128 v[90:93], v135 offset:17408
	ds_read_b128 v[114:117], v134 offset:16384
	ds_read_b128 v[122:125], v134 offset:17408
	s_waitcnt vmcnt(4)
	s_barrier
	s_waitcnt lgkmcnt(0)
	s_setprio 1
	s_waitcnt lgkmcnt(0)
	v_mfma_f32_16x16x32_bf16 v[130:133], v[6:9], v[18:21], v[130:133]
	v_mfma_f32_16x16x32_bf16 v[102:105], v[6:9], v[50:53], v[102:105]
	v_mfma_f32_16x16x32_bf16 v[70:73], v[6:9], v[82:85], v[70:73]
	v_mfma_f32_16x16x32_bf16 v[6:9], v[6:9], v[114:117], v[38:41]
	v_mfma_f32_16x16x32_bf16 v[30:33], v[150:153], v[114:117], v[30:33]
	v_mfma_f32_16x16x32_bf16 v[126:129], v[150:153], v[18:21], v[126:129]
	v_mfma_f32_16x16x32_bf16 v[102:105], v[146:149], v[58:61], v[102:105]
	v_mfma_f32_16x16x32_bf16 v[94:97], v[150:153], v[50:53], v[94:97]
	v_mfma_f32_16x16x32_bf16 v[70:73], v[146:149], v[90:93], v[70:73]
	v_mfma_f32_16x16x32_bf16 v[62:65], v[150:153], v[82:85], v[62:65]
	v_mfma_f32_16x16x32_bf16 v[6:9], v[146:149], v[122:125], v[6:9]
	v_mfma_f32_16x16x32_bf16 v[38:41], v[154:157], v[122:125], v[30:33]
	v_mfma_f32_16x16x32_bf16 v[200:203], v[146:149], v[26:29], v[130:133]
	v_mfma_f32_16x16x32_bf16 v[220:223], v[154:157], v[26:29], v[126:129]
	v_mfma_f32_16x16x32_bf16 v[224:227], v[154:157], v[58:61], v[94:97]
	v_mfma_f32_16x16x32_bf16 v[228:231], v[154:157], v[90:93], v[62:65]
	s_setprio 0
	s_setprio 1
	v_mfma_f32_16x16x32_bf16 v[30:33], v[10:13], v[18:21], v[118:121]
	v_mfma_f32_16x16x32_bf16 v[18:21], v[74:77], v[18:21], v[110:113]
	v_mfma_f32_16x16x32_bf16 v[150:153], v[106:109], v[26:29], v[18:21]
	v_mfma_f32_16x16x32_bf16 v[18:21], v[10:13], v[50:53], v[86:89]
	v_mfma_f32_16x16x32_bf16 v[154:157], v[42:45], v[58:61], v[18:21]
	v_mfma_f32_16x16x32_bf16 v[18:21], v[74:77], v[50:53], v[78:81]
	v_mfma_f32_16x16x32_bf16 v[232:235], v[106:109], v[58:61], v[18:21]
	v_mfma_f32_16x16x32_bf16 v[18:21], v[10:13], v[82:85], v[54:57]
	v_mfma_f32_16x16x32_bf16 v[10:13], v[10:13], v[114:117], v[22:25]
	v_mfma_f32_16x16x32_bf16 v[236:239], v[42:45], v[90:93], v[18:21]
	v_mfma_f32_16x16x32_bf16 v[18:21], v[74:77], v[82:85], v[46:49]
	v_mfma_f32_16x16x32_bf16 v[244:247], v[42:45], v[122:125], v[10:13]
	v_mfma_f32_16x16x32_bf16 v[10:13], v[74:77], v[114:117], v[14:17]
	v_mfma_f32_16x16x32_bf16 v[146:149], v[42:45], v[26:29], v[30:33]
	v_mfma_f32_16x16x32_bf16 v[240:243], v[106:109], v[90:93], v[18:21]
	v_mfma_f32_16x16x32_bf16 v[248:251], v[106:109], v[122:125], v[10:13]
	s_setprio 0
	s_barrier
	ds_read_b128 v[14:17], v139
	ds_read_b128 v[22:25], v139 offset:1024
	ds_read_b128 v[46:49], v139 offset:2048
	ds_read_b128 v[78:81], v139 offset:3072
	ds_read_b128 v[30:33], v137 offset:32768
	ds_read_b128 v[54:57], v137 offset:33792
	ds_read_b128 v[62:65], v136 offset:32768
	ds_read_b128 v[86:89], v136 offset:33792
	ds_read_b128 v[94:97], v135 offset:32768
	ds_read_b128 v[110:113], v135 offset:33792
	ds_read_b128 v[118:121], v134 offset:32768
	ds_read_b128 v[126:129], v134 offset:33792
	s_waitcnt vmcnt(2)
	s_barrier
; #define LDA(dst, b, h) _Pragma("unroll") for (int m = 0; m < 4; ++m) _Pragma("unroll") for (int k = 0; k < 2; ++k) \
;     dst[m][k] = *reinterpret_cast<const LAS bf16x8*>(lds + SAo(b, h) + lds_byte(wr * 64 + m * 16 + fr, k * 32 + fq * 8))
; #define LDB(dst, b, h) _Pragma("unroll") for (int n = 0; n < 2; ++n) _Pragma("unroll") for (int k = 0; k < 2; ++k) \
;     dst[n][k] = *reinterpret_cast<const LAS bf16x8*>(lds + SBo(b, h) + lds_byte(wc * 32 + n * 16 + fr, k * 32 + fq * 8))
; #define MMA(ai, bj, At_, Bt_) do { __builtin_amdgcn_s_setprio(1); \
;     _Pragma("unroll") for (int m = 0; m < 4; ++m) _Pragma("unroll") for (int n = 0; n < 2; ++n) _Pragma("unroll") for (int k = 0; k < 2; ++k) \
;       acc[ai][bj][m][n] = __builtin_amdgcn_mfma_f32_16x16x32_bf16(Bt_[n][k], At_[m][k], acc[ai][bj][m][n], 0, 0, 0); \
;     __builtin_amdgcn_s_setprio(0); } while (0)
; #define WAIT_V(n) asm volatile("s_waitcnt vmcnt(" #n ")" ::: "memory")
; #define WAIT_L(n) asm volatile("s_waitcnt lgkmcnt(" #n ")" ::: "memory")
; #define BAR __builtin_amdgcn_s_barrier()
; template <bool PRE = false>
; __device__ __forceinline__ void gemm_kloop(Acc& acc, const bf16_t* __restrict__ A, int lda, const bf16_t* __restrict__ Bt, int ldb,
;                                            int brow, int bcol, int nt, LAS unsigned char* lds) {
;     ...
;     { LDB(B0, 1, 0); LDA(At, 1, 0); WAIT_V(2); BAR; WAIT_L(0); MMA(0, 0, At, B0); BAR;
;       LDB(B1, 1, 1); WAIT_V(0); BAR; WAIT_L(0); MMA(0, 1, At, B1); BAR;
;       LDA(At, 1, 1); BAR; WAIT_L(0); MMA(1, 0, At, B0); MMA(1, 1, At, B1); BAR; }
;     if (wr == 0) BAR;
	s_waitcnt lgkmcnt(0)
	s_setprio 1
	s_waitcnt lgkmcnt(0)
	v_mfma_f32_16x16x32_bf16 v[2:5], v[14:17], v[30:33], v[2:5]
	v_mfma_f32_16x16x32_bf16 v[10:13], v[22:25], v[54:57], v[2:5]
	v_mfma_f32_16x16x32_bf16 v[2:5], v[46:49], v[30:33], v[204:207]
	v_mfma_f32_16x16x32_bf16 v[18:21], v[78:81], v[54:57], v[2:5]
	v_mfma_f32_16x16x32_bf16 v[2:5], v[14:17], v[62:65], v[34:37]
	v_mfma_f32_16x16x32_bf16 v[42:45], v[22:25], v[86:89], v[2:5]
	v_mfma_f32_16x16x32_bf16 v[2:5], v[46:49], v[62:65], v[208:211]
	v_mfma_f32_16x16x32_bf16 v[50:53], v[78:81], v[86:89], v[2:5]
	v_mfma_f32_16x16x32_bf16 v[2:5], v[14:17], v[94:97], v[66:69]
	v_mfma_f32_16x16x32_bf16 v[74:77], v[22:25], v[110:113], v[2:5]
	v_mfma_f32_16x16x32_bf16 v[2:5], v[46:49], v[94:97], v[212:215]
	v_mfma_f32_16x16x32_bf16 v[82:85], v[78:81], v[110:113], v[2:5]
	v_mfma_f32_16x16x32_bf16 v[2:5], v[14:17], v[118:121], v[98:101]
	v_mfma_f32_16x16x32_bf16 v[106:109], v[22:25], v[126:129], v[2:5]
	v_mfma_f32_16x16x32_bf16 v[2:5], v[46:49], v[118:121], v[216:219]
	v_mfma_f32_16x16x32_bf16 v[114:117], v[78:81], v[126:129], v[2:5]
	s_setprio 0
	s_barrier
	s_nop 4
	ds_read_b128 v[2:5], v138
	ds_read_b128 v[204:207], v138 offset:1024
	ds_read_b128 v[208:211], v138 offset:2048
	ds_read_b128 v[212:215], v138 offset:3072
	s_waitcnt vmcnt(0)
	s_barrier
	s_waitcnt lgkmcnt(0)
	s_setprio 1
	s_waitcnt lgkmcnt(0)
	v_mfma_f32_16x16x32_bf16 v[26:29], v[2:5], v[30:33], v[140:143]
	v_mfma_f32_16x16x32_bf16 v[30:33], v[208:211], v[30:33], v[158:161]
	v_mfma_f32_16x16x32_bf16 v[34:37], v[212:215], v[54:57], v[30:33]
	v_mfma_f32_16x16x32_bf16 v[30:33], v[2:5], v[62:65], v[162:165]
	v_mfma_f32_16x16x32_bf16 v[58:61], v[204:207], v[86:89], v[30:33]
	v_mfma_f32_16x16x32_bf16 v[30:33], v[208:211], v[62:65], v[166:169]
	v_mfma_f32_16x16x32_bf16 v[66:69], v[212:215], v[86:89], v[30:33]
	v_mfma_f32_16x16x32_bf16 v[30:33], v[2:5], v[94:97], v[170:173]
	v_mfma_f32_16x16x32_bf16 v[90:93], v[204:207], v[110:113], v[30:33]
	v_mfma_f32_16x16x32_bf16 v[30:33], v[208:211], v[94:97], v[174:177]
	v_mfma_f32_16x16x32_bf16 v[98:101], v[212:215], v[110:113], v[30:33]
	v_mfma_f32_16x16x32_bf16 v[30:33], v[2:5], v[118:121], v[184:187]
	v_mfma_f32_16x16x32_bf16 v[122:125], v[204:207], v[126:129], v[30:33]
	v_mfma_f32_16x16x32_bf16 v[30:33], v[208:211], v[118:121], v[188:191]
	v_mfma_f32_16x16x32_bf16 v[26:29], v[204:207], v[54:57], v[26:29]
	v_mfma_f32_16x16x32_bf16 v[130:133], v[212:215], v[126:129], v[30:33]
	s_setprio 0
	s_barrier
	ds_read_b128 v[138:141], v137 offset:49152
	ds_read_b128 v[158:161], v137 offset:50176
	ds_read_b128 v[162:165], v136 offset:49152
	ds_read_b128 v[166:169], v136 offset:50176
	ds_read_b128 v[170:173], v135 offset:49152
	ds_read_b128 v[174:177], v135 offset:50176
	ds_read_b128 v[184:187], v134 offset:49152
	ds_read_b128 v[134:137], v134 offset:50176
	s_barrier
	s_waitcnt lgkmcnt(0)
	s_setprio 1
	s_waitcnt lgkmcnt(0)
	v_mfma_f32_16x16x32_bf16 v[30:33], v[14:17], v[138:141], v[200:203]
	v_mfma_f32_16x16x32_bf16 v[126:129], v[22:25], v[158:161], v[30:33]
	v_mfma_f32_16x16x32_bf16 v[30:33], v[46:49], v[138:141], v[220:223]
	v_mfma_f32_16x16x32_bf16 v[118:121], v[78:81], v[158:161], v[30:33]
	v_mfma_f32_16x16x32_bf16 v[30:33], v[14:17], v[162:165], v[102:105]
	v_mfma_f32_16x16x32_bf16 v[94:97], v[22:25], v[166:169], v[30:33]
	v_mfma_f32_16x16x32_bf16 v[30:33], v[46:49], v[162:165], v[224:227]
	v_mfma_f32_16x16x32_bf16 v[86:89], v[78:81], v[166:169], v[30:33]
	v_mfma_f32_16x16x32_bf16 v[30:33], v[14:17], v[170:173], v[70:73]
	v_mfma_f32_16x16x32_bf16 v[62:65], v[22:25], v[174:177], v[30:33]
	v_mfma_f32_16x16x32_bf16 v[30:33], v[46:49], v[170:173], v[228:231]
	v_mfma_f32_16x16x32_bf16 v[6:9], v[14:17], v[184:187], v[6:9]
	v_mfma_f32_16x16x32_bf16 v[54:57], v[78:81], v[174:177], v[30:33]
	v_mfma_f32_16x16x32_bf16 v[30:33], v[22:25], v[134:137], v[6:9]
	v_mfma_f32_16x16x32_bf16 v[6:9], v[46:49], v[184:187], v[38:41]
	v_mfma_f32_16x16x32_bf16 v[22:25], v[78:81], v[134:137], v[6:9]
	s_setprio 0
	s_setprio 1
	v_mfma_f32_16x16x32_bf16 v[6:9], v[2:5], v[138:141], v[146:149]
	v_mfma_f32_16x16x32_bf16 v[110:113], v[204:207], v[158:161], v[6:9]
	v_mfma_f32_16x16x32_bf16 v[6:9], v[208:211], v[138:141], v[150:153]
	v_mfma_f32_16x16x32_bf16 v[102:105], v[212:215], v[158:161], v[6:9]
	v_mfma_f32_16x16x32_bf16 v[6:9], v[2:5], v[162:165], v[154:157]
	v_mfma_f32_16x16x32_bf16 v[78:81], v[204:207], v[166:169], v[6:9]
	v_mfma_f32_16x16x32_bf16 v[6:9], v[208:211], v[162:165], v[232:235]
	v_mfma_f32_16x16x32_bf16 v[70:73], v[212:215], v[166:169], v[6:9]
	v_mfma_f32_16x16x32_bf16 v[6:9], v[2:5], v[170:173], v[236:239]
	v_mfma_f32_16x16x32_bf16 v[2:5], v[2:5], v[184:187], v[244:247]
	v_mfma_f32_16x16x32_bf16 v[46:49], v[204:207], v[174:177], v[6:9]
	v_mfma_f32_16x16x32_bf16 v[6:9], v[208:211], v[170:173], v[240:243]
	v_mfma_f32_16x16x32_bf16 v[14:17], v[204:207], v[134:137], v[2:5]
	v_mfma_f32_16x16x32_bf16 v[2:5], v[208:211], v[184:187], v[248:251]
	v_mfma_f32_16x16x32_bf16 v[38:41], v[212:215], v[174:177], v[6:9]
	v_mfma_f32_16x16x32_bf16 v[6:9], v[212:215], v[134:137], v[2:5]
	s_setprio 0
	v_cmp_gt_u32_e32 vcc, s85, v1
	s_barrier
	s_and_saveexec_b64 s[12:13], vcc
	s_cbranch_execz .LBB0_558
	s_barrier

; #define LDA(dst, b, h) _Pragma("unroll") for (int m = 0; m < 4; ++m) _Pragma("unroll") for (int k = 0; k < 2; ++k) \
;     dst[m][k] = *reinterpret_cast<const LAS bf16x8*>(lds + SAo(b, h) + lds_byte(wr * 64 + m * 16 + fr, k * 32 + fq * 8))
; #define LDB(dst, b, h) _Pragma("unroll") for (int n = 0; n < 2; ++n) _Pragma("unroll") for (int k = 0; k < 2; ++k) \
;     dst[n][k] = *reinterpret_cast<const LAS bf16x8*>(lds + SBo(b, h) + lds_byte(wc * 32 + n * 16 + fr, k * 32 + fq * 8))
; #define MMA(ai, bj, At_, Bt_) do { __builtin_amdgcn_s_setprio(1); \
;     _Pragma("unroll") for (int m = 0; m < 4; ++m) _Pragma("unroll") for (int n = 0; n < 2; ++n) _Pragma("unroll") for (int k = 0; k < 2; ++k) \
;       acc[ai][bj][m][n] = __builtin_amdgcn_mfma_f32_16x16x32_bf16(Bt_[n][k], At_[m][k], acc[ai][bj][m][n], 0, 0, 0); \
;     __builtin_amdgcn_s_setprio(0); } while (0)
; #define WAIT_L(n) asm volatile("s_waitcnt lgkmcnt(" #n ")" ::: "memory")
; #define BAR __builtin_amdgcn_s_barrier()
; #define SCHED __builtin_amdgcn_sched_barrier(0)
; template <bool PRE = false>
; __device__ __forceinline__ void gemm_kloop(Acc& acc, const bf16_t* __restrict__ A, int lda, const bf16_t* __restrict__ Bt, int ldb,
;                                            int brow, int bcol, int nt, LAS unsigned char* lds) {
;     ...
;     for (int t = 0; t < nt - 2; t += 2) {
;         LDB(B0, 0, 0); SCHED; LDA(At, 0, 0); STAGE(SAo(1, 1), A, lda, brow + HALF, t + 1, offA);
;         WAIT_L(8); BAR; WAIT_L(0); MMA(0, 0, At, B0); BAR; SCHED;
;         LDB(B1, 0, 1); STAGE(SBo(0, 0), Bt, ldb, bcol, t + 2, offB);
;         BAR; WAIT_L(0); MMA(0, 1, At, B1); BAR;
;         LDA(At, 0, 1); STAGE(SAo(0, 0), A, lda, brow, t + 2, offA);
;         BAR; WAIT_L(0); MMA(1, 0, At, B0); BAR; SCHED;
.LBB0_748:
	ds_read_b128 v[146:149], v141
	ds_read_b128 v[150:153], v141 offset:1024
	ds_read_b128 v[154:157], v141 offset:2048
	ds_read_b128 v[158:161], v141 offset:3072
	s_add_i32 s52, s1, 3
	s_mov_b32 s8, s26
	ds_read_b128 v[162:165], v137
	ds_read_b128 v[166:169], v137 offset:1024
	ds_read_b128 v[170:173], v136
	ds_read_b128 v[174:177], v136 offset:1024
	ds_read_b128 v[184:187], v135
	ds_read_b128 v[188:191], v135 offset:1024
	ds_read_b128 v[200:203], v134
	ds_read_b128 v[204:207], v134 offset:1024
	s_ashr_i32 s53, s52, 31
	s_lshl_b64 s[52:53], s[52:53], 7
	s_lshl_b32 s8, s8, 10
	v_lshl_add_u64 v[142:143], v[130:131], 0, s[52:53]
	s_add_i32 s8, s8, 0
	s_add_i32 m0, s8, 0xc000
	v_lshl_add_u64 v[192:193], v[142:143], 0, s[48:49]
	global_load_lds_dwordx4 v[192:193], off
	v_lshl_add_u64 v[142:143], v[142:143], 0, s[50:51]
	s_add_i32 m0, s8, 0xe000
	s_nop 0
	global_load_lds_dwordx4 v[142:143], off
	s_waitcnt lgkmcnt(8)
	s_waitcnt vmcnt(10)
	s_barrier
	s_waitcnt lgkmcnt(0)
	s_setprio 1
	s_waitcnt lgkmcnt(0)
	v_mfma_f32_16x16x32_bf16 v[126:129], v[146:149], v[162:165], v[126:129]
	v_mfma_f32_16x16x32_bf16 v[122:125], v[154:157], v[162:165], v[122:125]
	v_mfma_f32_16x16x32_bf16 v[118:121], v[146:149], v[170:173], v[118:121]
	v_mfma_f32_16x16x32_bf16 v[114:117], v[154:157], v[170:173], v[114:117]
	v_mfma_f32_16x16x32_bf16 v[110:113], v[146:149], v[184:187], v[110:113]
	v_mfma_f32_16x16x32_bf16 v[106:109], v[154:157], v[184:187], v[106:109]
	v_mfma_f32_16x16x32_bf16 v[102:105], v[146:149], v[200:203], v[102:105]
	v_mfma_f32_16x16x32_bf16 v[98:101], v[154:157], v[200:203], v[98:101]
	v_mfma_f32_16x16x32_bf16 v[126:129], v[150:153], v[166:169], v[126:129]
	v_mfma_f32_16x16x32_bf16 v[122:125], v[158:161], v[166:169], v[122:125]
	v_mfma_f32_16x16x32_bf16 v[118:121], v[150:153], v[174:177], v[118:121]
	v_mfma_f32_16x16x32_bf16 v[114:117], v[158:161], v[174:177], v[114:117]
	v_mfma_f32_16x16x32_bf16 v[110:113], v[150:153], v[188:191], v[110:113]
	v_mfma_f32_16x16x32_bf16 v[106:109], v[158:161], v[188:191], v[106:109]
	v_mfma_f32_16x16x32_bf16 v[102:105], v[150:153], v[204:207], v[102:105]
	v_mfma_f32_16x16x32_bf16 v[98:101], v[158:161], v[204:207], v[98:101]
	s_setprio 0
	s_barrier
	s_add_i32 s52, s1, 4
	s_mov_b32 s8, s26
	s_mov_b32 s54, s52
	ds_read_b128 v[208:211], v140
	ds_read_b128 v[212:215], v140 offset:1024
	ds_read_b128 v[216:219], v140 offset:2048
	ds_read_b128 v[220:223], v140 offset:3072
	s_ashr_i32 s55, s54, 31
	s_lshl_b64 s[54:55], s[54:55], 7
	s_lshl_b32 s8, s8, 10
	v_lshl_add_u64 v[142:143], v[132:133], 0, s[54:55]
	s_add_i32 s8, s8, 0
	s_add_i32 m0, s8, 0x10000
	v_lshl_add_u64 v[192:193], v[142:143], 0, s[12:13]
	global_load_lds_dwordx4 v[192:193], off
	v_lshl_add_u64 v[142:143], v[142:143], 0, s[38:39]
	s_add_i32 m0, s8, 0x12000
	s_nop 0
	global_load_lds_dwordx4 v[142:143], off
	s_waitcnt vmcnt(10)
	s_barrier
	s_waitcnt lgkmcnt(0)
	s_setprio 1
	s_waitcnt lgkmcnt(0)
	v_mfma_f32_16x16x32_bf16 v[94:97], v[208:211], v[162:165], v[94:97]
	v_mfma_f32_16x16x32_bf16 v[90:93], v[216:219], v[162:165], v[90:93]
	v_mfma_f32_16x16x32_bf16 v[86:89], v[208:211], v[170:173], v[86:89]
	v_mfma_f32_16x16x32_bf16 v[82:85], v[216:219], v[170:173], v[82:85]
	v_mfma_f32_16x16x32_bf16 v[78:81], v[208:211], v[184:187], v[78:81]
	v_mfma_f32_16x16x32_bf16 v[74:77], v[216:219], v[184:187], v[74:77]
	v_mfma_f32_16x16x32_bf16 v[70:73], v[208:211], v[200:203], v[70:73]
	v_mfma_f32_16x16x32_bf16 v[66:69], v[216:219], v[200:203], v[66:69]
	v_mfma_f32_16x16x32_bf16 v[94:97], v[212:215], v[166:169], v[94:97]
	v_mfma_f32_16x16x32_bf16 v[90:93], v[220:223], v[166:169], v[90:93]
	v_mfma_f32_16x16x32_bf16 v[86:89], v[212:215], v[174:177], v[86:89]
	v_mfma_f32_16x16x32_bf16 v[82:85], v[220:223], v[174:177], v[82:85]
	v_mfma_f32_16x16x32_bf16 v[78:81], v[212:215], v[188:191], v[78:81]
	v_mfma_f32_16x16x32_bf16 v[74:77], v[220:223], v[188:191], v[74:77]
	v_mfma_f32_16x16x32_bf16 v[70:73], v[212:215], v[204:207], v[70:73]
	v_mfma_f32_16x16x32_bf16 v[66:69], v[220:223], v[204:207], v[66:69]
	s_setprio 0
	s_mov_b32 s8, s26
	s_mov_b32 s54, s52
	s_barrier
	ds_read_b128 v[162:165], v137 offset:16384
	ds_read_b128 v[166:169], v137 offset:17408
	ds_read_b128 v[170:173], v136 offset:16384
	ds_read_b128 v[174:177], v136 offset:17408
	ds_read_b128 v[184:187], v135 offset:16384
	ds_read_b128 v[188:191], v135 offset:17408
	ds_read_b128 v[200:203], v134 offset:16384
	ds_read_b128 v[204:207], v134 offset:17408
	s_ashr_i32 s55, s54, 31
	s_lshl_b64 s[54:55], s[54:55], 7
	s_lshl_b32 s8, s8, 10
	v_lshl_add_u64 v[142:143], v[130:131], 0, s[54:55]
	s_add_i32 s8, s8, 0
	v_lshl_add_u64 v[192:193], v[142:143], 0, s[40:41]
	s_mov_b32 m0, s8
	v_lshl_add_u64 v[142:143], v[142:143], 0, s[42:43]
	global_load_lds_dwordx4 v[192:193], off
	s_add_i32 m0, s8, 0x2000
	s_nop 0
	global_load_lds_dwordx4 v[142:143], off
	s_barrier
	s_waitcnt lgkmcnt(0)
	s_setprio 1
	s_waitcnt lgkmcnt(0)
	v_mfma_f32_16x16x32_bf16 v[62:65], v[146:149], v[162:165], v[62:65]
	v_mfma_f32_16x16x32_bf16 v[58:61], v[154:157], v[162:165], v[58:61]
	v_mfma_f32_16x16x32_bf16 v[54:57], v[146:149], v[170:173], v[54:57]
	v_mfma_f32_16x16x32_bf16 v[50:53], v[154:157], v[170:173], v[50:53]
	v_mfma_f32_16x16x32_bf16 v[46:49], v[146:149], v[184:187], v[46:49]
	v_mfma_f32_16x16x32_bf16 v[42:45], v[154:157], v[184:187], v[42:45]
	v_mfma_f32_16x16x32_bf16 v[38:41], v[146:149], v[200:203], v[38:41]
	v_mfma_f32_16x16x32_bf16 v[34:37], v[154:157], v[200:203], v[34:37]
	v_mfma_f32_16x16x32_bf16 v[62:65], v[150:153], v[166:169], v[62:65]
	v_mfma_f32_16x16x32_bf16 v[58:61], v[158:161], v[166:169], v[58:61]
	v_mfma_f32_16x16x32_bf16 v[54:57], v[150:153], v[174:177], v[54:57]
	v_mfma_f32_16x16x32_bf16 v[50:53], v[158:161], v[174:177], v[50:53]
	v_mfma_f32_16x16x32_bf16 v[46:49], v[150:153], v[188:191], v[46:49]
	v_mfma_f32_16x16x32_bf16 v[42:45], v[158:161], v[188:191], v[42:45]
	v_mfma_f32_16x16x32_bf16 v[38:41], v[150:153], v[204:207], v[38:41]
	v_mfma_f32_16x16x32_bf16 v[34:37], v[158:161], v[204:207], v[34:37]
	s_setprio 0
	s_barrier
; #define LDA(dst, b, h) _Pragma("unroll") for (int m = 0; m < 4; ++m) _Pragma("unroll") for (int k = 0; k < 2; ++k) \
;     dst[m][k] = *reinterpret_cast<const LAS bf16x8*>(lds + SAo(b, h) + lds_byte(wr * 64 + m * 16 + fr, k * 32 + fq * 8))
; #define LDB(dst, b, h) _Pragma("unroll") for (int n = 0; n < 2; ++n) _Pragma("unroll") for (int k = 0; k < 2; ++k) \
;     dst[n][k] = *reinterpret_cast<const LAS bf16x8*>(lds + SBo(b, h) + lds_byte(wc * 32 + n * 16 + fr, k * 32 + fq * 8))
; #define MMA(ai, bj, At_, Bt_) do { __builtin_amdgcn_s_setprio(1); \
;     _Pragma("unroll") for (int m = 0; m < 4; ++m) _Pragma("unroll") for (int n = 0; n < 2; ++n) _Pragma("unroll") for (int k = 0; k < 2; ++k) \
;       acc[ai][bj][m][n] = __builtin_amdgcn_mfma_f32_16x16x32_bf16(Bt_[n][k], At_[m][k], acc[ai][bj][m][n], 0, 0, 0); \
;     __builtin_amdgcn_s_setprio(0); } while (0)
; #define WAIT_V(n) asm volatile("s_waitcnt vmcnt(" #n ")" ::: "memory")
; #define WAIT_L(n) asm volatile("s_waitcnt lgkmcnt(" #n ")" ::: "memory")
; #define BAR __builtin_amdgcn_s_barrier()
; #define SCHED __builtin_amdgcn_sched_barrier(0)
; template <bool PRE = false>
; __device__ __forceinline__ void gemm_kloop(Acc& acc, const bf16_t* __restrict__ A, int lda, const bf16_t* __restrict__ Bt, int ldb,
;                                            int brow, int bcol, int nt, LAS unsigned char* lds) {
;     ...
;         STAGE(SBo(0, 1), Bt, ldb, bcol + HALF, t + 2, offB);
;         WAIT_V(6); BAR; MMA(1, 1, At, B1); BAR;
;         LDB(B0, 1, 0); SCHED; LDA(At, 1, 0); STAGE(SAo(0, 1), A, lda, brow + HALF, t + 2, offA);
;         WAIT_L(8); BAR; WAIT_L(0); MMA(0, 0, At, B0); BAR; SCHED;
;         LDB(B1, 1, 1); STAGE(SBo(1, 0), Bt, ldb, bcol, t + 3, offB);
;         BAR; WAIT_L(0); MMA(0, 1, At, B1); BAR;
	s_mov_b32 s8, s26
	s_mov_b32 s54, s52
	s_ashr_i32 s55, s54, 31
	s_lshl_b64 s[54:55], s[54:55], 7
	s_lshl_b32 s8, s8, 10
	v_lshl_add_u64 v[142:143], v[132:133], 0, s[54:55]
	s_add_i32 s8, s8, 0
	s_add_i32 m0, s8, 0x14000
	v_lshl_add_u64 v[146:147], v[142:143], 0, s[44:45]
	global_load_lds_dwordx4 v[146:147], off
	v_lshl_add_u64 v[142:143], v[142:143], 0, s[46:47]
	s_add_i32 m0, s8, 0x16000
	s_nop 0
	global_load_lds_dwordx4 v[142:143], off
	s_waitcnt vmcnt(10)
	s_barrier
	s_setprio 1
	v_mfma_f32_16x16x32_bf16 v[30:33], v[208:211], v[162:165], v[30:33]
	v_mfma_f32_16x16x32_bf16 v[26:29], v[216:219], v[162:165], v[26:29]
	v_mfma_f32_16x16x32_bf16 v[22:25], v[208:211], v[170:173], v[22:25]
	v_mfma_f32_16x16x32_bf16 v[18:21], v[216:219], v[170:173], v[18:21]
	v_mfma_f32_16x16x32_bf16 v[14:17], v[208:211], v[184:187], v[14:17]
	v_mfma_f32_16x16x32_bf16 v[10:13], v[216:219], v[184:187], v[10:13]
	v_mfma_f32_16x16x32_bf16 v[6:9], v[208:211], v[200:203], v[6:9]
	v_mfma_f32_16x16x32_bf16 v[2:5], v[216:219], v[200:203], v[2:5]
	v_mfma_f32_16x16x32_bf16 v[30:33], v[212:215], v[166:169], v[30:33]
	v_mfma_f32_16x16x32_bf16 v[26:29], v[220:223], v[166:169], v[26:29]
	v_mfma_f32_16x16x32_bf16 v[22:25], v[212:215], v[174:177], v[22:25]
	v_mfma_f32_16x16x32_bf16 v[18:21], v[220:223], v[174:177], v[18:21]
	v_mfma_f32_16x16x32_bf16 v[14:17], v[212:215], v[188:191], v[14:17]
	v_mfma_f32_16x16x32_bf16 v[10:13], v[220:223], v[188:191], v[10:13]
	v_mfma_f32_16x16x32_bf16 v[6:9], v[212:215], v[204:207], v[6:9]
	v_mfma_f32_16x16x32_bf16 v[2:5], v[220:223], v[204:207], v[2:5]
	s_setprio 0
	s_barrier
	ds_read_b128 v[146:149], v139
	ds_read_b128 v[150:153], v139 offset:1024
	ds_read_b128 v[154:157], v139 offset:2048
	ds_read_b128 v[158:161], v139 offset:3072
	s_mov_b32 s8, s26
	ds_read_b128 v[162:165], v137 offset:32768
	ds_read_b128 v[166:169], v137 offset:33792
	ds_read_b128 v[170:173], v136 offset:32768
	ds_read_b128 v[174:177], v136 offset:33792
	ds_read_b128 v[184:187], v135 offset:32768
	ds_read_b128 v[188:191], v135 offset:33792
	ds_read_b128 v[200:203], v134 offset:32768
	ds_read_b128 v[204:207], v134 offset:33792
	s_ashr_i32 s53, s52, 31
	s_lshl_b64 s[52:53], s[52:53], 7
	s_lshl_b32 s8, s8, 10
	v_lshl_add_u64 v[142:143], v[130:131], 0, s[52:53]
	s_add_i32 s8, s8, 0
	s_add_i32 m0, s8, 0x4000
	v_lshl_add_u64 v[192:193], v[142:143], 0, s[48:49]
	global_load_lds_dwordx4 v[192:193], off
	v_lshl_add_u64 v[142:143], v[142:143], 0, s[50:51]
	s_add_i32 m0, s8, 0x6000
	s_nop 0
	global_load_lds_dwordx4 v[142:143], off
	s_waitcnt lgkmcnt(8)
	s_waitcnt vmcnt(10)
	s_barrier
	s_waitcnt lgkmcnt(0)
	s_setprio 1
	s_waitcnt lgkmcnt(0)
	v_mfma_f32_16x16x32_bf16 v[126:129], v[146:149], v[162:165], v[126:129]
	v_mfma_f32_16x16x32_bf16 v[122:125], v[154:157], v[162:165], v[122:125]
	v_mfma_f32_16x16x32_bf16 v[118:121], v[146:149], v[170:173], v[118:121]
	v_mfma_f32_16x16x32_bf16 v[114:117], v[154:157], v[170:173], v[114:117]
	v_mfma_f32_16x16x32_bf16 v[110:113], v[146:149], v[184:187], v[110:113]
	v_mfma_f32_16x16x32_bf16 v[106:109], v[154:157], v[184:187], v[106:109]
	v_mfma_f32_16x16x32_bf16 v[102:105], v[146:149], v[200:203], v[102:105]
	v_mfma_f32_16x16x32_bf16 v[98:101], v[154:157], v[200:203], v[98:101]
	v_mfma_f32_16x16x32_bf16 v[126:129], v[150:153], v[166:169], v[126:129]
	v_mfma_f32_16x16x32_bf16 v[122:125], v[158:161], v[166:169], v[122:125]
	v_mfma_f32_16x16x32_bf16 v[118:121], v[150:153], v[174:177], v[118:121]
	v_mfma_f32_16x16x32_bf16 v[114:117], v[158:161], v[174:177], v[114:117]
	v_mfma_f32_16x16x32_bf16 v[110:113], v[150:153], v[188:191], v[110:113]
	v_mfma_f32_16x16x32_bf16 v[106:109], v[158:161], v[188:191], v[106:109]
	v_mfma_f32_16x16x32_bf16 v[102:105], v[150:153], v[204:207], v[102:105]
	v_mfma_f32_16x16x32_bf16 v[98:101], v[158:161], v[204:207], v[98:101]
	s_setprio 0
	s_barrier
	s_add_i32 s52, s1, 5
	s_mov_b32 s8, s26
	s_mov_b32 s54, s52
	ds_read_b128 v[208:211], v138
	ds_read_b128 v[212:215], v138 offset:1024
	ds_read_b128 v[216:219], v138 offset:2048
	ds_read_b128 v[220:223], v138 offset:3072
	s_ashr_i32 s55, s54, 31
	s_lshl_b64 s[54:55], s[54:55], 7
	s_lshl_b32 s8, s8, 10
	v_lshl_add_u64 v[142:143], v[132:133], 0, s[54:55]
	s_add_i32 s8, s8, 0
	s_add_i32 m0, s8, 0x18000
	v_lshl_add_u64 v[192:193], v[142:143], 0, s[12:13]
	global_load_lds_dwordx4 v[192:193], off
	v_lshl_add_u64 v[142:143], v[142:143], 0, s[38:39]
	s_add_i32 m0, s8, 0x1a000
	s_nop 0
	global_load_lds_dwordx4 v[142:143], off
	s_waitcnt vmcnt(10)
	s_barrier
	s_waitcnt lgkmcnt(0)
	s_setprio 1
	s_waitcnt lgkmcnt(0)
	v_mfma_f32_16x16x32_bf16 v[94:97], v[208:211], v[162:165], v[94:97]
	v_mfma_f32_16x16x32_bf16 v[90:93], v[216:219], v[162:165], v[90:93]
	v_mfma_f32_16x16x32_bf16 v[86:89], v[208:211], v[170:173], v[86:89]
	v_mfma_f32_16x16x32_bf16 v[82:85], v[216:219], v[170:173], v[82:85]
	v_mfma_f32_16x16x32_bf16 v[78:81], v[208:211], v[184:187], v[78:81]
	v_mfma_f32_16x16x32_bf16 v[74:77], v[216:219], v[184:187], v[74:77]
	v_mfma_f32_16x16x32_bf16 v[70:73], v[208:211], v[200:203], v[70:73]
	v_mfma_f32_16x16x32_bf16 v[66:69], v[216:219], v[200:203], v[66:69]
	v_mfma_f32_16x16x32_bf16 v[94:97], v[212:215], v[166:169], v[94:97]
	v_mfma_f32_16x16x32_bf16 v[90:93], v[220:223], v[166:169], v[90:93]
	v_mfma_f32_16x16x32_bf16 v[86:89], v[212:215], v[174:177], v[86:89]
	v_mfma_f32_16x16x32_bf16 v[82:85], v[220:223], v[174:177], v[82:85]
	v_mfma_f32_16x16x32_bf16 v[78:81], v[212:215], v[188:191], v[78:81]
	v_mfma_f32_16x16x32_bf16 v[74:77], v[220:223], v[188:191], v[74:77]
	v_mfma_f32_16x16x32_bf16 v[70:73], v[212:215], v[204:207], v[70:73]
	v_mfma_f32_16x16x32_bf16 v[66:69], v[220:223], v[204:207], v[66:69]
	s_setprio 0
	s_mov_b32 s8, s26
	s_mov_b32 s54, s52
	s_barrier
; #define LDA(dst, b, h) _Pragma("unroll") for (int m = 0; m < 4; ++m) _Pragma("unroll") for (int k = 0; k < 2; ++k) \
;     dst[m][k] = *reinterpret_cast<const LAS bf16x8*>(lds + SAo(b, h) + lds_byte(wr * 64 + m * 16 + fr, k * 32 + fq * 8))
; #define LDB(dst, b, h) _Pragma("unroll") for (int n = 0; n < 2; ++n) _Pragma("unroll") for (int k = 0; k < 2; ++k) \
;     dst[n][k] = *reinterpret_cast<const LAS bf16x8*>(lds + SBo(b, h) + lds_byte(wc * 32 + n * 16 + fr, k * 32 + fq * 8))
; #define MMA(ai, bj, At_, Bt_) do { __builtin_amdgcn_s_setprio(1); \
;     _Pragma("unroll") for (int m = 0; m < 4; ++m) _Pragma("unroll") for (int n = 0; n < 2; ++n) _Pragma("unroll") for (int k = 0; k < 2; ++k) \
;       acc[ai][bj][m][n] = __builtin_amdgcn_mfma_f32_16x16x32_bf16(Bt_[n][k], At_[m][k], acc[ai][bj][m][n], 0, 0, 0); \
;     __builtin_amdgcn_s_setprio(0); } while (0)
; #define WAIT_V(n) asm volatile("s_waitcnt vmcnt(" #n ")" ::: "memory")
; #define WAIT_L(n) asm volatile("s_waitcnt lgkmcnt(" #n ")" ::: "memory")
; #define BAR __builtin_amdgcn_s_barrier()
; #define SCHED __builtin_amdgcn_sched_barrier(0)
; template <bool PRE = false>
; __device__ __forceinline__ void gemm_kloop(Acc& acc, const bf16_t* __restrict__ A, int lda, const bf16_t* __restrict__ Bt, int ldb,
;                                            int brow, int bcol, int nt, LAS unsigned char* lds) {
;     ...
;         LDA(At, 1, 1); STAGE(SAo(1, 0), A, lda, brow, t + 3, offA);
;         BAR; WAIT_L(0); MMA(1, 0, At, B0); BAR; SCHED;
;         STAGE(SBo(1, 1), Bt, ldb, bcol + HALF, t + 3, offB);
;         WAIT_V(6); BAR; MMA(1, 1, At, B1); BAR;
;     }
;     { LDB(B0, 0, 0); LDA(At, 0, 0); STAGE(SAo(1, 1), A, lda, brow + HALF, nt - 1, offA);
	ds_read_b128 v[162:165], v137 offset:49152
	ds_read_b128 v[166:169], v137 offset:50176
	ds_read_b128 v[170:173], v136 offset:49152
	ds_read_b128 v[174:177], v136 offset:50176
	ds_read_b128 v[184:187], v135 offset:49152
	ds_read_b128 v[188:191], v135 offset:50176
	ds_read_b128 v[200:203], v134 offset:49152
	ds_read_b128 v[204:207], v134 offset:50176
	s_ashr_i32 s55, s54, 31
	s_lshl_b64 s[54:55], s[54:55], 7
	s_lshl_b32 s8, s8, 10
	v_lshl_add_u64 v[142:143], v[130:131], 0, s[54:55]
	s_add_i32 s8, s8, 0
	s_add_i32 m0, s8, 0x8000
	v_lshl_add_u64 v[192:193], v[142:143], 0, s[40:41]
	global_load_lds_dwordx4 v[192:193], off
	v_lshl_add_u64 v[142:143], v[142:143], 0, s[42:43]
	s_add_i32 m0, s8, 0xa000
	s_nop 0
	global_load_lds_dwordx4 v[142:143], off
	s_barrier
	s_waitcnt lgkmcnt(0)
	s_setprio 1
	s_waitcnt lgkmcnt(0)
	v_mfma_f32_16x16x32_bf16 v[62:65], v[146:149], v[162:165], v[62:65]
	v_mfma_f32_16x16x32_bf16 v[58:61], v[154:157], v[162:165], v[58:61]
	v_mfma_f32_16x16x32_bf16 v[54:57], v[146:149], v[170:173], v[54:57]
	v_mfma_f32_16x16x32_bf16 v[50:53], v[154:157], v[170:173], v[50:53]
	v_mfma_f32_16x16x32_bf16 v[46:49], v[146:149], v[184:187], v[46:49]
	v_mfma_f32_16x16x32_bf16 v[42:45], v[154:157], v[184:187], v[42:45]
	v_mfma_f32_16x16x32_bf16 v[38:41], v[146:149], v[200:203], v[38:41]
	v_mfma_f32_16x16x32_bf16 v[34:37], v[154:157], v[200:203], v[34:37]
	v_mfma_f32_16x16x32_bf16 v[62:65], v[150:153], v[166:169], v[62:65]
	v_mfma_f32_16x16x32_bf16 v[58:61], v[158:161], v[166:169], v[58:61]
	v_mfma_f32_16x16x32_bf16 v[54:57], v[150:153], v[174:177], v[54:57]
	v_mfma_f32_16x16x32_bf16 v[50:53], v[158:161], v[174:177], v[50:53]
	v_mfma_f32_16x16x32_bf16 v[46:49], v[150:153], v[188:191], v[46:49]
	v_mfma_f32_16x16x32_bf16 v[42:45], v[158:161], v[188:191], v[42:45]
	v_mfma_f32_16x16x32_bf16 v[38:41], v[150:153], v[204:207], v[38:41]
	v_mfma_f32_16x16x32_bf16 v[34:37], v[158:161], v[204:207], v[34:37]
	s_setprio 0
	s_barrier
	s_mov_b32 s8, s26
	s_ashr_i32 s53, s52, 31
	s_lshl_b64 s[52:53], s[52:53], 7
	s_lshl_b32 s8, s8, 10
	v_lshl_add_u64 v[142:143], v[132:133], 0, s[52:53]
	s_add_i32 s8, s8, 0
	s_add_i32 m0, s8, 0x1c000
	v_lshl_add_u64 v[146:147], v[142:143], 0, s[44:45]
	global_load_lds_dwordx4 v[146:147], off
	v_lshl_add_u64 v[142:143], v[142:143], 0, s[46:47]
	s_add_i32 m0, s8, 0x1e000
	s_nop 0
	global_load_lds_dwordx4 v[142:143], off
	s_waitcnt vmcnt(10)
	s_barrier
	s_setprio 1
	v_mfma_f32_16x16x32_bf16 v[30:33], v[208:211], v[162:165], v[30:33]
	v_mfma_f32_16x16x32_bf16 v[26:29], v[216:219], v[162:165], v[26:29]
	v_mfma_f32_16x16x32_bf16 v[22:25], v[208:211], v[170:173], v[22:25]
	v_mfma_f32_16x16x32_bf16 v[18:21], v[216:219], v[170:173], v[18:21]
	v_mfma_f32_16x16x32_bf16 v[14:17], v[208:211], v[184:187], v[14:17]
	v_mfma_f32_16x16x32_bf16 v[10:13], v[216:219], v[184:187], v[10:13]
	v_mfma_f32_16x16x32_bf16 v[6:9], v[208:211], v[200:203], v[6:9]
	v_mfma_f32_16x16x32_bf16 v[2:5], v[216:219], v[200:203], v[2:5]
	v_mfma_f32_16x16x32_bf16 v[30:33], v[212:215], v[166:169], v[30:33]
	v_mfma_f32_16x16x32_bf16 v[26:29], v[220:223], v[166:169], v[26:29]
	v_mfma_f32_16x16x32_bf16 v[22:25], v[212:215], v[174:177], v[22:25]
	v_mfma_f32_16x16x32_bf16 v[18:21], v[220:223], v[174:177], v[18:21]
	v_mfma_f32_16x16x32_bf16 v[14:17], v[212:215], v[188:191], v[14:17]
	v_mfma_f32_16x16x32_bf16 v[10:13], v[220:223], v[188:191], v[10:13]
	v_mfma_f32_16x16x32_bf16 v[6:9], v[212:215], v[204:207], v[6:9]
	v_mfma_f32_16x16x32_bf16 v[2:5], v[220:223], v[204:207], v[2:5]
	s_setprio 0
	s_add_i32 s1, s1, 2
	s_cmp_lt_u32 s1, 12
	s_barrier
	s_cbranch_scc1 .LBB0_748
	s_mov_b32 s12, 15
	ds_read_b128 v[130:133], v141
	ds_read_b128 v[146:149], v141 offset:1024
	ds_read_b128 v[150:153], v141 offset:2048
	ds_read_b128 v[154:157], v141 offset:3072
	ds_read_b128 v[158:161], v137
	ds_read_b128 v[162:165], v137 offset:1024
	ds_read_b128 v[166:169], v136
	ds_read_b128 v[170:173], v136 offset:1024
	ds_read_b128 v[174:177], v135
	ds_read_b128 v[184:187], v135 offset:1024
	ds_read_b128 v[188:191], v134
	ds_read_b128 v[200:203], v134 offset:1024
	s_ashr_i32 s13, s12, 31
	s_lshl_b64 s[12:13], s[12:13], 7
	s_add_u32 s12, s34, s12
	s_addc_u32 s13, s35, s13
	s_lshl_b32 s1, s26, 10
	v_lshl_add_u64 v[142:143], s[12:13], 0, v[144:145]
	s_add_i32 s1, s1, 0
	s_add_i32 m0, s1, 0xc000
	v_lshl_add_u64 v[192:193], v[142:143], 0, s[48:49]
	global_load_lds_dwordx4 v[192:193], off
	v_lshl_add_u64 v[142:143], v[142:143], 0, s[50:51]
	s_add_i32 m0, s1, 0xe000
	s_nop 0
	global_load_lds_dwordx4 v[142:143], off
	s_waitcnt vmcnt(10)
	s_barrier
	s_waitcnt lgkmcnt(0)
	s_setprio 1
	s_waitcnt lgkmcnt(0)
	v_mfma_f32_16x16x32_bf16 v[126:129], v[130:133], v[158:161], v[126:129]
	v_mfma_f32_16x16x32_bf16 v[122:125], v[150:153], v[158:161], v[122:125]
	v_mfma_f32_16x16x32_bf16 v[118:121], v[130:133], v[166:169], v[118:121]
	v_mfma_f32_16x16x32_bf16 v[114:117], v[150:153], v[166:169], v[114:117]
	v_mfma_f32_16x16x32_bf16 v[102:105], v[130:133], v[188:191], v[102:105]
	v_mfma_f32_16x16x32_bf16 v[98:101], v[150:153], v[188:191], v[98:101]
	v_mfma_f32_16x16x32_bf16 v[126:129], v[146:149], v[162:165], v[126:129]
	v_mfma_f32_16x16x32_bf16 v[122:125], v[154:157], v[162:165], v[122:125]
	v_mfma_f32_16x16x32_bf16 v[118:121], v[146:149], v[170:173], v[118:121]
	v_mfma_f32_16x16x32_bf16 v[114:117], v[154:157], v[170:173], v[114:117]
	v_mfma_f32_16x16x32_bf16 v[110:113], v[130:133], v[174:177], v[110:113]
	v_mfma_f32_16x16x32_bf16 v[106:109], v[150:153], v[174:177], v[106:109]
	v_mfma_f32_16x16x32_bf16 v[102:105], v[146:149], v[200:203], v[102:105]
	v_mfma_f32_16x16x32_bf16 v[98:101], v[154:157], v[200:203], v[98:101]
	v_mfma_f32_16x16x32_bf16 v[204:207], v[146:149], v[184:187], v[110:113]
	v_mfma_f32_16x16x32_bf16 v[208:211], v[154:157], v[184:187], v[106:109]
	s_setprio 0
	s_barrier
; #define LDA(dst, b, h) _Pragma("unroll") for (int m = 0; m < 4; ++m) _Pragma("unroll") for (int k = 0; k < 2; ++k) \
;     dst[m][k] = *reinterpret_cast<const LAS bf16x8*>(lds + SAo(b, h) + lds_byte(wr * 64 + m * 16 + fr, k * 32 + fq * 8))
; #define LDB(dst, b, h) _Pragma("unroll") for (int n = 0; n < 2; ++n) _Pragma("unroll") for (int k = 0; k < 2; ++k) \
;     dst[n][k] = *reinterpret_cast<const LAS bf16x8*>(lds + SBo(b, h) + lds_byte(wc * 32 + n * 16 + fr, k * 32 + fq * 8))
; #define MMA(ai, bj, At_, Bt_) do { __builtin_amdgcn_s_setprio(1); \
;     _Pragma("unroll") for (int m = 0; m < 4; ++m) _Pragma("unroll") for (int n = 0; n < 2; ++n) _Pragma("unroll") for (int k = 0; k < 2; ++k) \
;       acc[ai][bj][m][n] = __builtin_amdgcn_mfma_f32_16x16x32_bf16(Bt_[n][k], At_[m][k], acc[ai][bj][m][n], 0, 0, 0); \
;     __builtin_amdgcn_s_setprio(0); } while (0)
; #define WAIT_V(n) asm volatile("s_waitcnt vmcnt(" #n ")" ::: "memory")
; #define WAIT_L(n) asm volatile("s_waitcnt lgkmcnt(" #n ")" ::: "memory")
; #define BAR __builtin_amdgcn_s_barrier()
; template <bool PRE = false>
; __device__ __forceinline__ void gemm_kloop(Acc& acc, const bf16_t* __restrict__ A, int lda, const bf16_t* __restrict__ Bt, int ldb,
;                                            int brow, int bcol, int nt, LAS unsigned char* lds) {
;     ...
;     { LDB(B0, 0, 0); LDA(At, 0, 0); STAGE(SAo(1, 1), A, lda, brow + HALF, nt - 1, offA);
;       BAR; WAIT_L(0); MMA(0, 0, At, B0); BAR;
;       LDB(B1, 0, 1); BAR; WAIT_L(0); MMA(0, 1, At, B1); BAR;
;       LDA(At, 0, 1); WAIT_V(4); BAR; WAIT_L(0); MMA(1, 0, At, B0); MMA(1, 1, At, B1); BAR; }
;     { LDB(B0, 1, 0); LDA(At, 1, 0); WAIT_V(2); BAR; WAIT_L(0); MMA(0, 0, At, B0); BAR;
	s_nop 1
	ds_read_b128 v[106:109], v140
	ds_read_b128 v[110:113], v140 offset:1024
	ds_read_b128 v[212:215], v140 offset:2048
	ds_read_b128 v[140:143], v140 offset:3072
	s_waitcnt vmcnt(8)
	s_barrier
	s_waitcnt lgkmcnt(0)
	s_setprio 1
	s_waitcnt lgkmcnt(0)
	v_mfma_f32_16x16x32_bf16 v[86:89], v[106:109], v[166:169], v[86:89]
	v_mfma_f32_16x16x32_bf16 v[82:85], v[212:215], v[166:169], v[82:85]
	v_mfma_f32_16x16x32_bf16 v[70:73], v[106:109], v[188:191], v[70:73]
	v_mfma_f32_16x16x32_bf16 v[66:69], v[212:215], v[188:191], v[66:69]
	v_mfma_f32_16x16x32_bf16 v[94:97], v[106:109], v[158:161], v[94:97]
	v_mfma_f32_16x16x32_bf16 v[90:93], v[212:215], v[158:161], v[90:93]
	v_mfma_f32_16x16x32_bf16 v[86:89], v[110:113], v[170:173], v[86:89]
	v_mfma_f32_16x16x32_bf16 v[82:85], v[140:143], v[170:173], v[82:85]
	v_mfma_f32_16x16x32_bf16 v[78:81], v[106:109], v[174:177], v[78:81]
	v_mfma_f32_16x16x32_bf16 v[74:77], v[212:215], v[174:177], v[74:77]
	v_mfma_f32_16x16x32_bf16 v[70:73], v[110:113], v[200:203], v[70:73]
	v_mfma_f32_16x16x32_bf16 v[66:69], v[140:143], v[200:203], v[66:69]
	v_mfma_f32_16x16x32_bf16 v[216:219], v[110:113], v[162:165], v[94:97]
	v_mfma_f32_16x16x32_bf16 v[158:161], v[140:143], v[162:165], v[90:93]
	v_mfma_f32_16x16x32_bf16 v[162:165], v[110:113], v[184:187], v[78:81]
	v_mfma_f32_16x16x32_bf16 v[166:169], v[140:143], v[184:187], v[74:77]
	s_setprio 0
	s_barrier
	s_nop 0
	ds_read_b128 v[74:77], v137 offset:16384
	ds_read_b128 v[78:81], v137 offset:17408
	ds_read_b128 v[90:93], v136 offset:16384
	ds_read_b128 v[94:97], v136 offset:17408
	ds_read_b128 v[170:173], v135 offset:16384
	ds_read_b128 v[174:177], v135 offset:17408
	ds_read_b128 v[184:187], v134 offset:16384
	ds_read_b128 v[188:191], v134 offset:17408
	s_waitcnt vmcnt(4)
	s_barrier
	s_waitcnt lgkmcnt(0)
	s_setprio 1
	s_waitcnt lgkmcnt(0)
	v_mfma_f32_16x16x32_bf16 v[62:65], v[130:133], v[74:77], v[62:65]
	v_mfma_f32_16x16x32_bf16 v[58:61], v[150:153], v[74:77], v[58:61]
	v_mfma_f32_16x16x32_bf16 v[54:57], v[130:133], v[90:93], v[54:57]
	v_mfma_f32_16x16x32_bf16 v[50:53], v[150:153], v[90:93], v[50:53]
	v_mfma_f32_16x16x32_bf16 v[38:41], v[130:133], v[184:187], v[38:41]
	v_mfma_f32_16x16x32_bf16 v[34:37], v[150:153], v[184:187], v[34:37]
	v_mfma_f32_16x16x32_bf16 v[62:65], v[146:149], v[78:81], v[62:65]
	v_mfma_f32_16x16x32_bf16 v[58:61], v[154:157], v[78:81], v[58:61]
	v_mfma_f32_16x16x32_bf16 v[54:57], v[146:149], v[94:97], v[54:57]
	v_mfma_f32_16x16x32_bf16 v[50:53], v[154:157], v[94:97], v[50:53]
	v_mfma_f32_16x16x32_bf16 v[46:49], v[130:133], v[170:173], v[46:49]
	v_mfma_f32_16x16x32_bf16 v[42:45], v[150:153], v[170:173], v[42:45]
	v_mfma_f32_16x16x32_bf16 v[38:41], v[146:149], v[188:191], v[38:41]
	v_mfma_f32_16x16x32_bf16 v[34:37], v[154:157], v[188:191], v[34:37]
	v_mfma_f32_16x16x32_bf16 v[200:203], v[146:149], v[174:177], v[46:49]
	v_mfma_f32_16x16x32_bf16 v[220:223], v[154:157], v[174:177], v[42:45]
	s_setprio 0
	s_setprio 1
	v_mfma_f32_16x16x32_bf16 v[22:25], v[106:109], v[90:93], v[22:25]
	v_mfma_f32_16x16x32_bf16 v[18:21], v[212:215], v[90:93], v[18:21]
	v_mfma_f32_16x16x32_bf16 v[6:9], v[106:109], v[184:187], v[6:9]
	v_mfma_f32_16x16x32_bf16 v[2:5], v[212:215], v[184:187], v[2:5]
	v_mfma_f32_16x16x32_bf16 v[30:33], v[106:109], v[74:77], v[30:33]
	v_mfma_f32_16x16x32_bf16 v[26:29], v[212:215], v[74:77], v[26:29]
	v_mfma_f32_16x16x32_bf16 v[22:25], v[110:113], v[94:97], v[22:25]
	v_mfma_f32_16x16x32_bf16 v[18:21], v[140:143], v[94:97], v[18:21]
	v_mfma_f32_16x16x32_bf16 v[14:17], v[106:109], v[170:173], v[14:17]
	v_mfma_f32_16x16x32_bf16 v[10:13], v[212:215], v[170:173], v[10:13]
	v_mfma_f32_16x16x32_bf16 v[6:9], v[110:113], v[188:191], v[6:9]
	v_mfma_f32_16x16x32_bf16 v[2:5], v[140:143], v[188:191], v[2:5]
	v_mfma_f32_16x16x32_bf16 v[130:133], v[110:113], v[78:81], v[30:33]
	v_mfma_f32_16x16x32_bf16 v[146:149], v[140:143], v[78:81], v[26:29]
	v_mfma_f32_16x16x32_bf16 v[150:153], v[110:113], v[174:177], v[14:17]
	v_mfma_f32_16x16x32_bf16 v[154:157], v[140:143], v[174:177], v[10:13]
	s_setprio 0
	s_barrier
	s_nop 0
	ds_read_b128 v[10:13], v139
	ds_read_b128 v[14:17], v139 offset:1024
	ds_read_b128 v[140:143], v139 offset:2048
	ds_read_b128 v[170:173], v139 offset:3072
	ds_read_b128 v[26:29], v137 offset:32768
	ds_read_b128 v[30:33], v137 offset:33792
	ds_read_b128 v[42:45], v136 offset:32768
	ds_read_b128 v[46:49], v136 offset:33792
	ds_read_b128 v[174:177], v135 offset:32768
	ds_read_b128 v[184:187], v135 offset:33792
	ds_read_b128 v[188:191], v134 offset:32768
	ds_read_b128 v[212:215], v134 offset:33792
	s_waitcnt vmcnt(2)
	s_barrier
; #define LDA(dst, b, h) _Pragma("unroll") for (int m = 0; m < 4; ++m) _Pragma("unroll") for (int k = 0; k < 2; ++k) \
;     dst[m][k] = *reinterpret_cast<const LAS bf16x8*>(lds + SAo(b, h) + lds_byte(wr * 64 + m * 16 + fr, k * 32 + fq * 8))
; #define LDB(dst, b, h) _Pragma("unroll") for (int n = 0; n < 2; ++n) _Pragma("unroll") for (int k = 0; k < 2; ++k) \
;     dst[n][k] = *reinterpret_cast<const LAS bf16x8*>(lds + SBo(b, h) + lds_byte(wc * 32 + n * 16 + fr, k * 32 + fq * 8))
; #define MMA(ai, bj, At_, Bt_) do { __builtin_amdgcn_s_setprio(1); \
;     _Pragma("unroll") for (int m = 0; m < 4; ++m) _Pragma("unroll") for (int n = 0; n < 2; ++n) _Pragma("unroll") for (int k = 0; k < 2; ++k) \
;       acc[ai][bj][m][n] = __builtin_amdgcn_mfma_f32_16x16x32_bf16(Bt_[n][k], At_[m][k], acc[ai][bj][m][n], 0, 0, 0); \
;     __builtin_amdgcn_s_setprio(0); } while (0)
; #define WAIT_V(n) asm volatile("s_waitcnt vmcnt(" #n ")" ::: "memory")
; #define WAIT_L(n) asm volatile("s_waitcnt lgkmcnt(" #n ")" ::: "memory")
; #define BAR __builtin_amdgcn_s_barrier()
; template <bool PRE = false>
; __device__ __forceinline__ void gemm_kloop(Acc& acc, const bf16_t* __restrict__ A, int lda, const bf16_t* __restrict__ Bt, int ldb,
;                                            int brow, int bcol, int nt, LAS unsigned char* lds) {
;     ...
;     { LDB(B0, 1, 0); LDA(At, 1, 0); WAIT_V(2); BAR; WAIT_L(0); MMA(0, 0, At, B0); BAR;
;       LDB(B1, 1, 1); WAIT_V(0); BAR; WAIT_L(0); MMA(0, 1, At, B1); BAR;
;       LDA(At, 1, 1); BAR; WAIT_L(0); MMA(1, 0, At, B0); MMA(1, 1, At, B1); BAR; }
;     if (wr == 0) BAR;
	s_waitcnt lgkmcnt(0)
	s_setprio 1
	s_waitcnt lgkmcnt(0)
	v_mfma_f32_16x16x32_bf16 v[74:77], v[10:13], v[26:29], v[126:129]
	v_mfma_f32_16x16x32_bf16 v[126:129], v[14:17], v[30:33], v[74:77]
	v_mfma_f32_16x16x32_bf16 v[74:77], v[140:143], v[26:29], v[122:125]
	v_mfma_f32_16x16x32_bf16 v[122:125], v[170:173], v[30:33], v[74:77]
	v_mfma_f32_16x16x32_bf16 v[74:77], v[10:13], v[42:45], v[118:121]
	v_mfma_f32_16x16x32_bf16 v[110:113], v[14:17], v[46:49], v[74:77]
	v_mfma_f32_16x16x32_bf16 v[74:77], v[140:143], v[42:45], v[114:117]
	v_mfma_f32_16x16x32_bf16 v[106:109], v[170:173], v[46:49], v[74:77]
	v_mfma_f32_16x16x32_bf16 v[74:77], v[10:13], v[174:177], v[204:207]
	v_mfma_f32_16x16x32_bf16 v[94:97], v[14:17], v[184:187], v[74:77]
	v_mfma_f32_16x16x32_bf16 v[74:77], v[140:143], v[174:177], v[208:211]
	v_mfma_f32_16x16x32_bf16 v[90:93], v[170:173], v[184:187], v[74:77]
	v_mfma_f32_16x16x32_bf16 v[74:77], v[10:13], v[188:191], v[102:105]
	v_mfma_f32_16x16x32_bf16 v[78:81], v[14:17], v[212:215], v[74:77]
	v_mfma_f32_16x16x32_bf16 v[74:77], v[140:143], v[188:191], v[98:101]
	v_mfma_f32_16x16x32_bf16 v[74:77], v[170:173], v[212:215], v[74:77]
	s_setprio 0
	s_barrier
	ds_read_b128 v[204:207], v138
	ds_read_b128 v[208:211], v138 offset:1024
	ds_read_b128 v[224:227], v138 offset:2048
	ds_read_b128 v[228:231], v138 offset:3072
	s_waitcnt vmcnt(0)
	s_barrier
	s_waitcnt lgkmcnt(0)
	s_setprio 1
	s_waitcnt lgkmcnt(0)
	v_mfma_f32_16x16x32_bf16 v[98:101], v[204:207], v[26:29], v[216:219]
	v_mfma_f32_16x16x32_bf16 v[26:29], v[224:227], v[26:29], v[158:161]
	v_mfma_f32_16x16x32_bf16 v[114:117], v[228:231], v[30:33], v[26:29]
	v_mfma_f32_16x16x32_bf16 v[26:29], v[204:207], v[42:45], v[86:89]
	v_mfma_f32_16x16x32_bf16 v[102:105], v[208:211], v[46:49], v[26:29]
	v_mfma_f32_16x16x32_bf16 v[26:29], v[224:227], v[42:45], v[82:85]
	v_mfma_f32_16x16x32_bf16 v[118:121], v[208:211], v[30:33], v[98:101]
	v_mfma_f32_16x16x32_bf16 v[98:101], v[228:231], v[46:49], v[26:29]
	v_mfma_f32_16x16x32_bf16 v[26:29], v[204:207], v[174:177], v[162:165]
	v_mfma_f32_16x16x32_bf16 v[86:89], v[208:211], v[184:187], v[26:29]
	v_mfma_f32_16x16x32_bf16 v[26:29], v[224:227], v[174:177], v[166:169]
	v_mfma_f32_16x16x32_bf16 v[82:85], v[228:231], v[184:187], v[26:29]
	v_mfma_f32_16x16x32_bf16 v[26:29], v[204:207], v[188:191], v[70:73]
	v_mfma_f32_16x16x32_bf16 v[70:73], v[208:211], v[212:215], v[26:29]
	v_mfma_f32_16x16x32_bf16 v[26:29], v[224:227], v[188:191], v[66:69]
	v_mfma_f32_16x16x32_bf16 v[66:69], v[228:231], v[212:215], v[26:29]
	s_setprio 0
	s_barrier
	ds_read_b128 v[158:161], v137 offset:49152
	ds_read_b128 v[162:165], v137 offset:50176
	ds_read_b128 v[166:169], v136 offset:49152
	ds_read_b128 v[136:139], v136 offset:50176
	ds_read_b128 v[174:177], v135 offset:49152
	ds_read_b128 v[184:187], v135 offset:50176
	ds_read_b128 v[188:191], v134 offset:49152
	ds_read_b128 v[212:215], v134 offset:50176
	s_barrier
	s_waitcnt lgkmcnt(0)
	s_setprio 1
	s_waitcnt lgkmcnt(0)
	v_mfma_f32_16x16x32_bf16 v[26:29], v[10:13], v[158:161], v[62:65]
	v_mfma_f32_16x16x32_bf16 v[62:65], v[14:17], v[162:165], v[26:29]
	v_mfma_f32_16x16x32_bf16 v[26:29], v[140:143], v[158:161], v[58:61]
	v_mfma_f32_16x16x32_bf16 v[58:61], v[170:173], v[162:165], v[26:29]
	v_mfma_f32_16x16x32_bf16 v[26:29], v[10:13], v[166:169], v[54:57]
	v_mfma_f32_16x16x32_bf16 v[46:49], v[14:17], v[136:139], v[26:29]
	v_mfma_f32_16x16x32_bf16 v[26:29], v[140:143], v[166:169], v[50:53]
	v_mfma_f32_16x16x32_bf16 v[42:45], v[170:173], v[136:139], v[26:29]
	v_mfma_f32_16x16x32_bf16 v[26:29], v[10:13], v[174:177], v[200:203]
	v_mfma_f32_16x16x32_bf16 v[10:13], v[10:13], v[188:191], v[38:41]
	v_mfma_f32_16x16x32_bf16 v[30:33], v[14:17], v[184:187], v[26:29]
	v_mfma_f32_16x16x32_bf16 v[26:29], v[140:143], v[174:177], v[220:223]
	v_mfma_f32_16x16x32_bf16 v[14:17], v[14:17], v[212:215], v[10:13]
	v_mfma_f32_16x16x32_bf16 v[10:13], v[140:143], v[188:191], v[34:37]
	v_mfma_f32_16x16x32_bf16 v[26:29], v[170:173], v[184:187], v[26:29]
	v_mfma_f32_16x16x32_bf16 v[10:13], v[170:173], v[212:215], v[10:13]
	s_setprio 0
	s_setprio 1
	v_mfma_f32_16x16x32_bf16 v[34:37], v[204:207], v[158:161], v[130:133]
	v_mfma_f32_16x16x32_bf16 v[54:57], v[208:211], v[162:165], v[34:37]
	v_mfma_f32_16x16x32_bf16 v[34:37], v[224:227], v[158:161], v[146:149]
	v_mfma_f32_16x16x32_bf16 v[18:21], v[224:227], v[166:169], v[18:21]
	v_mfma_f32_16x16x32_bf16 v[50:53], v[228:231], v[162:165], v[34:37]
	v_mfma_f32_16x16x32_bf16 v[22:25], v[204:207], v[166:169], v[22:25]
	v_mfma_f32_16x16x32_bf16 v[34:37], v[228:231], v[136:139], v[18:21]
	v_mfma_f32_16x16x32_bf16 v[18:21], v[204:207], v[174:177], v[150:153]
	v_mfma_f32_16x16x32_bf16 v[38:41], v[208:211], v[136:139], v[22:25]
	v_mfma_f32_16x16x32_bf16 v[22:25], v[208:211], v[184:187], v[18:21]
	v_mfma_f32_16x16x32_bf16 v[18:21], v[224:227], v[174:177], v[154:157]
	v_mfma_f32_16x16x32_bf16 v[6:9], v[204:207], v[188:191], v[6:9]
	v_mfma_f32_16x16x32_bf16 v[2:5], v[224:227], v[188:191], v[2:5]
	v_mfma_f32_16x16x32_bf16 v[18:21], v[228:231], v[184:187], v[18:21]
	v_mfma_f32_16x16x32_bf16 v[6:9], v[208:211], v[212:215], v[6:9]
	v_mfma_f32_16x16x32_bf16 v[2:5], v[228:231], v[212:215], v[2:5]
	s_setprio 0
	v_cmp_gt_u32_e32 vcc, s85, v1
	s_barrier
	s_and_saveexec_b64 s[12:13], vcc
	s_cbranch_execz .LBB0_751
	s_barrier
